# v20 + odd phases: k0 A-reads first, lgkmcnt(4) before MFMA1 and lgkmcnt(0) before MFMA9
# baseline (speedup 1.0000x reference)
.LBB0_127:
	s_add_u32 s22, s20, 0xfff80080
	s_addc_u32 s23, s21, -1
	s_add_i32 s50, 0, 0x10000
	s_cmp_eq_u32 s49, 4
	s_cselect_b32 s23, s81, s23
	s_cselect_b32 s22, s80, s22
	s_cselect_b32 s39, s19, s48
	s_cselect_b32 s38, s31, s47
	v_lshl_add_u64 v[178:179], s[20:21], 0, v[138:139]
	s_add_i32 m0, s27, 0xc000
	ds_read_b128 v[162:165], v144
	ds_read_b128 v[170:173], v144 offset:2048
	ds_read_b128 v[192:195], v144 offset:4096
	ds_read_b128 v[200:203], v144 offset:6144
	ds_read_b128 v[166:169], v144 offset:1024
	ds_read_b128 v[174:177], v144 offset:3072
	ds_read_b128 v[196:199], v144 offset:5120
	ds_read_b128 v[204:207], v144 offset:7168
	global_load_lds_dwordx4 v[178:179], off
	v_lshl_add_u64 v[178:179], s[20:21], 0, v[140:141]
	s_add_i32 m0, s27, 0xe000
	s_nop 0
	global_load_lds_dwordx4 v[178:179], off
	s_waitcnt lgkmcnt(8)
	s_barrier
	s_waitcnt lgkmcnt(4)
	s_setprio 1
	s_waitcnt lgkmcnt(4)
	v_mfma_f32_16x16x32_bf16 v[126:129], v[146:149], v[162:165], v[126:129]
	v_mfma_f32_16x16x32_bf16 v[122:125], v[154:157], v[162:165], v[122:125]
	v_mfma_f32_16x16x32_bf16 v[118:121], v[146:149], v[170:173], v[118:121]
	v_mfma_f32_16x16x32_bf16 v[114:117], v[154:157], v[170:173], v[114:117]
	v_mfma_f32_16x16x32_bf16 v[102:105], v[146:149], v[192:195], v[102:105]
	v_mfma_f32_16x16x32_bf16 v[98:101], v[154:157], v[192:195], v[98:101]
	v_mfma_f32_16x16x32_bf16 v[86:89], v[146:149], v[200:203], v[86:89]
	v_mfma_f32_16x16x32_bf16 v[82:85], v[154:157], v[200:203], v[82:85]
	s_waitcnt lgkmcnt(0)
	v_mfma_f32_16x16x32_bf16 v[126:129], v[150:153], v[166:169], v[126:129]
	v_mfma_f32_16x16x32_bf16 v[122:125], v[158:161], v[166:169], v[122:125]
	v_mfma_f32_16x16x32_bf16 v[118:121], v[150:153], v[174:177], v[118:121]
	v_mfma_f32_16x16x32_bf16 v[114:117], v[158:161], v[174:177], v[114:117]
	v_mfma_f32_16x16x32_bf16 v[102:105], v[150:153], v[196:199], v[102:105]
	v_mfma_f32_16x16x32_bf16 v[98:101], v[158:161], v[196:199], v[98:101]
	v_mfma_f32_16x16x32_bf16 v[86:89], v[150:153], v[204:207], v[86:89]
	v_mfma_f32_16x16x32_bf16 v[82:85], v[158:161], v[204:207], v[82:85]
	s_setprio 0
	s_barrier
	s_add_i32 s52, 0, 0x14000
	s_add_i32 s50, s50, s26
	v_add_u32_e32 v145, s52, v142
	v_lshl_add_u64 v[178:179], s[38:39], 0, v[134:135]
	s_mov_b32 m0, s50
	ds_read_b128 v[208:211], v145
	ds_read_b128 v[224:227], v145 offset:1024
	ds_read_b128 v[228:231], v145 offset:2048
	ds_read_b128 v[232:235], v145 offset:3072
	global_load_lds_dwordx4 v[178:179], off
	v_lshl_add_u64 v[212:213], s[38:39], 0, v[130:131]
	s_add_i32 m0, s50, 0x2000
	s_nop 0
	global_load_lds_dwordx4 v[212:213], off
	s_barrier
	s_waitcnt lgkmcnt(0)
	s_setprio 1
	s_waitcnt lgkmcnt(0)
	v_mfma_f32_16x16x32_bf16 v[110:113], v[208:211], v[162:165], v[110:113]
	v_mfma_f32_16x16x32_bf16 v[106:109], v[228:231], v[162:165], v[106:109]
	v_mfma_f32_16x16x32_bf16 v[94:97], v[208:211], v[170:173], v[94:97]
	v_mfma_f32_16x16x32_bf16 v[90:93], v[228:231], v[170:173], v[90:93]
	v_mfma_f32_16x16x32_bf16 v[78:81], v[208:211], v[192:195], v[78:81]
	v_mfma_f32_16x16x32_bf16 v[74:77], v[228:231], v[192:195], v[74:77]
	v_mfma_f32_16x16x32_bf16 v[70:73], v[208:211], v[200:203], v[70:73]
	v_mfma_f32_16x16x32_bf16 v[66:69], v[228:231], v[200:203], v[66:69]
	v_mfma_f32_16x16x32_bf16 v[110:113], v[224:227], v[166:169], v[110:113]
	v_mfma_f32_16x16x32_bf16 v[106:109], v[232:235], v[166:169], v[106:109]
	v_mfma_f32_16x16x32_bf16 v[94:97], v[224:227], v[174:177], v[94:97]
	v_mfma_f32_16x16x32_bf16 v[90:93], v[232:235], v[174:177], v[90:93]
	v_mfma_f32_16x16x32_bf16 v[78:81], v[224:227], v[196:199], v[78:81]
	v_mfma_f32_16x16x32_bf16 v[74:77], v[232:235], v[196:199], v[74:77]
	v_mfma_f32_16x16x32_bf16 v[70:73], v[224:227], v[204:207], v[70:73]
	v_mfma_f32_16x16x32_bf16 v[66:69], v[232:235], v[204:207], v[66:69]
	s_setprio 0
	s_mov_b32 m0, s27
	v_lshl_add_u64 v[236:237], s[22:23], 0, v[136:137]
	s_barrier
	ds_read_b128 v[162:165], v144 offset:16384
	ds_read_b128 v[170:173], v144 offset:18432
	ds_read_b128 v[192:195], v144 offset:20480
	ds_read_b128 v[200:203], v144 offset:22528
	ds_read_b128 v[166:169], v144 offset:17408
	ds_read_b128 v[174:177], v144 offset:19456
	ds_read_b128 v[196:199], v144 offset:21504
	ds_read_b128 v[204:207], v144 offset:23552
	global_load_lds_dwordx4 v[236:237], off
	v_lshl_add_u64 v[238:239], s[22:23], 0, v[132:133]
	s_mov_b32 m0, s28
	s_nop 0
	global_load_lds_dwordx4 v[238:239], off
	s_waitcnt vmcnt(10)
	s_barrier
	s_waitcnt lgkmcnt(4)
	s_setprio 1
	s_waitcnt lgkmcnt(4)
	v_mfma_f32_16x16x32_bf16 v[62:65], v[146:149], v[162:165], v[62:65]
	v_mfma_f32_16x16x32_bf16 v[58:61], v[154:157], v[162:165], v[58:61]
	v_mfma_f32_16x16x32_bf16 v[54:57], v[146:149], v[170:173], v[54:57]
	v_mfma_f32_16x16x32_bf16 v[50:53], v[154:157], v[170:173], v[50:53]
	v_mfma_f32_16x16x32_bf16 v[38:41], v[146:149], v[192:195], v[38:41]
	v_mfma_f32_16x16x32_bf16 v[34:37], v[154:157], v[192:195], v[34:37]
	v_mfma_f32_16x16x32_bf16 v[22:25], v[146:149], v[200:203], v[22:25]
	v_mfma_f32_16x16x32_bf16 v[18:21], v[154:157], v[200:203], v[18:21]
	s_waitcnt lgkmcnt(0)
	v_mfma_f32_16x16x32_bf16 v[62:65], v[150:153], v[166:169], v[62:65]
	v_mfma_f32_16x16x32_bf16 v[58:61], v[158:161], v[166:169], v[58:61]
	v_mfma_f32_16x16x32_bf16 v[54:57], v[150:153], v[174:177], v[54:57]
	v_mfma_f32_16x16x32_bf16 v[50:53], v[158:161], v[174:177], v[50:53]
	v_mfma_f32_16x16x32_bf16 v[38:41], v[150:153], v[196:199], v[38:41]
	v_mfma_f32_16x16x32_bf16 v[34:37], v[158:161], v[196:199], v[34:37]
	v_mfma_f32_16x16x32_bf16 v[22:25], v[150:153], v[204:207], v[22:25]
	v_mfma_f32_16x16x32_bf16 v[18:21], v[158:161], v[204:207], v[18:21]
	s_setprio 0
	s_barrier
	s_add_u32 s50, s38, 0x20000
	s_addc_u32 s51, s39, 0
	s_add_i32 s52, s52, s26
	v_lshl_add_u64 v[146:147], s[50:51], 0, v[134:135]
	s_mov_b32 m0, s52
	s_nop 0
	global_load_lds_dwordx4 v[146:147], off
	v_lshl_add_u64 v[146:147], s[50:51], 0, v[130:131]
	s_add_i32 m0, s52, 0x2000
	s_nop 0
	global_load_lds_dwordx4 v[146:147], off
	v_add_u32_e32 v145, 0x18000, v142
	ds_read_b128 v[146:149], v145
	ds_read_b128 v[150:153], v145 offset:1024
	ds_read_b128 v[154:157], v145 offset:2048
	ds_read_b128 v[158:161], v145 offset:3072
	s_waitcnt vmcnt(6)
	s_barrier
	s_setprio 1
	v_mfma_f32_16x16x32_bf16 v[46:49], v[208:211], v[162:165], v[46:49]
	v_mfma_f32_16x16x32_bf16 v[42:45], v[228:231], v[162:165], v[42:45]
	v_mfma_f32_16x16x32_bf16 v[30:33], v[208:211], v[170:173], v[30:33]
	v_mfma_f32_16x16x32_bf16 v[26:29], v[228:231], v[170:173], v[26:29]
	v_mfma_f32_16x16x32_bf16 v[14:17], v[208:211], v[192:195], v[14:17]
	v_mfma_f32_16x16x32_bf16 v[10:13], v[228:231], v[192:195], v[10:13]
	v_mfma_f32_16x16x32_bf16 v[6:9], v[208:211], v[200:203], v[6:9]
	v_mfma_f32_16x16x32_bf16 v[2:5], v[228:231], v[200:203], v[2:5]
	v_mfma_f32_16x16x32_bf16 v[46:49], v[224:227], v[166:169], v[46:49]
	v_mfma_f32_16x16x32_bf16 v[42:45], v[232:235], v[166:169], v[42:45]
	v_mfma_f32_16x16x32_bf16 v[30:33], v[224:227], v[174:177], v[30:33]
	v_mfma_f32_16x16x32_bf16 v[26:29], v[232:235], v[174:177], v[26:29]
	v_mfma_f32_16x16x32_bf16 v[14:17], v[224:227], v[196:199], v[14:17]
	v_mfma_f32_16x16x32_bf16 v[10:13], v[232:235], v[196:199], v[10:13]
	v_mfma_f32_16x16x32_bf16 v[6:9], v[224:227], v[204:207], v[6:9]
	v_mfma_f32_16x16x32_bf16 v[2:5], v[232:235], v[204:207], v[2:5]
	s_setprio 0
	s_add_i32 s50, 0, 0x18000
	s_barrier
	s_add_u32 s22, s22, 0x80000
	s_addc_u32 s23, s23, 0
	s_mov_b32 m0, s29
	v_lshl_add_u64 v[208:209], s[22:23], 0, v[136:137]
	ds_read_b128 v[162:165], v144 offset:32768
	ds_read_b128 v[170:173], v144 offset:34816
	ds_read_b128 v[192:195], v144 offset:36864
	ds_read_b128 v[200:203], v144 offset:38912
	ds_read_b128 v[166:169], v144 offset:33792
	ds_read_b128 v[174:177], v144 offset:35840
	ds_read_b128 v[196:199], v144 offset:37888
	ds_read_b128 v[204:207], v144 offset:39936
	global_load_lds_dwordx4 v[208:209], off
	v_lshl_add_u64 v[208:209], s[22:23], 0, v[132:133]
	s_mov_b32 m0, s36
	s_nop 0
	global_load_lds_dwordx4 v[208:209], off
	s_waitcnt lgkmcnt(8)
	s_barrier
	s_waitcnt lgkmcnt(4)
	s_setprio 1
	s_waitcnt lgkmcnt(4)
	v_mfma_f32_16x16x32_bf16 v[126:129], v[146:149], v[162:165], v[126:129]
	v_mfma_f32_16x16x32_bf16 v[122:125], v[154:157], v[162:165], v[122:125]
	v_mfma_f32_16x16x32_bf16 v[118:121], v[146:149], v[170:173], v[118:121]
	v_mfma_f32_16x16x32_bf16 v[114:117], v[154:157], v[170:173], v[114:117]
	v_mfma_f32_16x16x32_bf16 v[102:105], v[146:149], v[192:195], v[102:105]
	v_mfma_f32_16x16x32_bf16 v[98:101], v[154:157], v[192:195], v[98:101]
	v_mfma_f32_16x16x32_bf16 v[86:89], v[146:149], v[200:203], v[86:89]
	v_mfma_f32_16x16x32_bf16 v[82:85], v[154:157], v[200:203], v[82:85]
	s_waitcnt lgkmcnt(0)
	v_mfma_f32_16x16x32_bf16 v[126:129], v[150:153], v[166:169], v[126:129]
	v_mfma_f32_16x16x32_bf16 v[122:125], v[158:161], v[166:169], v[122:125]
	v_mfma_f32_16x16x32_bf16 v[118:121], v[150:153], v[174:177], v[118:121]
	v_mfma_f32_16x16x32_bf16 v[114:117], v[158:161], v[174:177], v[114:117]
	v_mfma_f32_16x16x32_bf16 v[102:105], v[150:153], v[196:199], v[102:105]
	v_mfma_f32_16x16x32_bf16 v[98:101], v[158:161], v[196:199], v[98:101]
	v_mfma_f32_16x16x32_bf16 v[86:89], v[150:153], v[204:207], v[86:89]
	v_mfma_f32_16x16x32_bf16 v[82:85], v[158:161], v[204:207], v[82:85]
	s_setprio 0
	s_barrier
	s_add_i32 s51, 0, 0x1c000
	s_add_i32 s22, s50, s26
	v_add_u32_e32 v145, s51, v142
	v_lshl_add_u64 v[178:179], v[178:179], 0, s[78:79]
	s_mov_b32 m0, s22
	ds_read_b128 v[208:211], v145
	ds_read_b128 v[224:227], v145 offset:1024
	ds_read_b128 v[228:231], v145 offset:2048
	ds_read_b128 v[232:235], v145 offset:3072
	global_load_lds_dwordx4 v[178:179], off
	v_lshl_add_u64 v[178:179], v[212:213], 0, s[78:79]
	s_add_i32 m0, s22, 0x2000
	s_nop 0
	global_load_lds_dwordx4 v[178:179], off
	s_barrier
	s_waitcnt lgkmcnt(0)
	s_setprio 1
	s_waitcnt lgkmcnt(0)
	v_mfma_f32_16x16x32_bf16 v[110:113], v[208:211], v[162:165], v[110:113]
	v_mfma_f32_16x16x32_bf16 v[106:109], v[228:231], v[162:165], v[106:109]
	v_mfma_f32_16x16x32_bf16 v[94:97], v[208:211], v[170:173], v[94:97]
	v_mfma_f32_16x16x32_bf16 v[90:93], v[228:231], v[170:173], v[90:93]
	v_mfma_f32_16x16x32_bf16 v[78:81], v[208:211], v[192:195], v[78:81]
	v_mfma_f32_16x16x32_bf16 v[74:77], v[228:231], v[192:195], v[74:77]
	v_mfma_f32_16x16x32_bf16 v[70:73], v[208:211], v[200:203], v[70:73]
	v_mfma_f32_16x16x32_bf16 v[66:69], v[228:231], v[200:203], v[66:69]
	v_mfma_f32_16x16x32_bf16 v[110:113], v[224:227], v[166:169], v[110:113]
	v_mfma_f32_16x16x32_bf16 v[106:109], v[232:235], v[166:169], v[106:109]
	v_mfma_f32_16x16x32_bf16 v[94:97], v[224:227], v[174:177], v[94:97]
	v_mfma_f32_16x16x32_bf16 v[90:93], v[232:235], v[174:177], v[90:93]
	v_mfma_f32_16x16x32_bf16 v[78:81], v[224:227], v[196:199], v[78:81]
	v_mfma_f32_16x16x32_bf16 v[74:77], v[232:235], v[196:199], v[74:77]
	v_mfma_f32_16x16x32_bf16 v[70:73], v[224:227], v[204:207], v[70:73]
	v_mfma_f32_16x16x32_bf16 v[66:69], v[232:235], v[204:207], v[66:69]
	s_setprio 0
	s_mov_b32 m0, s42
	v_lshl_add_u64 v[178:179], v[236:237], 0, s[78:79]
	s_barrier
	ds_read_b128 v[162:165], v144 offset:49152
	ds_read_b128 v[170:173], v144 offset:51200
	ds_read_b128 v[192:195], v144 offset:53248
	ds_read_b128 v[200:203], v144 offset:55296
	ds_read_b128 v[166:169], v144 offset:50176
	ds_read_b128 v[174:177], v144 offset:52224
	ds_read_b128 v[196:199], v144 offset:54272
	ds_read_b128 v[204:207], v144 offset:56320
	global_load_lds_dwordx4 v[178:179], off
	v_lshl_add_u64 v[178:179], v[238:239], 0, s[78:79]
	s_mov_b32 m0, s43
	s_nop 0
	global_load_lds_dwordx4 v[178:179], off
	s_waitcnt vmcnt(10)
	s_barrier
	s_waitcnt lgkmcnt(4)
	s_setprio 1
	s_waitcnt lgkmcnt(4)
	v_mfma_f32_16x16x32_bf16 v[62:65], v[146:149], v[162:165], v[62:65]
	v_mfma_f32_16x16x32_bf16 v[58:61], v[154:157], v[162:165], v[58:61]
	v_mfma_f32_16x16x32_bf16 v[54:57], v[146:149], v[170:173], v[54:57]
	v_mfma_f32_16x16x32_bf16 v[50:53], v[154:157], v[170:173], v[50:53]
	v_mfma_f32_16x16x32_bf16 v[38:41], v[146:149], v[192:195], v[38:41]
	v_mfma_f32_16x16x32_bf16 v[34:37], v[154:157], v[192:195], v[34:37]
	v_mfma_f32_16x16x32_bf16 v[22:25], v[146:149], v[200:203], v[22:25]
	v_mfma_f32_16x16x32_bf16 v[18:21], v[154:157], v[200:203], v[18:21]
	s_waitcnt lgkmcnt(0)
	v_mfma_f32_16x16x32_bf16 v[62:65], v[150:153], v[166:169], v[62:65]
	v_mfma_f32_16x16x32_bf16 v[58:61], v[158:161], v[166:169], v[58:61]
	v_mfma_f32_16x16x32_bf16 v[54:57], v[150:153], v[174:177], v[54:57]
	v_mfma_f32_16x16x32_bf16 v[50:53], v[158:161], v[174:177], v[50:53]
	v_mfma_f32_16x16x32_bf16 v[38:41], v[150:153], v[196:199], v[38:41]
	v_mfma_f32_16x16x32_bf16 v[34:37], v[158:161], v[196:199], v[34:37]
	v_mfma_f32_16x16x32_bf16 v[22:25], v[150:153], v[204:207], v[22:25]
	v_mfma_f32_16x16x32_bf16 v[18:21], v[158:161], v[204:207], v[18:21]
	s_setprio 0
	s_barrier
	s_add_u32 s22, s38, 0x20080
	s_addc_u32 s23, s39, 0
	s_add_i32 s38, s51, s26
	v_lshl_add_u64 v[146:147], s[22:23], 0, v[134:135]
	s_mov_b32 m0, s38
	s_nop 0
	global_load_lds_dwordx4 v[146:147], off
	v_lshl_add_u64 v[146:147], s[22:23], 0, v[130:131]
	s_add_i32 m0, s38, 0x2000
	s_nop 0
	global_load_lds_dwordx4 v[146:147], off
	v_add_u32_e32 v145, 0x10000, v142
	ds_read_b128 v[146:149], v145
	ds_read_b128 v[150:153], v145 offset:1024
	ds_read_b128 v[154:157], v145 offset:2048
	ds_read_b128 v[158:161], v145 offset:3072
	s_waitcnt vmcnt(6)
	s_barrier
	s_setprio 1
	v_mfma_f32_16x16x32_bf16 v[46:49], v[208:211], v[162:165], v[46:49]
	v_mfma_f32_16x16x32_bf16 v[42:45], v[228:231], v[162:165], v[42:45]
	v_mfma_f32_16x16x32_bf16 v[30:33], v[208:211], v[170:173], v[30:33]
	v_mfma_f32_16x16x32_bf16 v[26:29], v[228:231], v[170:173], v[26:29]
	v_mfma_f32_16x16x32_bf16 v[14:17], v[208:211], v[192:195], v[14:17]
	v_mfma_f32_16x16x32_bf16 v[10:13], v[228:231], v[192:195], v[10:13]
	v_mfma_f32_16x16x32_bf16 v[6:9], v[208:211], v[200:203], v[6:9]
	v_mfma_f32_16x16x32_bf16 v[2:5], v[228:231], v[200:203], v[2:5]
	v_mfma_f32_16x16x32_bf16 v[46:49], v[224:227], v[166:169], v[46:49]
	v_mfma_f32_16x16x32_bf16 v[42:45], v[232:235], v[166:169], v[42:45]
	v_mfma_f32_16x16x32_bf16 v[30:33], v[224:227], v[174:177], v[30:33]
	v_mfma_f32_16x16x32_bf16 v[26:29], v[232:235], v[174:177], v[26:29]
	v_mfma_f32_16x16x32_bf16 v[14:17], v[224:227], v[196:199], v[14:17]
	v_mfma_f32_16x16x32_bf16 v[10:13], v[232:235], v[196:199], v[10:13]
	v_mfma_f32_16x16x32_bf16 v[6:9], v[224:227], v[204:207], v[6:9]
	v_mfma_f32_16x16x32_bf16 v[2:5], v[232:235], v[204:207], v[2:5]
	s_setprio 0
	s_add_i32 s49, s49, 2
	s_add_u32 s20, s20, 0x100
	s_addc_u32 s21, s21, 0
	s_add_u32 s47, s47, 0x100
	s_addc_u32 s48, s48, 0
	s_cmp_gt_u32 s49, 5
	s_barrier
	s_cbranch_scc0 .LBB0_127
	s_waitcnt lgkmcnt(0)
	v_lshl_add_u32 v146, s46, 8, v1
	v_lshl_or_b32 v148, s45, 8, v143
	v_ashrrev_i32_e32 v147, 31, v146
	v_readlane_b32 s48, v254, 40
	v_ashrrev_i32_e32 v149, 31, v148
	v_lshlrev_b64 v[150:151], 12, v[146:147]
	v_readlane_b32 s52, v254, 44
	v_readlane_b32 s53, v254, 45
	v_lshlrev_b64 v[148:149], 1, v[148:149]
	s_mov_b32 s19, 0x80000
	v_lshl_add_u64 v[150:151], s[52:53], 0, v[150:151]
	v_lshl_add_u64 v[150:151], v[150:151], 0, v[148:149]
	s_mov_b64 s[20:21], 0x80000
	v_cvt_pk_bf16_f32 v62, v62, v63
	v_cvt_pk_bf16_f32 v63, v64, v65
	v_cvt_pk_bf16_f32 v64, v58, v59
	v_add_co_u32_e32 v58, vcc, s19, v150
	v_cvt_pk_bf16_f32 v70, v70, v71
	v_cvt_pk_bf16_f32 v71, v72, v73
	v_cvt_pk_bf16_f32 v72, v66, v67
	v_lshl_add_u64 v[66:67], v[150:151], 0, s[20:21]
	v_addc_co_u32_e32 v59, vcc, 0, v151, vcc
	v_cvt_pk_bf16_f32 v46, v46, v47
	v_cvt_pk_bf16_f32 v47, v48, v49
	v_cvt_pk_bf16_f32 v48, v42, v43
	v_cvt_pk_bf16_f32 v49, v44, v45
	s_mov_b32 s19, 0x90000
	v_cvt_pk_bf16_f32 v110, v110, v111
	v_cvt_pk_bf16_f32 v111, v112, v113
	v_cvt_pk_bf16_f32 v112, v106, v107
	v_or_b32_e32 v106, 16, v146
	global_store_dwordx4 v[66:67], v[46:49], off offset:256
	s_mov_b64 s[20:21], 0x90000
	v_ashrrev_i32_e32 v107, 31, v106
	v_add_co_u32_e32 v48, vcc, s19, v150
	v_cvt_pk_bf16_f32 v94, v94, v95
	v_cvt_pk_bf16_f32 v95, v96, v97
	v_cvt_pk_bf16_f32 v96, v90, v91
	v_or_b32_e32 v90, 32, v146
	v_lshl_add_u64 v[46:47], v[150:151], 0, s[20:21]
	v_addc_co_u32_e32 v49, vcc, 0, v151, vcc
	v_cvt_pk_bf16_f32 v30, v30, v31
	v_cvt_pk_bf16_f32 v31, v32, v33
	v_cvt_pk_bf16_f32 v32, v26, v27
	v_cvt_pk_bf16_f32 v33, v28, v29
	s_mov_b32 s19, 0xa0000
	v_lshlrev_b64 v[106:107], 12, v[106:107]
	v_ashrrev_i32_e32 v91, 31, v90
	v_cvt_pk_bf16_f32 v78, v78, v79
	v_cvt_pk_bf16_f32 v79, v80, v81
	v_cvt_pk_bf16_f32 v80, v74, v75
	v_or_b32_e32 v74, 48, v146
	global_store_dwordx4 v[46:47], v[30:33], off offset:256
	s_mov_b64 s[20:21], 0xa0000
	v_cvt_pk_bf16_f32 v113, v108, v109
	v_add_co_u32_e32 v32, vcc, s19, v150
	v_lshl_add_u64 v[106:107], s[52:53], 0, v[106:107]
	v_lshlrev_b64 v[90:91], 12, v[90:91]
	v_ashrrev_i32_e32 v75, 31, v74
	v_lshl_add_u64 v[30:31], v[150:151], 0, s[20:21]
	v_addc_co_u32_e32 v33, vcc, 0, v151, vcc
	v_cvt_pk_bf16_f32 v14, v14, v15
	v_cvt_pk_bf16_f32 v15, v16, v17
	v_cvt_pk_bf16_f32 v16, v10, v11
	v_cvt_pk_bf16_f32 v17, v12, v13
	s_mov_b32 s19, 0xb0000
	global_store_dwordx4 v[150:151], v[110:113], off offset:256
	v_cvt_pk_bf16_f32 v97, v92, v93
	v_lshl_add_u64 v[90:91], s[52:53], 0, v[90:91]
	v_lshl_add_u64 v[110:111], v[106:107], 0, v[148:149]
	v_lshlrev_b64 v[74:75], 12, v[74:75]
	global_store_dwordx4 v[30:31], v[14:17], off offset:256
	global_store_dwordx4 v[110:111], v[94:97], off offset:256
	v_cvt_pk_bf16_f32 v81, v76, v77
	v_add_co_u32_e32 v16, vcc, s19, v150
	v_lshl_add_u64 v[94:95], v[90:91], 0, v[148:149]
	v_lshl_add_u64 v[74:75], s[52:53], 0, v[74:75]
	s_mov_b64 s[20:21], 0xb0000
	v_addc_co_u32_e32 v17, vcc, 0, v151, vcc
	v_cvt_pk_bf16_f32 v126, v126, v127
	v_cvt_pk_bf16_f32 v127, v128, v129
	v_cvt_pk_bf16_f32 v128, v122, v123
	v_cvt_pk_bf16_f32 v129, v124, v125
	v_cvt_pk_bf16_f32 v106, v118, v119
	v_cvt_pk_bf16_f32 v107, v120, v121
	v_cvt_pk_bf16_f32 v108, v114, v115
	v_cvt_pk_bf16_f32 v109, v116, v117
	v_cvt_pk_bf16_f32 v90, v102, v103
	v_cvt_pk_bf16_f32 v91, v104, v105
	v_cvt_pk_bf16_f32 v92, v98, v99
	v_cvt_pk_bf16_f32 v93, v100, v101
	global_store_dwordx4 v[94:95], v[78:81], off offset:256
	v_cvt_pk_bf16_f32 v76, v82, v83
	v_cvt_pk_bf16_f32 v77, v84, v85
	v_lshl_add_u64 v[78:79], v[74:75], 0, v[148:149]
	v_cvt_pk_bf16_f32 v74, v86, v87
	v_cvt_pk_bf16_f32 v75, v88, v89
	v_cvt_pk_bf16_f32 v73, v68, v69
	v_cvt_pk_bf16_f32 v65, v60, v61
	v_cvt_pk_bf16_f32 v42, v54, v55
	v_cvt_pk_bf16_f32 v43, v56, v57
	v_cvt_pk_bf16_f32 v44, v50, v51
	v_cvt_pk_bf16_f32 v45, v52, v53
	v_cvt_pk_bf16_f32 v26, v38, v39
	v_cvt_pk_bf16_f32 v27, v40, v41
	v_cvt_pk_bf16_f32 v28, v34, v35
	v_cvt_pk_bf16_f32 v29, v36, v37
	v_lshl_add_u64 v[14:15], v[150:151], 0, s[20:21]
	v_cvt_pk_bf16_f32 v10, v22, v23
	v_cvt_pk_bf16_f32 v11, v24, v25
	v_cvt_pk_bf16_f32 v12, v18, v19
	v_cvt_pk_bf16_f32 v13, v20, v21
	v_cvt_pk_bf16_f32 v6, v6, v7
	v_cvt_pk_bf16_f32 v7, v8, v9
	v_cvt_pk_bf16_f32 v8, v2, v3
	v_cvt_pk_bf16_f32 v9, v4, v5
	s_and_b64 vcc, exec, s[0:1]
	s_mov_b32 s45, s18
	s_mov_b32 s46, s30
	s_mov_b64 s[22:23], s[82:83]
	s_mov_b64 s[20:21], s[80:81]
	s_mov_b32 s64, 0x800000
	s_movk_i32 s65, 0x1fff
	v_readlane_b32 s49, v254, 41
	v_readlane_b32 s50, v254, 42
	v_readlane_b32 s51, v254, 43
	v_readlane_b32 s54, v254, 46
	v_readlane_b32 s55, v254, 47
	v_readlane_b32 s56, v254, 48
	v_readlane_b32 s57, v254, 49
	v_readlane_b32 s58, v254, 50
	v_readlane_b32 s59, v254, 51
	v_readlane_b32 s60, v254, 52
	v_readlane_b32 s61, v254, 53
	v_readlane_b32 s62, v254, 54
	v_readlane_b32 s63, v254, 55
	global_store_dwordx4 v[150:151], v[126:129], off
	global_store_dwordx4 v[110:111], v[106:109], off
	global_store_dwordx4 v[94:95], v[90:93], off
	global_store_dwordx4 v[78:79], v[74:77], off
	global_store_dwordx4 v[78:79], v[70:73], off offset:256
	global_store_dwordx4 v[58:59], v[62:65], off
	global_store_dwordx4 v[48:49], v[42:45], off
	global_store_dwordx4 v[32:33], v[26:29], off
	global_store_dwordx4 v[16:17], v[10:13], off
	global_store_dwordx4 v[14:15], v[6:9], off offset:256
	s_cbranch_vccz .LBB0_118
	s_waitcnt vmcnt(0)
	v_readlane_b32 s44, v255, 30
	s_mov_b32 s66, s90
	s_cmpk_gt_u32 s25, 0xff
	v_readlane_b32 s45, v255, 31
	v_readlane_b32 s42, v255, 32
	s_cbranch_scc1 .LBB0_131
	s_barrier

.LBB0_240:
	s_add_u32 s22, s80, 0xfff80080
	s_addc_u32 s23, s81, -1
	s_add_i32 s52, 0, 0x10000
	s_cmp_eq_u32 s51, 28
	s_cselect_b32 s23, s21, s23
	s_cselect_b32 s22, s47, s22
	s_cselect_b32 s83, s19, s50
	s_cselect_b32 s82, s48, s49
	v_lshl_add_u64 v[178:179], s[80:81], 0, v[134:135]
	s_add_i32 m0, s27, 0xc000
	ds_read_b128 v[158:161], v140
	ds_read_b128 v[166:169], v140 offset:2048
	ds_read_b128 v[174:177], v140 offset:4096
	ds_read_b128 v[196:199], v140 offset:6144
	ds_read_b128 v[162:165], v140 offset:1024
	ds_read_b128 v[170:173], v140 offset:3072
	ds_read_b128 v[192:195], v140 offset:5120
	ds_read_b128 v[200:203], v140 offset:7168
	global_load_lds_dwordx4 v[178:179], off
	v_lshl_add_u64 v[178:179], s[80:81], 0, v[136:137]
	s_add_i32 m0, s27, 0xe000
	s_nop 0
	global_load_lds_dwordx4 v[178:179], off
	s_waitcnt lgkmcnt(8)
	s_barrier
	s_waitcnt lgkmcnt(4)
	s_setprio 1
	s_waitcnt lgkmcnt(4)
	v_mfma_f32_16x16x32_bf16 v[126:129], v[142:145], v[158:161], v[126:129]
	v_mfma_f32_16x16x32_bf16 v[122:125], v[150:153], v[158:161], v[122:125]
	v_mfma_f32_16x16x32_bf16 v[118:121], v[142:145], v[166:169], v[118:121]
	v_mfma_f32_16x16x32_bf16 v[114:117], v[150:153], v[166:169], v[114:117]
	v_mfma_f32_16x16x32_bf16 v[110:113], v[142:145], v[174:177], v[110:113]
	v_mfma_f32_16x16x32_bf16 v[102:105], v[150:153], v[174:177], v[102:105]
	v_mfma_f32_16x16x32_bf16 v[94:97], v[142:145], v[196:199], v[94:97]
	v_mfma_f32_16x16x32_bf16 v[86:89], v[150:153], v[196:199], v[86:89]
	s_waitcnt lgkmcnt(0)
	v_mfma_f32_16x16x32_bf16 v[126:129], v[146:149], v[162:165], v[126:129]
	v_mfma_f32_16x16x32_bf16 v[122:125], v[154:157], v[162:165], v[122:125]
	v_mfma_f32_16x16x32_bf16 v[118:121], v[146:149], v[170:173], v[118:121]
	v_mfma_f32_16x16x32_bf16 v[114:117], v[154:157], v[170:173], v[114:117]
	v_mfma_f32_16x16x32_bf16 v[110:113], v[146:149], v[192:195], v[110:113]
	v_mfma_f32_16x16x32_bf16 v[102:105], v[154:157], v[192:195], v[102:105]
	v_mfma_f32_16x16x32_bf16 v[94:97], v[146:149], v[200:203], v[94:97]
	v_mfma_f32_16x16x32_bf16 v[86:89], v[154:157], v[200:203], v[86:89]
	s_setprio 0
	s_barrier
	s_add_i32 s54, 0, 0x14000
	s_add_i32 s52, s52, s26
	v_add_u32_e32 v141, s54, v138
	v_lshl_add_u64 v[178:179], s[82:83], 0, v[132:133]
	s_mov_b32 m0, s52
	ds_read_b128 v[204:207], v141
	ds_read_b128 v[208:211], v141 offset:1024
	ds_read_b128 v[224:227], v141 offset:2048
	ds_read_b128 v[228:231], v141 offset:3072
	global_load_lds_dwordx4 v[178:179], off
	v_lshl_add_u64 v[212:213], s[82:83], 0, v[130:131]
	s_add_i32 m0, s52, 0x2000
	s_nop 0
	global_load_lds_dwordx4 v[212:213], off
	s_barrier
	s_waitcnt lgkmcnt(0)
	s_setprio 1
	s_waitcnt lgkmcnt(0)
	v_mfma_f32_16x16x32_bf16 v[106:109], v[204:207], v[158:161], v[106:109]
	v_mfma_f32_16x16x32_bf16 v[98:101], v[224:227], v[158:161], v[98:101]
	v_mfma_f32_16x16x32_bf16 v[90:93], v[204:207], v[166:169], v[90:93]
	v_mfma_f32_16x16x32_bf16 v[82:85], v[224:227], v[166:169], v[82:85]
	v_mfma_f32_16x16x32_bf16 v[78:81], v[204:207], v[174:177], v[78:81]
	v_mfma_f32_16x16x32_bf16 v[74:77], v[224:227], v[174:177], v[74:77]
	v_mfma_f32_16x16x32_bf16 v[70:73], v[204:207], v[196:199], v[70:73]
	v_mfma_f32_16x16x32_bf16 v[66:69], v[224:227], v[196:199], v[66:69]
	v_mfma_f32_16x16x32_bf16 v[106:109], v[208:211], v[162:165], v[106:109]
	v_mfma_f32_16x16x32_bf16 v[98:101], v[228:231], v[162:165], v[98:101]
	v_mfma_f32_16x16x32_bf16 v[90:93], v[208:211], v[170:173], v[90:93]
	v_mfma_f32_16x16x32_bf16 v[82:85], v[228:231], v[170:173], v[82:85]
	v_mfma_f32_16x16x32_bf16 v[78:81], v[208:211], v[192:195], v[78:81]
	v_mfma_f32_16x16x32_bf16 v[74:77], v[228:231], v[192:195], v[74:77]
	v_mfma_f32_16x16x32_bf16 v[70:73], v[208:211], v[200:203], v[70:73]
	v_mfma_f32_16x16x32_bf16 v[66:69], v[228:231], v[200:203], v[66:69]
	s_setprio 0
	s_mov_b32 m0, s27
	v_lshl_add_u64 v[232:233], s[22:23], 0, v[132:133]
	s_barrier
	ds_read_b128 v[158:161], v140 offset:16384
	ds_read_b128 v[166:169], v140 offset:18432
	ds_read_b128 v[174:177], v140 offset:20480
	ds_read_b128 v[196:199], v140 offset:22528
	ds_read_b128 v[162:165], v140 offset:17408
	ds_read_b128 v[170:173], v140 offset:19456
	ds_read_b128 v[192:195], v140 offset:21504
	ds_read_b128 v[200:203], v140 offset:23552
	global_load_lds_dwordx4 v[232:233], off
	v_lshl_add_u64 v[234:235], s[22:23], 0, v[130:131]
	s_mov_b32 m0, s28
	s_nop 0
	global_load_lds_dwordx4 v[234:235], off
	s_waitcnt vmcnt(10)
	s_barrier
	s_waitcnt lgkmcnt(4)
	s_setprio 1
	s_waitcnt lgkmcnt(4)
	v_mfma_f32_16x16x32_bf16 v[62:65], v[142:145], v[158:161], v[62:65]
	v_mfma_f32_16x16x32_bf16 v[58:61], v[150:153], v[158:161], v[58:61]
	v_mfma_f32_16x16x32_bf16 v[54:57], v[142:145], v[166:169], v[54:57]
	v_mfma_f32_16x16x32_bf16 v[50:53], v[150:153], v[166:169], v[50:53]
	v_mfma_f32_16x16x32_bf16 v[46:49], v[142:145], v[174:177], v[46:49]
	v_mfma_f32_16x16x32_bf16 v[38:41], v[150:153], v[174:177], v[38:41]
	v_mfma_f32_16x16x32_bf16 v[30:33], v[142:145], v[196:199], v[30:33]
	v_mfma_f32_16x16x32_bf16 v[22:25], v[150:153], v[196:199], v[22:25]
	s_waitcnt lgkmcnt(0)
	v_mfma_f32_16x16x32_bf16 v[62:65], v[146:149], v[162:165], v[62:65]
	v_mfma_f32_16x16x32_bf16 v[58:61], v[154:157], v[162:165], v[58:61]
	v_mfma_f32_16x16x32_bf16 v[54:57], v[146:149], v[170:173], v[54:57]
	v_mfma_f32_16x16x32_bf16 v[50:53], v[154:157], v[170:173], v[50:53]
	v_mfma_f32_16x16x32_bf16 v[46:49], v[146:149], v[192:195], v[46:49]
	v_mfma_f32_16x16x32_bf16 v[38:41], v[154:157], v[192:195], v[38:41]
	v_mfma_f32_16x16x32_bf16 v[30:33], v[146:149], v[200:203], v[30:33]
	v_mfma_f32_16x16x32_bf16 v[22:25], v[154:157], v[200:203], v[22:25]
	s_setprio 0
	s_barrier
	s_add_u32 s52, s82, 0x80000
	s_addc_u32 s53, s83, 0
	s_add_i32 s54, s54, s26
	v_lshl_add_u64 v[142:143], s[52:53], 0, v[132:133]
	s_mov_b32 m0, s54
	s_nop 0
	global_load_lds_dwordx4 v[142:143], off
	v_lshl_add_u64 v[142:143], s[52:53], 0, v[130:131]
	s_add_i32 m0, s54, 0x2000
	s_nop 0
	global_load_lds_dwordx4 v[142:143], off
	v_add_u32_e32 v141, 0x18000, v138
	ds_read_b128 v[142:145], v141
	ds_read_b128 v[146:149], v141 offset:1024
	ds_read_b128 v[150:153], v141 offset:2048
	ds_read_b128 v[154:157], v141 offset:3072
	s_waitcnt vmcnt(6)
	s_barrier
	s_setprio 1
	v_mfma_f32_16x16x32_bf16 v[42:45], v[204:207], v[158:161], v[42:45]
	v_mfma_f32_16x16x32_bf16 v[34:37], v[224:227], v[158:161], v[34:37]
	v_mfma_f32_16x16x32_bf16 v[26:29], v[204:207], v[166:169], v[26:29]
	v_mfma_f32_16x16x32_bf16 v[18:21], v[224:227], v[166:169], v[18:21]
	v_mfma_f32_16x16x32_bf16 v[14:17], v[204:207], v[174:177], v[14:17]
	v_mfma_f32_16x16x32_bf16 v[10:13], v[224:227], v[174:177], v[10:13]
	v_mfma_f32_16x16x32_bf16 v[6:9], v[204:207], v[196:199], v[6:9]
	v_mfma_f32_16x16x32_bf16 v[2:5], v[224:227], v[196:199], v[2:5]
	v_mfma_f32_16x16x32_bf16 v[42:45], v[208:211], v[162:165], v[42:45]
	v_mfma_f32_16x16x32_bf16 v[34:37], v[228:231], v[162:165], v[34:37]
	v_mfma_f32_16x16x32_bf16 v[26:29], v[208:211], v[170:173], v[26:29]
	v_mfma_f32_16x16x32_bf16 v[18:21], v[228:231], v[170:173], v[18:21]
	v_mfma_f32_16x16x32_bf16 v[14:17], v[208:211], v[192:195], v[14:17]
	v_mfma_f32_16x16x32_bf16 v[10:13], v[228:231], v[192:195], v[10:13]
	v_mfma_f32_16x16x32_bf16 v[6:9], v[208:211], v[200:203], v[6:9]
	v_mfma_f32_16x16x32_bf16 v[2:5], v[228:231], v[200:203], v[2:5]
	s_setprio 0
	s_add_i32 s52, 0, 0x18000
	s_barrier
	s_add_u32 s22, s22, 0x80000
	s_addc_u32 s23, s23, 0
	s_mov_b32 m0, s29
	v_lshl_add_u64 v[204:205], s[22:23], 0, v[132:133]
	ds_read_b128 v[158:161], v140 offset:32768
	ds_read_b128 v[166:169], v140 offset:34816
	ds_read_b128 v[174:177], v140 offset:36864
	ds_read_b128 v[196:199], v140 offset:38912
	ds_read_b128 v[162:165], v140 offset:33792
	ds_read_b128 v[170:173], v140 offset:35840
	ds_read_b128 v[192:195], v140 offset:37888
	ds_read_b128 v[200:203], v140 offset:39936
	global_load_lds_dwordx4 v[204:205], off
	v_lshl_add_u64 v[204:205], s[22:23], 0, v[130:131]
	s_mov_b32 m0, s36
	s_nop 0
	global_load_lds_dwordx4 v[204:205], off
	s_waitcnt lgkmcnt(8)
	s_barrier
	s_waitcnt lgkmcnt(4)
	s_setprio 1
	s_waitcnt lgkmcnt(4)
	v_mfma_f32_16x16x32_bf16 v[126:129], v[142:145], v[158:161], v[126:129]
	v_mfma_f32_16x16x32_bf16 v[122:125], v[150:153], v[158:161], v[122:125]
	v_mfma_f32_16x16x32_bf16 v[118:121], v[142:145], v[166:169], v[118:121]
	v_mfma_f32_16x16x32_bf16 v[114:117], v[150:153], v[166:169], v[114:117]
	v_mfma_f32_16x16x32_bf16 v[110:113], v[142:145], v[174:177], v[110:113]
	v_mfma_f32_16x16x32_bf16 v[102:105], v[150:153], v[174:177], v[102:105]
	v_mfma_f32_16x16x32_bf16 v[94:97], v[142:145], v[196:199], v[94:97]
	v_mfma_f32_16x16x32_bf16 v[86:89], v[150:153], v[196:199], v[86:89]
	s_waitcnt lgkmcnt(0)
	v_mfma_f32_16x16x32_bf16 v[126:129], v[146:149], v[162:165], v[126:129]
	v_mfma_f32_16x16x32_bf16 v[122:125], v[154:157], v[162:165], v[122:125]
	v_mfma_f32_16x16x32_bf16 v[118:121], v[146:149], v[170:173], v[118:121]
	v_mfma_f32_16x16x32_bf16 v[114:117], v[154:157], v[170:173], v[114:117]
	v_mfma_f32_16x16x32_bf16 v[110:113], v[146:149], v[192:195], v[110:113]
	v_mfma_f32_16x16x32_bf16 v[102:105], v[154:157], v[192:195], v[102:105]
	v_mfma_f32_16x16x32_bf16 v[94:97], v[146:149], v[200:203], v[94:97]
	v_mfma_f32_16x16x32_bf16 v[86:89], v[154:157], v[200:203], v[86:89]
	s_setprio 0
	s_barrier
	s_add_i32 s53, 0, 0x1c000
	s_add_i32 s22, s52, s26
	v_add_u32_e32 v141, s53, v138
	v_lshl_add_u64 v[178:179], v[178:179], 0, s[78:79]
	s_mov_b32 m0, s22
	ds_read_b128 v[204:207], v141
	ds_read_b128 v[208:211], v141 offset:1024
	ds_read_b128 v[224:227], v141 offset:2048
	ds_read_b128 v[228:231], v141 offset:3072
	global_load_lds_dwordx4 v[178:179], off
	v_lshl_add_u64 v[178:179], v[212:213], 0, s[78:79]
	s_add_i32 m0, s22, 0x2000
	s_nop 0
	global_load_lds_dwordx4 v[178:179], off
	s_barrier
	s_waitcnt lgkmcnt(0)
	s_setprio 1
	s_waitcnt lgkmcnt(0)
	v_mfma_f32_16x16x32_bf16 v[106:109], v[204:207], v[158:161], v[106:109]
	v_mfma_f32_16x16x32_bf16 v[98:101], v[224:227], v[158:161], v[98:101]
	v_mfma_f32_16x16x32_bf16 v[90:93], v[204:207], v[166:169], v[90:93]
	v_mfma_f32_16x16x32_bf16 v[82:85], v[224:227], v[166:169], v[82:85]
	v_mfma_f32_16x16x32_bf16 v[78:81], v[204:207], v[174:177], v[78:81]
	v_mfma_f32_16x16x32_bf16 v[74:77], v[224:227], v[174:177], v[74:77]
	v_mfma_f32_16x16x32_bf16 v[70:73], v[204:207], v[196:199], v[70:73]
	v_mfma_f32_16x16x32_bf16 v[66:69], v[224:227], v[196:199], v[66:69]
	v_mfma_f32_16x16x32_bf16 v[106:109], v[208:211], v[162:165], v[106:109]
	v_mfma_f32_16x16x32_bf16 v[98:101], v[228:231], v[162:165], v[98:101]
	v_mfma_f32_16x16x32_bf16 v[90:93], v[208:211], v[170:173], v[90:93]
	v_mfma_f32_16x16x32_bf16 v[82:85], v[228:231], v[170:173], v[82:85]
	v_mfma_f32_16x16x32_bf16 v[78:81], v[208:211], v[192:195], v[78:81]
	v_mfma_f32_16x16x32_bf16 v[74:77], v[228:231], v[192:195], v[74:77]
	v_mfma_f32_16x16x32_bf16 v[70:73], v[208:211], v[200:203], v[70:73]
	v_mfma_f32_16x16x32_bf16 v[66:69], v[228:231], v[200:203], v[66:69]
	s_setprio 0
	s_mov_b32 m0, s42
	v_lshl_add_u64 v[178:179], v[232:233], 0, s[78:79]
	s_barrier
	ds_read_b128 v[158:161], v140 offset:49152
	ds_read_b128 v[166:169], v140 offset:51200
	ds_read_b128 v[174:177], v140 offset:53248
	ds_read_b128 v[196:199], v140 offset:55296
	ds_read_b128 v[162:165], v140 offset:50176
	ds_read_b128 v[170:173], v140 offset:52224
	ds_read_b128 v[192:195], v140 offset:54272
	ds_read_b128 v[200:203], v140 offset:56320
	global_load_lds_dwordx4 v[178:179], off
	v_lshl_add_u64 v[178:179], v[234:235], 0, s[78:79]
	s_mov_b32 m0, s43
	s_nop 0
	global_load_lds_dwordx4 v[178:179], off
	s_waitcnt vmcnt(10)
	s_barrier
	s_waitcnt lgkmcnt(4)
	s_setprio 1
	s_waitcnt lgkmcnt(4)
	v_mfma_f32_16x16x32_bf16 v[62:65], v[142:145], v[158:161], v[62:65]
	v_mfma_f32_16x16x32_bf16 v[58:61], v[150:153], v[158:161], v[58:61]
	v_mfma_f32_16x16x32_bf16 v[54:57], v[142:145], v[166:169], v[54:57]
	v_mfma_f32_16x16x32_bf16 v[50:53], v[150:153], v[166:169], v[50:53]
	v_mfma_f32_16x16x32_bf16 v[46:49], v[142:145], v[174:177], v[46:49]
	v_mfma_f32_16x16x32_bf16 v[38:41], v[150:153], v[174:177], v[38:41]
	v_mfma_f32_16x16x32_bf16 v[30:33], v[142:145], v[196:199], v[30:33]
	v_mfma_f32_16x16x32_bf16 v[22:25], v[150:153], v[196:199], v[22:25]
	s_waitcnt lgkmcnt(0)
	v_mfma_f32_16x16x32_bf16 v[62:65], v[146:149], v[162:165], v[62:65]
	v_mfma_f32_16x16x32_bf16 v[58:61], v[154:157], v[162:165], v[58:61]
	v_mfma_f32_16x16x32_bf16 v[54:57], v[146:149], v[170:173], v[54:57]
	v_mfma_f32_16x16x32_bf16 v[50:53], v[154:157], v[170:173], v[50:53]
	v_mfma_f32_16x16x32_bf16 v[46:49], v[146:149], v[192:195], v[46:49]
	v_mfma_f32_16x16x32_bf16 v[38:41], v[154:157], v[192:195], v[38:41]
	v_mfma_f32_16x16x32_bf16 v[30:33], v[146:149], v[200:203], v[30:33]
	v_mfma_f32_16x16x32_bf16 v[22:25], v[154:157], v[200:203], v[22:25]
	s_setprio 0
	s_barrier
	s_add_u32 s22, s82, 0x80080
	s_addc_u32 s23, s83, 0
	s_add_i32 s52, s53, s26
	v_lshl_add_u64 v[142:143], s[22:23], 0, v[132:133]
	s_mov_b32 m0, s52
	s_nop 0
	global_load_lds_dwordx4 v[142:143], off
	v_lshl_add_u64 v[142:143], s[22:23], 0, v[130:131]
	s_add_i32 m0, s52, 0x2000
	s_nop 0
	global_load_lds_dwordx4 v[142:143], off
	v_add_u32_e32 v141, 0x10000, v138
	ds_read_b128 v[142:145], v141
	ds_read_b128 v[146:149], v141 offset:1024
	ds_read_b128 v[150:153], v141 offset:2048
	ds_read_b128 v[154:157], v141 offset:3072
	s_waitcnt vmcnt(6)
	s_barrier
	s_setprio 1
	v_mfma_f32_16x16x32_bf16 v[42:45], v[204:207], v[158:161], v[42:45]
	v_mfma_f32_16x16x32_bf16 v[34:37], v[224:227], v[158:161], v[34:37]
	v_mfma_f32_16x16x32_bf16 v[26:29], v[204:207], v[166:169], v[26:29]
	v_mfma_f32_16x16x32_bf16 v[18:21], v[224:227], v[166:169], v[18:21]
	v_mfma_f32_16x16x32_bf16 v[14:17], v[204:207], v[174:177], v[14:17]
	v_mfma_f32_16x16x32_bf16 v[10:13], v[224:227], v[174:177], v[10:13]
	v_mfma_f32_16x16x32_bf16 v[6:9], v[204:207], v[196:199], v[6:9]
	v_mfma_f32_16x16x32_bf16 v[2:5], v[224:227], v[196:199], v[2:5]
	v_mfma_f32_16x16x32_bf16 v[42:45], v[208:211], v[162:165], v[42:45]
	v_mfma_f32_16x16x32_bf16 v[34:37], v[228:231], v[162:165], v[34:37]
	v_mfma_f32_16x16x32_bf16 v[26:29], v[208:211], v[170:173], v[26:29]
	v_mfma_f32_16x16x32_bf16 v[18:21], v[228:231], v[170:173], v[18:21]
	v_mfma_f32_16x16x32_bf16 v[14:17], v[208:211], v[192:195], v[14:17]
	v_mfma_f32_16x16x32_bf16 v[10:13], v[228:231], v[192:195], v[10:13]
	v_mfma_f32_16x16x32_bf16 v[6:9], v[208:211], v[200:203], v[6:9]
	v_mfma_f32_16x16x32_bf16 v[2:5], v[228:231], v[200:203], v[2:5]
	s_setprio 0
	s_add_i32 s51, s51, 2
	s_add_u32 s80, s80, 0x100
	s_addc_u32 s81, s81, 0
	s_add_u32 s49, s49, 0x100
	s_addc_u32 s50, s50, 0
	s_cmp_gt_u32 s51, 29
	s_barrier
	s_cbranch_scc0 .LBB0_240
	s_waitcnt lgkmcnt(0)
	v_readlane_b32 s48, v254, 40
	v_lshl_or_b32 v142, s45, 8, v139
	v_readlane_b32 s52, v254, 44
	v_readlane_b32 s53, v254, 45
	v_lshl_add_u32 v141, s46, 8, v1
	v_ashrrev_i32_e32 v143, 31, v142
	v_mov_b64_e32 v[144:145], s[52:53]
	s_movk_i32 s19, 0x1400
	v_mad_i64_i32 v[146:147], s[22:23], v141, s19, v[144:145]
	v_lshlrev_b64 v[142:143], 2, v[142:143]
	v_lshl_add_u64 v[146:147], v[146:147], 0, v[142:143]
	global_store_dwordx4 v[146:147], v[126:129], off
	global_store_dwordx4 v[146:147], v[122:125], off offset:64
	global_store_dwordx4 v[146:147], v[106:109], off offset:512
	global_store_dwordx4 v[146:147], v[98:101], off offset:576
	s_movk_i32 s94, 0x1400
	s_and_b64 vcc, exec, s[0:1]
	v_or_b32_e32 v98, 16, v141
	v_mad_i64_i32 v[98:99], s[22:23], v98, s19, v[144:145]
	v_lshl_add_u64 v[98:99], v[98:99], 0, v[142:143]
	global_store_dwordx4 v[98:99], v[118:121], off
	global_store_dwordx4 v[98:99], v[114:117], off offset:64
	global_store_dwordx4 v[98:99], v[90:93], off offset:512
	global_store_dwordx4 v[98:99], v[82:85], off offset:576
	s_mov_b32 s45, s18
	s_mov_b32 s46, s20
	v_or_b32_e32 v82, 32, v141
	v_mad_i64_i32 v[82:83], s[22:23], v82, s19, v[144:145]
	v_lshl_add_u64 v[82:83], v[82:83], 0, v[142:143]
	global_store_dwordx4 v[82:83], v[110:113], off
	global_store_dwordx4 v[82:83], v[102:105], off offset:64
	global_store_dwordx4 v[82:83], v[78:81], off offset:512
	global_store_dwordx4 v[82:83], v[74:77], off offset:576
	s_mov_b64 s[80:81], s[30:31]
	v_readlane_b32 s49, v254, 41
	v_or_b32_e32 v74, 48, v141
	v_mad_i64_i32 v[74:75], s[22:23], v74, s19, v[144:145]
	v_lshl_add_u64 v[74:75], v[74:75], 0, v[142:143]
	global_store_dwordx4 v[74:75], v[94:97], off
	global_store_dwordx4 v[74:75], v[86:89], off offset:64
	global_store_dwordx4 v[74:75], v[70:73], off offset:512
	global_store_dwordx4 v[74:75], v[66:69], off offset:576
	v_readlane_b32 s50, v254, 42
	v_readlane_b32 s51, v254, 43
	v_add_u32_e32 v66, 0x80, v141
	v_mad_i64_i32 v[66:67], s[22:23], v66, s19, v[144:145]
	v_lshl_add_u64 v[66:67], v[66:67], 0, v[142:143]
	global_store_dwordx4 v[66:67], v[62:65], off
	global_store_dwordx4 v[66:67], v[58:61], off offset:64
	global_store_dwordx4 v[66:67], v[42:45], off offset:512
	global_store_dwordx4 v[66:67], v[34:37], off offset:576
	v_readlane_b32 s54, v254, 46
	v_readlane_b32 s55, v254, 47
	v_add_u32_e32 v34, 0x90, v141
	v_mad_i64_i32 v[34:35], s[22:23], v34, s19, v[144:145]
	v_lshl_add_u64 v[34:35], v[34:35], 0, v[142:143]
	global_store_dwordx4 v[34:35], v[54:57], off
	global_store_dwordx4 v[34:35], v[50:53], off offset:64
	global_store_dwordx4 v[34:35], v[26:29], off offset:512
	global_store_dwordx4 v[34:35], v[18:21], off offset:576
	v_readlane_b32 s56, v254, 48
	v_readlane_b32 s57, v254, 49
	v_add_u32_e32 v18, 0xa0, v141
	v_mad_i64_i32 v[18:19], s[22:23], v18, s19, v[144:145]
	v_lshl_add_u64 v[18:19], v[18:19], 0, v[142:143]
	global_store_dwordx4 v[18:19], v[46:49], off
	global_store_dwordx4 v[18:19], v[38:41], off offset:64
	global_store_dwordx4 v[18:19], v[14:17], off offset:512
	global_store_dwordx4 v[18:19], v[10:13], off offset:576
	v_readlane_b32 s58, v254, 50
	v_readlane_b32 s59, v254, 51
	v_add_u32_e32 v10, 0xb0, v141
	v_mad_i64_i32 v[10:11], s[22:23], v10, s19, v[144:145]
	v_lshl_add_u64 v[10:11], v[10:11], 0, v[142:143]
	s_mov_b64 s[22:23], s[38:39]
	v_readlane_b32 s60, v254, 52
	v_readlane_b32 s61, v254, 53
	v_readlane_b32 s62, v254, 54
	v_readlane_b32 s63, v254, 55
	global_store_dwordx4 v[10:11], v[30:33], off
	global_store_dwordx4 v[10:11], v[22:25], off offset:64
	global_store_dwordx4 v[10:11], v[6:9], off offset:512
	global_store_dwordx4 v[10:11], v[2:5], off offset:576
	s_cbranch_vccz .LBB0_237
	s_waitcnt vmcnt(0)
	v_readlane_b32 s44, v255, 30
	s_cmpk_gt_u32 s25, 0xff
	v_readlane_b32 s45, v255, 31
	v_readlane_b32 s42, v255, 32
	s_cbranch_scc1 .LBB0_244
	s_barrier

.LBB0_357:
	s_add_u32 s22, s20, 0xfffe0080
	s_addc_u32 s23, s21, -1
	s_add_i32 s52, 0, 0x10000
	s_cmp_eq_u32 s51, 4
	s_cselect_b32 s23, s31, s23
	s_cselect_b32 s22, s47, s22
	s_cselect_b32 s85, s19, s50
	s_cselect_b32 s84, s48, s49
	v_lshl_add_u64 v[178:179], s[20:21], 0, v[138:139]
	s_add_i32 m0, s27, 0xc000
	ds_read_b128 v[162:165], v144
	ds_read_b128 v[170:173], v144 offset:2048
	ds_read_b128 v[192:195], v144 offset:4096
	ds_read_b128 v[200:203], v144 offset:6144
	ds_read_b128 v[166:169], v144 offset:1024
	ds_read_b128 v[174:177], v144 offset:3072
	ds_read_b128 v[196:199], v144 offset:5120
	ds_read_b128 v[204:207], v144 offset:7168
	global_load_lds_dwordx4 v[178:179], off
	v_lshl_add_u64 v[178:179], s[20:21], 0, v[140:141]
	s_add_i32 m0, s27, 0xe000
	s_nop 0
	global_load_lds_dwordx4 v[178:179], off
	s_waitcnt lgkmcnt(8)
	s_barrier
	s_waitcnt lgkmcnt(4)
	s_setprio 1
	s_waitcnt lgkmcnt(4)
	v_mfma_f32_16x16x32_bf16 v[126:129], v[146:149], v[162:165], v[126:129]
	v_mfma_f32_16x16x32_bf16 v[122:125], v[154:157], v[162:165], v[122:125]
	v_mfma_f32_16x16x32_bf16 v[118:121], v[146:149], v[170:173], v[118:121]
	v_mfma_f32_16x16x32_bf16 v[114:117], v[154:157], v[170:173], v[114:117]
	v_mfma_f32_16x16x32_bf16 v[102:105], v[146:149], v[192:195], v[102:105]
	v_mfma_f32_16x16x32_bf16 v[98:101], v[154:157], v[192:195], v[98:101]
	v_mfma_f32_16x16x32_bf16 v[86:89], v[146:149], v[200:203], v[86:89]
	v_mfma_f32_16x16x32_bf16 v[82:85], v[154:157], v[200:203], v[82:85]
	s_waitcnt lgkmcnt(0)
	v_mfma_f32_16x16x32_bf16 v[126:129], v[150:153], v[166:169], v[126:129]
	v_mfma_f32_16x16x32_bf16 v[122:125], v[158:161], v[166:169], v[122:125]
	v_mfma_f32_16x16x32_bf16 v[118:121], v[150:153], v[174:177], v[118:121]
	v_mfma_f32_16x16x32_bf16 v[114:117], v[158:161], v[174:177], v[114:117]
	v_mfma_f32_16x16x32_bf16 v[102:105], v[150:153], v[196:199], v[102:105]
	v_mfma_f32_16x16x32_bf16 v[98:101], v[158:161], v[196:199], v[98:101]
	v_mfma_f32_16x16x32_bf16 v[86:89], v[150:153], v[204:207], v[86:89]
	v_mfma_f32_16x16x32_bf16 v[82:85], v[158:161], v[204:207], v[82:85]
	s_setprio 0
	s_barrier
	s_add_i32 s54, 0, 0x14000
	s_add_i32 s52, s52, s26
	v_add_u32_e32 v145, s54, v142
	v_lshl_add_u64 v[178:179], s[84:85], 0, v[134:135]
	s_mov_b32 m0, s52
	ds_read_b128 v[208:211], v145
	ds_read_b128 v[224:227], v145 offset:1024
	ds_read_b128 v[228:231], v145 offset:2048
	ds_read_b128 v[232:235], v145 offset:3072
	global_load_lds_dwordx4 v[178:179], off
	v_lshl_add_u64 v[212:213], s[84:85], 0, v[130:131]
	s_add_i32 m0, s52, 0x2000
	s_nop 0
	global_load_lds_dwordx4 v[212:213], off
	s_barrier
	s_waitcnt lgkmcnt(0)
	s_setprio 1
	s_waitcnt lgkmcnt(0)
	v_mfma_f32_16x16x32_bf16 v[110:113], v[208:211], v[162:165], v[110:113]
	v_mfma_f32_16x16x32_bf16 v[106:109], v[228:231], v[162:165], v[106:109]
	v_mfma_f32_16x16x32_bf16 v[94:97], v[208:211], v[170:173], v[94:97]
	v_mfma_f32_16x16x32_bf16 v[90:93], v[228:231], v[170:173], v[90:93]
	v_mfma_f32_16x16x32_bf16 v[78:81], v[208:211], v[192:195], v[78:81]
	v_mfma_f32_16x16x32_bf16 v[74:77], v[228:231], v[192:195], v[74:77]
	v_mfma_f32_16x16x32_bf16 v[70:73], v[208:211], v[200:203], v[70:73]
	v_mfma_f32_16x16x32_bf16 v[66:69], v[228:231], v[200:203], v[66:69]
	v_mfma_f32_16x16x32_bf16 v[110:113], v[224:227], v[166:169], v[110:113]
	v_mfma_f32_16x16x32_bf16 v[106:109], v[232:235], v[166:169], v[106:109]
	v_mfma_f32_16x16x32_bf16 v[94:97], v[224:227], v[174:177], v[94:97]
	v_mfma_f32_16x16x32_bf16 v[90:93], v[232:235], v[174:177], v[90:93]
	v_mfma_f32_16x16x32_bf16 v[78:81], v[224:227], v[196:199], v[78:81]
	v_mfma_f32_16x16x32_bf16 v[74:77], v[232:235], v[196:199], v[74:77]
	v_mfma_f32_16x16x32_bf16 v[70:73], v[224:227], v[204:207], v[70:73]
	v_mfma_f32_16x16x32_bf16 v[66:69], v[232:235], v[204:207], v[66:69]
	s_setprio 0
	s_mov_b32 m0, s27
	v_lshl_add_u64 v[236:237], s[22:23], 0, v[136:137]
	s_barrier
	ds_read_b128 v[162:165], v144 offset:16384
	ds_read_b128 v[170:173], v144 offset:18432
	ds_read_b128 v[192:195], v144 offset:20480
	ds_read_b128 v[200:203], v144 offset:22528
	ds_read_b128 v[166:169], v144 offset:17408
	ds_read_b128 v[174:177], v144 offset:19456
	ds_read_b128 v[196:199], v144 offset:21504
	ds_read_b128 v[204:207], v144 offset:23552
	global_load_lds_dwordx4 v[236:237], off
	v_lshl_add_u64 v[238:239], s[22:23], 0, v[132:133]
	s_mov_b32 m0, s28
	s_nop 0
	global_load_lds_dwordx4 v[238:239], off
	s_waitcnt vmcnt(10)
	s_barrier
	s_waitcnt lgkmcnt(4)
	s_setprio 1
	s_waitcnt lgkmcnt(4)
	v_mfma_f32_16x16x32_bf16 v[62:65], v[146:149], v[162:165], v[62:65]
	v_mfma_f32_16x16x32_bf16 v[58:61], v[154:157], v[162:165], v[58:61]
	v_mfma_f32_16x16x32_bf16 v[54:57], v[146:149], v[170:173], v[54:57]
	v_mfma_f32_16x16x32_bf16 v[50:53], v[154:157], v[170:173], v[50:53]
	v_mfma_f32_16x16x32_bf16 v[38:41], v[146:149], v[192:195], v[38:41]
	v_mfma_f32_16x16x32_bf16 v[34:37], v[154:157], v[192:195], v[34:37]
	v_mfma_f32_16x16x32_bf16 v[22:25], v[146:149], v[200:203], v[22:25]
	v_mfma_f32_16x16x32_bf16 v[18:21], v[154:157], v[200:203], v[18:21]
	s_waitcnt lgkmcnt(0)
	v_mfma_f32_16x16x32_bf16 v[62:65], v[150:153], v[166:169], v[62:65]
	v_mfma_f32_16x16x32_bf16 v[58:61], v[158:161], v[166:169], v[58:61]
	v_mfma_f32_16x16x32_bf16 v[54:57], v[150:153], v[174:177], v[54:57]
	v_mfma_f32_16x16x32_bf16 v[50:53], v[158:161], v[174:177], v[50:53]
	v_mfma_f32_16x16x32_bf16 v[38:41], v[150:153], v[196:199], v[38:41]
	v_mfma_f32_16x16x32_bf16 v[34:37], v[158:161], v[196:199], v[34:37]
	v_mfma_f32_16x16x32_bf16 v[22:25], v[150:153], v[204:207], v[22:25]
	v_mfma_f32_16x16x32_bf16 v[18:21], v[158:161], v[204:207], v[18:21]
	s_setprio 0
	s_barrier
	s_add_u32 s52, s84, 0x20000
	s_addc_u32 s53, s85, 0
	s_add_i32 s54, s54, s26
	v_lshl_add_u64 v[146:147], s[52:53], 0, v[134:135]
	s_mov_b32 m0, s54
	s_nop 0
	global_load_lds_dwordx4 v[146:147], off
	v_lshl_add_u64 v[146:147], s[52:53], 0, v[130:131]
	s_add_i32 m0, s54, 0x2000
	s_nop 0
	global_load_lds_dwordx4 v[146:147], off
	v_add_u32_e32 v145, 0x18000, v142
	ds_read_b128 v[146:149], v145
	ds_read_b128 v[150:153], v145 offset:1024
	ds_read_b128 v[154:157], v145 offset:2048
	ds_read_b128 v[158:161], v145 offset:3072
	s_waitcnt vmcnt(6)
	s_barrier
	s_setprio 1
	v_mfma_f32_16x16x32_bf16 v[46:49], v[208:211], v[162:165], v[46:49]
	v_mfma_f32_16x16x32_bf16 v[42:45], v[228:231], v[162:165], v[42:45]
	v_mfma_f32_16x16x32_bf16 v[30:33], v[208:211], v[170:173], v[30:33]
	v_mfma_f32_16x16x32_bf16 v[26:29], v[228:231], v[170:173], v[26:29]
	v_mfma_f32_16x16x32_bf16 v[14:17], v[208:211], v[192:195], v[14:17]
	v_mfma_f32_16x16x32_bf16 v[10:13], v[228:231], v[192:195], v[10:13]
	v_mfma_f32_16x16x32_bf16 v[6:9], v[208:211], v[200:203], v[6:9]
	v_mfma_f32_16x16x32_bf16 v[2:5], v[228:231], v[200:203], v[2:5]
	v_mfma_f32_16x16x32_bf16 v[46:49], v[224:227], v[166:169], v[46:49]
	v_mfma_f32_16x16x32_bf16 v[42:45], v[232:235], v[166:169], v[42:45]
	v_mfma_f32_16x16x32_bf16 v[30:33], v[224:227], v[174:177], v[30:33]
	v_mfma_f32_16x16x32_bf16 v[26:29], v[232:235], v[174:177], v[26:29]
	v_mfma_f32_16x16x32_bf16 v[14:17], v[224:227], v[196:199], v[14:17]
	v_mfma_f32_16x16x32_bf16 v[10:13], v[232:235], v[196:199], v[10:13]
	v_mfma_f32_16x16x32_bf16 v[6:9], v[224:227], v[204:207], v[6:9]
	v_mfma_f32_16x16x32_bf16 v[2:5], v[232:235], v[204:207], v[2:5]
	s_setprio 0
	s_add_i32 s52, 0, 0x18000
	s_barrier
	s_add_u32 s22, s22, 0x20000
	s_addc_u32 s23, s23, 0
	s_mov_b32 m0, s29
	v_lshl_add_u64 v[208:209], s[22:23], 0, v[136:137]
	ds_read_b128 v[162:165], v144 offset:32768
	ds_read_b128 v[170:173], v144 offset:34816
	ds_read_b128 v[192:195], v144 offset:36864
	ds_read_b128 v[200:203], v144 offset:38912
	ds_read_b128 v[166:169], v144 offset:33792
	ds_read_b128 v[174:177], v144 offset:35840
	ds_read_b128 v[196:199], v144 offset:37888
	ds_read_b128 v[204:207], v144 offset:39936
	global_load_lds_dwordx4 v[208:209], off
	v_lshl_add_u64 v[208:209], s[22:23], 0, v[132:133]
	s_mov_b32 m0, s36
	s_nop 0
	global_load_lds_dwordx4 v[208:209], off
	s_waitcnt lgkmcnt(8)
	s_barrier
	s_waitcnt lgkmcnt(4)
	s_setprio 1
	s_waitcnt lgkmcnt(4)
	v_mfma_f32_16x16x32_bf16 v[126:129], v[146:149], v[162:165], v[126:129]
	v_mfma_f32_16x16x32_bf16 v[122:125], v[154:157], v[162:165], v[122:125]
	v_mfma_f32_16x16x32_bf16 v[118:121], v[146:149], v[170:173], v[118:121]
	v_mfma_f32_16x16x32_bf16 v[114:117], v[154:157], v[170:173], v[114:117]
	v_mfma_f32_16x16x32_bf16 v[102:105], v[146:149], v[192:195], v[102:105]
	v_mfma_f32_16x16x32_bf16 v[98:101], v[154:157], v[192:195], v[98:101]
	v_mfma_f32_16x16x32_bf16 v[86:89], v[146:149], v[200:203], v[86:89]
	v_mfma_f32_16x16x32_bf16 v[82:85], v[154:157], v[200:203], v[82:85]
	s_waitcnt lgkmcnt(0)
	v_mfma_f32_16x16x32_bf16 v[126:129], v[150:153], v[166:169], v[126:129]
	v_mfma_f32_16x16x32_bf16 v[122:125], v[158:161], v[166:169], v[122:125]
	v_mfma_f32_16x16x32_bf16 v[118:121], v[150:153], v[174:177], v[118:121]
	v_mfma_f32_16x16x32_bf16 v[114:117], v[158:161], v[174:177], v[114:117]
	v_mfma_f32_16x16x32_bf16 v[102:105], v[150:153], v[196:199], v[102:105]
	v_mfma_f32_16x16x32_bf16 v[98:101], v[158:161], v[196:199], v[98:101]
	v_mfma_f32_16x16x32_bf16 v[86:89], v[150:153], v[204:207], v[86:89]
	v_mfma_f32_16x16x32_bf16 v[82:85], v[158:161], v[204:207], v[82:85]
	s_setprio 0
	s_barrier
	s_add_i32 s53, 0, 0x1c000
	s_add_i32 s22, s52, s26
	v_add_u32_e32 v145, s53, v142
	v_lshl_add_u64 v[178:179], v[178:179], 0, s[78:79]
	s_mov_b32 m0, s22
	ds_read_b128 v[208:211], v145
	ds_read_b128 v[224:227], v145 offset:1024
	ds_read_b128 v[228:231], v145 offset:2048
	ds_read_b128 v[232:235], v145 offset:3072
	global_load_lds_dwordx4 v[178:179], off
	v_lshl_add_u64 v[178:179], v[212:213], 0, s[78:79]
	s_add_i32 m0, s22, 0x2000
	s_nop 0
	global_load_lds_dwordx4 v[178:179], off
	s_barrier
	s_waitcnt lgkmcnt(0)
	s_setprio 1
	s_waitcnt lgkmcnt(0)
	v_mfma_f32_16x16x32_bf16 v[110:113], v[208:211], v[162:165], v[110:113]
	v_mfma_f32_16x16x32_bf16 v[106:109], v[228:231], v[162:165], v[106:109]
	v_mfma_f32_16x16x32_bf16 v[94:97], v[208:211], v[170:173], v[94:97]
	v_mfma_f32_16x16x32_bf16 v[90:93], v[228:231], v[170:173], v[90:93]
	v_mfma_f32_16x16x32_bf16 v[78:81], v[208:211], v[192:195], v[78:81]
	v_mfma_f32_16x16x32_bf16 v[74:77], v[228:231], v[192:195], v[74:77]
	v_mfma_f32_16x16x32_bf16 v[70:73], v[208:211], v[200:203], v[70:73]
	v_mfma_f32_16x16x32_bf16 v[66:69], v[228:231], v[200:203], v[66:69]
	v_mfma_f32_16x16x32_bf16 v[110:113], v[224:227], v[166:169], v[110:113]
	v_mfma_f32_16x16x32_bf16 v[106:109], v[232:235], v[166:169], v[106:109]
	v_mfma_f32_16x16x32_bf16 v[94:97], v[224:227], v[174:177], v[94:97]
	v_mfma_f32_16x16x32_bf16 v[90:93], v[232:235], v[174:177], v[90:93]
	v_mfma_f32_16x16x32_bf16 v[78:81], v[224:227], v[196:199], v[78:81]
	v_mfma_f32_16x16x32_bf16 v[74:77], v[232:235], v[196:199], v[74:77]
	v_mfma_f32_16x16x32_bf16 v[70:73], v[224:227], v[204:207], v[70:73]
	v_mfma_f32_16x16x32_bf16 v[66:69], v[232:235], v[204:207], v[66:69]
	s_setprio 0
	s_mov_b32 m0, s42
	v_lshl_add_u64 v[178:179], v[236:237], 0, s[78:79]
	s_barrier
	ds_read_b128 v[162:165], v144 offset:49152
	ds_read_b128 v[170:173], v144 offset:51200
	ds_read_b128 v[192:195], v144 offset:53248
	ds_read_b128 v[200:203], v144 offset:55296
	ds_read_b128 v[166:169], v144 offset:50176
	ds_read_b128 v[174:177], v144 offset:52224
	ds_read_b128 v[196:199], v144 offset:54272
	ds_read_b128 v[204:207], v144 offset:56320
	global_load_lds_dwordx4 v[178:179], off
	v_lshl_add_u64 v[178:179], v[238:239], 0, s[78:79]
	s_mov_b32 m0, s43
	s_nop 0
	global_load_lds_dwordx4 v[178:179], off
	s_waitcnt vmcnt(10)
	s_barrier
	s_waitcnt lgkmcnt(4)
	s_setprio 1
	s_waitcnt lgkmcnt(4)
	v_mfma_f32_16x16x32_bf16 v[62:65], v[146:149], v[162:165], v[62:65]
	v_mfma_f32_16x16x32_bf16 v[58:61], v[154:157], v[162:165], v[58:61]
	v_mfma_f32_16x16x32_bf16 v[54:57], v[146:149], v[170:173], v[54:57]
	v_mfma_f32_16x16x32_bf16 v[50:53], v[154:157], v[170:173], v[50:53]
	v_mfma_f32_16x16x32_bf16 v[38:41], v[146:149], v[192:195], v[38:41]
	v_mfma_f32_16x16x32_bf16 v[34:37], v[154:157], v[192:195], v[34:37]
	v_mfma_f32_16x16x32_bf16 v[22:25], v[146:149], v[200:203], v[22:25]
	v_mfma_f32_16x16x32_bf16 v[18:21], v[154:157], v[200:203], v[18:21]
	s_waitcnt lgkmcnt(0)
	v_mfma_f32_16x16x32_bf16 v[62:65], v[150:153], v[166:169], v[62:65]
	v_mfma_f32_16x16x32_bf16 v[58:61], v[158:161], v[166:169], v[58:61]
	v_mfma_f32_16x16x32_bf16 v[54:57], v[150:153], v[174:177], v[54:57]
	v_mfma_f32_16x16x32_bf16 v[50:53], v[158:161], v[174:177], v[50:53]
	v_mfma_f32_16x16x32_bf16 v[38:41], v[150:153], v[196:199], v[38:41]
	v_mfma_f32_16x16x32_bf16 v[34:37], v[158:161], v[196:199], v[34:37]
	v_mfma_f32_16x16x32_bf16 v[22:25], v[150:153], v[204:207], v[22:25]
	v_mfma_f32_16x16x32_bf16 v[18:21], v[158:161], v[204:207], v[18:21]
	s_setprio 0
	s_barrier
	s_add_u32 s22, s84, 0x20080
	s_addc_u32 s23, s85, 0
	s_add_i32 s52, s53, s26
	v_lshl_add_u64 v[146:147], s[22:23], 0, v[134:135]
	s_mov_b32 m0, s52
	s_nop 0
	global_load_lds_dwordx4 v[146:147], off
	v_lshl_add_u64 v[146:147], s[22:23], 0, v[130:131]
	s_add_i32 m0, s52, 0x2000
	s_nop 0
	global_load_lds_dwordx4 v[146:147], off
	v_add_u32_e32 v145, 0x10000, v142
	ds_read_b128 v[146:149], v145
	ds_read_b128 v[150:153], v145 offset:1024
	ds_read_b128 v[154:157], v145 offset:2048
	ds_read_b128 v[158:161], v145 offset:3072
	s_waitcnt vmcnt(6)
	s_barrier
	s_setprio 1
	v_mfma_f32_16x16x32_bf16 v[46:49], v[208:211], v[162:165], v[46:49]
	v_mfma_f32_16x16x32_bf16 v[42:45], v[228:231], v[162:165], v[42:45]
	v_mfma_f32_16x16x32_bf16 v[30:33], v[208:211], v[170:173], v[30:33]
	v_mfma_f32_16x16x32_bf16 v[26:29], v[228:231], v[170:173], v[26:29]
	v_mfma_f32_16x16x32_bf16 v[14:17], v[208:211], v[192:195], v[14:17]
	v_mfma_f32_16x16x32_bf16 v[10:13], v[228:231], v[192:195], v[10:13]
	v_mfma_f32_16x16x32_bf16 v[6:9], v[208:211], v[200:203], v[6:9]
	v_mfma_f32_16x16x32_bf16 v[2:5], v[228:231], v[200:203], v[2:5]
	v_mfma_f32_16x16x32_bf16 v[46:49], v[224:227], v[166:169], v[46:49]
	v_mfma_f32_16x16x32_bf16 v[42:45], v[232:235], v[166:169], v[42:45]
	v_mfma_f32_16x16x32_bf16 v[30:33], v[224:227], v[174:177], v[30:33]
	v_mfma_f32_16x16x32_bf16 v[26:29], v[232:235], v[174:177], v[26:29]
	v_mfma_f32_16x16x32_bf16 v[14:17], v[224:227], v[196:199], v[14:17]
	v_mfma_f32_16x16x32_bf16 v[10:13], v[232:235], v[196:199], v[10:13]
	v_mfma_f32_16x16x32_bf16 v[6:9], v[224:227], v[204:207], v[6:9]
	v_mfma_f32_16x16x32_bf16 v[2:5], v[232:235], v[204:207], v[2:5]
	s_setprio 0
	s_add_i32 s51, s51, 2
	s_add_u32 s20, s20, 0x100
	s_addc_u32 s21, s21, 0
	s_add_u32 s49, s49, 0x100
	s_addc_u32 s50, s50, 0
	s_cmp_gt_u32 s51, 5
	s_barrier
	s_cbranch_scc0 .LBB0_357
	s_waitcnt lgkmcnt(0)
	v_lshl_add_u32 v146, s46, 8, v1
	v_lshl_or_b32 v148, s45, 8, v143
	v_ashrrev_i32_e32 v147, 31, v146
	v_readlane_b32 s48, v254, 40
	v_ashrrev_i32_e32 v149, 31, v148
	v_lshlrev_b64 v[150:151], 12, v[146:147]
	v_readlane_b32 s60, v254, 52
	v_readlane_b32 s61, v254, 53
	v_lshlrev_b64 v[148:149], 1, v[148:149]
	s_mov_b32 s19, 0x80000
	v_lshl_add_u64 v[150:151], s[60:61], 0, v[150:151]
	v_lshl_add_u64 v[150:151], v[150:151], 0, v[148:149]
	s_mov_b64 s[20:21], 0x80000
	v_cvt_pk_bf16_f32 v62, v62, v63
	v_cvt_pk_bf16_f32 v63, v64, v65
	v_cvt_pk_bf16_f32 v64, v58, v59
	v_add_co_u32_e32 v58, vcc, s19, v150
	v_cvt_pk_bf16_f32 v70, v70, v71
	v_cvt_pk_bf16_f32 v71, v72, v73
	v_cvt_pk_bf16_f32 v72, v66, v67
	v_lshl_add_u64 v[66:67], v[150:151], 0, s[20:21]
	v_addc_co_u32_e32 v59, vcc, 0, v151, vcc
	v_cvt_pk_bf16_f32 v46, v46, v47
	v_cvt_pk_bf16_f32 v47, v48, v49
	v_cvt_pk_bf16_f32 v48, v42, v43
	v_cvt_pk_bf16_f32 v49, v44, v45
	s_mov_b32 s19, 0x90000
	v_cvt_pk_bf16_f32 v110, v110, v111
	v_cvt_pk_bf16_f32 v111, v112, v113
	v_cvt_pk_bf16_f32 v112, v106, v107
	v_or_b32_e32 v106, 16, v146
	global_store_dwordx4 v[66:67], v[46:49], off offset:256
	s_mov_b64 s[20:21], 0x90000
	v_ashrrev_i32_e32 v107, 31, v106
	v_add_co_u32_e32 v48, vcc, s19, v150
	v_cvt_pk_bf16_f32 v94, v94, v95
	v_cvt_pk_bf16_f32 v95, v96, v97
	v_cvt_pk_bf16_f32 v96, v90, v91
	v_or_b32_e32 v90, 32, v146
	v_lshl_add_u64 v[46:47], v[150:151], 0, s[20:21]
	v_addc_co_u32_e32 v49, vcc, 0, v151, vcc
	v_cvt_pk_bf16_f32 v30, v30, v31
	v_cvt_pk_bf16_f32 v31, v32, v33
	v_cvt_pk_bf16_f32 v32, v26, v27
	v_cvt_pk_bf16_f32 v33, v28, v29
	s_mov_b32 s19, 0xa0000
	v_lshlrev_b64 v[106:107], 12, v[106:107]
	v_ashrrev_i32_e32 v91, 31, v90
	v_cvt_pk_bf16_f32 v78, v78, v79
	v_cvt_pk_bf16_f32 v79, v80, v81
	v_cvt_pk_bf16_f32 v80, v74, v75
	v_or_b32_e32 v74, 48, v146
	global_store_dwordx4 v[46:47], v[30:33], off offset:256
	s_mov_b64 s[20:21], 0xa0000
	v_cvt_pk_bf16_f32 v113, v108, v109
	v_add_co_u32_e32 v32, vcc, s19, v150
	v_lshl_add_u64 v[106:107], s[60:61], 0, v[106:107]
	v_lshlrev_b64 v[90:91], 12, v[90:91]
	v_ashrrev_i32_e32 v75, 31, v74
	v_lshl_add_u64 v[30:31], v[150:151], 0, s[20:21]
	v_addc_co_u32_e32 v33, vcc, 0, v151, vcc
	v_cvt_pk_bf16_f32 v14, v14, v15
	v_cvt_pk_bf16_f32 v15, v16, v17
	v_cvt_pk_bf16_f32 v16, v10, v11
	v_cvt_pk_bf16_f32 v17, v12, v13
	s_mov_b32 s19, 0xb0000
	global_store_dwordx4 v[150:151], v[110:113], off offset:256
	v_cvt_pk_bf16_f32 v97, v92, v93
	v_lshl_add_u64 v[90:91], s[60:61], 0, v[90:91]
	v_lshl_add_u64 v[110:111], v[106:107], 0, v[148:149]
	v_lshlrev_b64 v[74:75], 12, v[74:75]
	global_store_dwordx4 v[30:31], v[14:17], off offset:256
	global_store_dwordx4 v[110:111], v[94:97], off offset:256
	v_cvt_pk_bf16_f32 v81, v76, v77
	v_add_co_u32_e32 v16, vcc, s19, v150
	v_lshl_add_u64 v[94:95], v[90:91], 0, v[148:149]
	v_lshl_add_u64 v[74:75], s[60:61], 0, v[74:75]
	s_mov_b64 s[20:21], 0xb0000
	v_addc_co_u32_e32 v17, vcc, 0, v151, vcc
	v_cvt_pk_bf16_f32 v126, v126, v127
	v_cvt_pk_bf16_f32 v127, v128, v129
	v_cvt_pk_bf16_f32 v128, v122, v123
	v_cvt_pk_bf16_f32 v129, v124, v125
	v_cvt_pk_bf16_f32 v106, v118, v119
	v_cvt_pk_bf16_f32 v107, v120, v121
	v_cvt_pk_bf16_f32 v108, v114, v115
	v_cvt_pk_bf16_f32 v109, v116, v117
	v_cvt_pk_bf16_f32 v90, v102, v103
	v_cvt_pk_bf16_f32 v91, v104, v105
	v_cvt_pk_bf16_f32 v92, v98, v99
	v_cvt_pk_bf16_f32 v93, v100, v101
	global_store_dwordx4 v[94:95], v[78:81], off offset:256
	v_cvt_pk_bf16_f32 v76, v82, v83
	v_cvt_pk_bf16_f32 v77, v84, v85
	v_lshl_add_u64 v[78:79], v[74:75], 0, v[148:149]
	v_cvt_pk_bf16_f32 v74, v86, v87
	v_cvt_pk_bf16_f32 v75, v88, v89
	v_cvt_pk_bf16_f32 v73, v68, v69
	v_cvt_pk_bf16_f32 v65, v60, v61
	v_cvt_pk_bf16_f32 v42, v54, v55
	v_cvt_pk_bf16_f32 v43, v56, v57
	v_cvt_pk_bf16_f32 v44, v50, v51
	v_cvt_pk_bf16_f32 v45, v52, v53
	v_cvt_pk_bf16_f32 v26, v38, v39
	v_cvt_pk_bf16_f32 v27, v40, v41
	v_cvt_pk_bf16_f32 v28, v34, v35
	v_cvt_pk_bf16_f32 v29, v36, v37
	v_lshl_add_u64 v[14:15], v[150:151], 0, s[20:21]
	v_cvt_pk_bf16_f32 v10, v22, v23
	v_cvt_pk_bf16_f32 v11, v24, v25
	v_cvt_pk_bf16_f32 v12, v18, v19
	v_cvt_pk_bf16_f32 v13, v20, v21
	v_cvt_pk_bf16_f32 v6, v6, v7
	v_cvt_pk_bf16_f32 v7, v8, v9
	v_cvt_pk_bf16_f32 v8, v2, v3
	v_cvt_pk_bf16_f32 v9, v4, v5
	s_and_b64 vcc, exec, s[38:39]
	s_mov_b32 s45, s18
	s_mov_b32 s46, s30
	s_mov_b64 s[22:23], s[82:83]
	s_mov_b64 s[20:21], s[80:81]
	s_mov_b32 s64, 0x800000
	s_movk_i32 s65, 0x1fff
	v_readlane_b32 s49, v254, 41
	v_readlane_b32 s50, v254, 42
	v_readlane_b32 s51, v254, 43
	v_readlane_b32 s52, v254, 44
	v_readlane_b32 s53, v254, 45
	v_readlane_b32 s54, v254, 46
	v_readlane_b32 s55, v254, 47
	v_readlane_b32 s56, v254, 48
	v_readlane_b32 s57, v254, 49
	v_readlane_b32 s58, v254, 50
	v_readlane_b32 s59, v254, 51
	v_readlane_b32 s62, v254, 54
	v_readlane_b32 s63, v254, 55
	global_store_dwordx4 v[150:151], v[126:129], off
	global_store_dwordx4 v[110:111], v[106:109], off
	global_store_dwordx4 v[94:95], v[90:93], off
	global_store_dwordx4 v[78:79], v[74:77], off
	global_store_dwordx4 v[78:79], v[70:73], off offset:256
	global_store_dwordx4 v[58:59], v[62:65], off
	global_store_dwordx4 v[48:49], v[42:45], off
	global_store_dwordx4 v[32:33], v[26:29], off
	global_store_dwordx4 v[16:17], v[10:13], off
	global_store_dwordx4 v[14:15], v[6:9], off offset:256
	s_cbranch_vccz .LBB0_350
	s_waitcnt vmcnt(0)
	v_readlane_b32 s44, v255, 30
	s_mov_b32 s66, s90
	s_cmpk_gt_u32 s25, 0xff
	v_readlane_b32 s45, v255, 31
	v_readlane_b32 s42, v255, 32
	s_cbranch_scc1 .LBB0_361
	s_barrier

.LBB0_373:
	s_add_u32 s22, s20, 0xfffe0080
	s_addc_u32 s23, s21, -1
	s_add_i32 s52, 0, 0x10000
	s_cmp_eq_u32 s51, 4
	s_cselect_b32 s23, s31, s23
	s_cselect_b32 s22, s47, s22
	s_cselect_b32 s83, s19, s50
	s_cselect_b32 s82, s48, s49
	v_lshl_add_u64 v[178:179], s[20:21], 0, v[138:139]
	s_add_i32 m0, s27, 0xc000
	ds_read_b128 v[162:165], v144
	ds_read_b128 v[170:173], v144 offset:2048
	ds_read_b128 v[192:195], v144 offset:4096
	ds_read_b128 v[200:203], v144 offset:6144
	ds_read_b128 v[166:169], v144 offset:1024
	ds_read_b128 v[174:177], v144 offset:3072
	ds_read_b128 v[196:199], v144 offset:5120
	ds_read_b128 v[204:207], v144 offset:7168
	global_load_lds_dwordx4 v[178:179], off
	v_lshl_add_u64 v[178:179], s[20:21], 0, v[140:141]
	s_add_i32 m0, s27, 0xe000
	s_nop 0
	global_load_lds_dwordx4 v[178:179], off
	s_waitcnt lgkmcnt(8)
	s_barrier
	s_waitcnt lgkmcnt(4)
	s_setprio 1
	s_waitcnt lgkmcnt(4)
	v_mfma_f32_16x16x32_bf16 v[126:129], v[146:149], v[162:165], v[126:129]
	v_mfma_f32_16x16x32_bf16 v[122:125], v[154:157], v[162:165], v[122:125]
	v_mfma_f32_16x16x32_bf16 v[118:121], v[146:149], v[170:173], v[118:121]
	v_mfma_f32_16x16x32_bf16 v[114:117], v[154:157], v[170:173], v[114:117]
	v_mfma_f32_16x16x32_bf16 v[102:105], v[146:149], v[192:195], v[102:105]
	v_mfma_f32_16x16x32_bf16 v[98:101], v[154:157], v[192:195], v[98:101]
	v_mfma_f32_16x16x32_bf16 v[86:89], v[146:149], v[200:203], v[86:89]
	v_mfma_f32_16x16x32_bf16 v[82:85], v[154:157], v[200:203], v[82:85]
	s_waitcnt lgkmcnt(0)
	v_mfma_f32_16x16x32_bf16 v[126:129], v[150:153], v[166:169], v[126:129]
	v_mfma_f32_16x16x32_bf16 v[122:125], v[158:161], v[166:169], v[122:125]
	v_mfma_f32_16x16x32_bf16 v[118:121], v[150:153], v[174:177], v[118:121]
	v_mfma_f32_16x16x32_bf16 v[114:117], v[158:161], v[174:177], v[114:117]
	v_mfma_f32_16x16x32_bf16 v[102:105], v[150:153], v[196:199], v[102:105]
	v_mfma_f32_16x16x32_bf16 v[98:101], v[158:161], v[196:199], v[98:101]
	v_mfma_f32_16x16x32_bf16 v[86:89], v[150:153], v[204:207], v[86:89]
	v_mfma_f32_16x16x32_bf16 v[82:85], v[158:161], v[204:207], v[82:85]
	s_setprio 0
	s_barrier
	s_add_i32 s54, 0, 0x14000
	s_add_i32 s52, s52, s26
	v_add_u32_e32 v145, s54, v142
	v_lshl_add_u64 v[178:179], s[82:83], 0, v[134:135]
	s_mov_b32 m0, s52
	ds_read_b128 v[208:211], v145
	ds_read_b128 v[224:227], v145 offset:1024
	ds_read_b128 v[228:231], v145 offset:2048
	ds_read_b128 v[232:235], v145 offset:3072
	global_load_lds_dwordx4 v[178:179], off
	v_lshl_add_u64 v[212:213], s[82:83], 0, v[130:131]
	s_add_i32 m0, s52, 0x2000
	s_nop 0
	global_load_lds_dwordx4 v[212:213], off
	s_barrier
	s_waitcnt lgkmcnt(0)
	s_setprio 1
	s_waitcnt lgkmcnt(0)
	v_mfma_f32_16x16x32_bf16 v[110:113], v[208:211], v[162:165], v[110:113]
	v_mfma_f32_16x16x32_bf16 v[106:109], v[228:231], v[162:165], v[106:109]
	v_mfma_f32_16x16x32_bf16 v[94:97], v[208:211], v[170:173], v[94:97]
	v_mfma_f32_16x16x32_bf16 v[90:93], v[228:231], v[170:173], v[90:93]
	v_mfma_f32_16x16x32_bf16 v[78:81], v[208:211], v[192:195], v[78:81]
	v_mfma_f32_16x16x32_bf16 v[74:77], v[228:231], v[192:195], v[74:77]
	v_mfma_f32_16x16x32_bf16 v[70:73], v[208:211], v[200:203], v[70:73]
	v_mfma_f32_16x16x32_bf16 v[66:69], v[228:231], v[200:203], v[66:69]
	v_mfma_f32_16x16x32_bf16 v[110:113], v[224:227], v[166:169], v[110:113]
	v_mfma_f32_16x16x32_bf16 v[106:109], v[232:235], v[166:169], v[106:109]
	v_mfma_f32_16x16x32_bf16 v[94:97], v[224:227], v[174:177], v[94:97]
	v_mfma_f32_16x16x32_bf16 v[90:93], v[232:235], v[174:177], v[90:93]
	v_mfma_f32_16x16x32_bf16 v[78:81], v[224:227], v[196:199], v[78:81]
	v_mfma_f32_16x16x32_bf16 v[74:77], v[232:235], v[196:199], v[74:77]
	v_mfma_f32_16x16x32_bf16 v[70:73], v[224:227], v[204:207], v[70:73]
	v_mfma_f32_16x16x32_bf16 v[66:69], v[232:235], v[204:207], v[66:69]
	s_setprio 0
	s_mov_b32 m0, s27
	v_lshl_add_u64 v[236:237], s[22:23], 0, v[136:137]
	s_barrier
	ds_read_b128 v[162:165], v144 offset:16384
	ds_read_b128 v[170:173], v144 offset:18432
	ds_read_b128 v[192:195], v144 offset:20480
	ds_read_b128 v[200:203], v144 offset:22528
	ds_read_b128 v[166:169], v144 offset:17408
	ds_read_b128 v[174:177], v144 offset:19456
	ds_read_b128 v[196:199], v144 offset:21504
	ds_read_b128 v[204:207], v144 offset:23552
	global_load_lds_dwordx4 v[236:237], off
	v_lshl_add_u64 v[238:239], s[22:23], 0, v[132:133]
	s_mov_b32 m0, s28
	s_nop 0
	global_load_lds_dwordx4 v[238:239], off
	s_waitcnt vmcnt(10)
	s_barrier
	s_waitcnt lgkmcnt(4)
	s_setprio 1
	s_waitcnt lgkmcnt(4)
	v_mfma_f32_16x16x32_bf16 v[62:65], v[146:149], v[162:165], v[62:65]
	v_mfma_f32_16x16x32_bf16 v[58:61], v[154:157], v[162:165], v[58:61]
	v_mfma_f32_16x16x32_bf16 v[54:57], v[146:149], v[170:173], v[54:57]
	v_mfma_f32_16x16x32_bf16 v[50:53], v[154:157], v[170:173], v[50:53]
	v_mfma_f32_16x16x32_bf16 v[38:41], v[146:149], v[192:195], v[38:41]
	v_mfma_f32_16x16x32_bf16 v[34:37], v[154:157], v[192:195], v[34:37]
	v_mfma_f32_16x16x32_bf16 v[22:25], v[146:149], v[200:203], v[22:25]
	v_mfma_f32_16x16x32_bf16 v[18:21], v[154:157], v[200:203], v[18:21]
	s_waitcnt lgkmcnt(0)
	v_mfma_f32_16x16x32_bf16 v[62:65], v[150:153], v[166:169], v[62:65]
	v_mfma_f32_16x16x32_bf16 v[58:61], v[158:161], v[166:169], v[58:61]
	v_mfma_f32_16x16x32_bf16 v[54:57], v[150:153], v[174:177], v[54:57]
	v_mfma_f32_16x16x32_bf16 v[50:53], v[158:161], v[174:177], v[50:53]
	v_mfma_f32_16x16x32_bf16 v[38:41], v[150:153], v[196:199], v[38:41]
	v_mfma_f32_16x16x32_bf16 v[34:37], v[158:161], v[196:199], v[34:37]
	v_mfma_f32_16x16x32_bf16 v[22:25], v[150:153], v[204:207], v[22:25]
	v_mfma_f32_16x16x32_bf16 v[18:21], v[158:161], v[204:207], v[18:21]
	s_setprio 0
	s_barrier
	s_add_u32 s52, s82, 0x20000
	s_addc_u32 s53, s83, 0
	s_add_i32 s54, s54, s26
	v_lshl_add_u64 v[146:147], s[52:53], 0, v[134:135]
	s_mov_b32 m0, s54
	s_nop 0
	global_load_lds_dwordx4 v[146:147], off
	v_lshl_add_u64 v[146:147], s[52:53], 0, v[130:131]
	s_add_i32 m0, s54, 0x2000
	s_nop 0
	global_load_lds_dwordx4 v[146:147], off
	v_add_u32_e32 v145, 0x18000, v142
	ds_read_b128 v[146:149], v145
	ds_read_b128 v[150:153], v145 offset:1024
	ds_read_b128 v[154:157], v145 offset:2048
	ds_read_b128 v[158:161], v145 offset:3072
	s_waitcnt vmcnt(6)
	s_barrier
	s_setprio 1
	v_mfma_f32_16x16x32_bf16 v[46:49], v[208:211], v[162:165], v[46:49]
	v_mfma_f32_16x16x32_bf16 v[42:45], v[228:231], v[162:165], v[42:45]
	v_mfma_f32_16x16x32_bf16 v[30:33], v[208:211], v[170:173], v[30:33]
	v_mfma_f32_16x16x32_bf16 v[26:29], v[228:231], v[170:173], v[26:29]
	v_mfma_f32_16x16x32_bf16 v[14:17], v[208:211], v[192:195], v[14:17]
	v_mfma_f32_16x16x32_bf16 v[10:13], v[228:231], v[192:195], v[10:13]
	v_mfma_f32_16x16x32_bf16 v[6:9], v[208:211], v[200:203], v[6:9]
	v_mfma_f32_16x16x32_bf16 v[2:5], v[228:231], v[200:203], v[2:5]
	v_mfma_f32_16x16x32_bf16 v[46:49], v[224:227], v[166:169], v[46:49]
	v_mfma_f32_16x16x32_bf16 v[42:45], v[232:235], v[166:169], v[42:45]
	v_mfma_f32_16x16x32_bf16 v[30:33], v[224:227], v[174:177], v[30:33]
	v_mfma_f32_16x16x32_bf16 v[26:29], v[232:235], v[174:177], v[26:29]
	v_mfma_f32_16x16x32_bf16 v[14:17], v[224:227], v[196:199], v[14:17]
	v_mfma_f32_16x16x32_bf16 v[10:13], v[232:235], v[196:199], v[10:13]
	v_mfma_f32_16x16x32_bf16 v[6:9], v[224:227], v[204:207], v[6:9]
	v_mfma_f32_16x16x32_bf16 v[2:5], v[232:235], v[204:207], v[2:5]
	s_setprio 0
	s_add_i32 s52, 0, 0x18000
	s_barrier
	s_add_u32 s22, s22, 0x20000
	s_addc_u32 s23, s23, 0
	s_mov_b32 m0, s29
	v_lshl_add_u64 v[208:209], s[22:23], 0, v[136:137]
	ds_read_b128 v[162:165], v144 offset:32768
	ds_read_b128 v[170:173], v144 offset:34816
	ds_read_b128 v[192:195], v144 offset:36864
	ds_read_b128 v[200:203], v144 offset:38912
	ds_read_b128 v[166:169], v144 offset:33792
	ds_read_b128 v[174:177], v144 offset:35840
	ds_read_b128 v[196:199], v144 offset:37888
	ds_read_b128 v[204:207], v144 offset:39936
	global_load_lds_dwordx4 v[208:209], off
	v_lshl_add_u64 v[208:209], s[22:23], 0, v[132:133]
	s_mov_b32 m0, s36
	s_nop 0
	global_load_lds_dwordx4 v[208:209], off
	s_waitcnt lgkmcnt(8)
	s_barrier
	s_waitcnt lgkmcnt(4)
	s_setprio 1
	s_waitcnt lgkmcnt(4)
	v_mfma_f32_16x16x32_bf16 v[126:129], v[146:149], v[162:165], v[126:129]
	v_mfma_f32_16x16x32_bf16 v[122:125], v[154:157], v[162:165], v[122:125]
	v_mfma_f32_16x16x32_bf16 v[118:121], v[146:149], v[170:173], v[118:121]
	v_mfma_f32_16x16x32_bf16 v[114:117], v[154:157], v[170:173], v[114:117]
	v_mfma_f32_16x16x32_bf16 v[102:105], v[146:149], v[192:195], v[102:105]
	v_mfma_f32_16x16x32_bf16 v[98:101], v[154:157], v[192:195], v[98:101]
	v_mfma_f32_16x16x32_bf16 v[86:89], v[146:149], v[200:203], v[86:89]
	v_mfma_f32_16x16x32_bf16 v[82:85], v[154:157], v[200:203], v[82:85]
	s_waitcnt lgkmcnt(0)
	v_mfma_f32_16x16x32_bf16 v[126:129], v[150:153], v[166:169], v[126:129]
	v_mfma_f32_16x16x32_bf16 v[122:125], v[158:161], v[166:169], v[122:125]
	v_mfma_f32_16x16x32_bf16 v[118:121], v[150:153], v[174:177], v[118:121]
	v_mfma_f32_16x16x32_bf16 v[114:117], v[158:161], v[174:177], v[114:117]
	v_mfma_f32_16x16x32_bf16 v[102:105], v[150:153], v[196:199], v[102:105]
	v_mfma_f32_16x16x32_bf16 v[98:101], v[158:161], v[196:199], v[98:101]
	v_mfma_f32_16x16x32_bf16 v[86:89], v[150:153], v[204:207], v[86:89]
	v_mfma_f32_16x16x32_bf16 v[82:85], v[158:161], v[204:207], v[82:85]
	s_setprio 0
	s_barrier
	s_add_i32 s53, 0, 0x1c000
	s_add_i32 s22, s52, s26
	v_add_u32_e32 v145, s53, v142
	v_lshl_add_u64 v[178:179], v[178:179], 0, s[78:79]
	s_mov_b32 m0, s22
	ds_read_b128 v[208:211], v145
	ds_read_b128 v[224:227], v145 offset:1024
	ds_read_b128 v[228:231], v145 offset:2048
	ds_read_b128 v[232:235], v145 offset:3072
	global_load_lds_dwordx4 v[178:179], off
	v_lshl_add_u64 v[178:179], v[212:213], 0, s[78:79]
	s_add_i32 m0, s22, 0x2000
	s_nop 0
	global_load_lds_dwordx4 v[178:179], off
	s_barrier
	s_waitcnt lgkmcnt(0)
	s_setprio 1
	s_waitcnt lgkmcnt(0)
	v_mfma_f32_16x16x32_bf16 v[110:113], v[208:211], v[162:165], v[110:113]
	v_mfma_f32_16x16x32_bf16 v[106:109], v[228:231], v[162:165], v[106:109]
	v_mfma_f32_16x16x32_bf16 v[94:97], v[208:211], v[170:173], v[94:97]
	v_mfma_f32_16x16x32_bf16 v[90:93], v[228:231], v[170:173], v[90:93]
	v_mfma_f32_16x16x32_bf16 v[78:81], v[208:211], v[192:195], v[78:81]
	v_mfma_f32_16x16x32_bf16 v[74:77], v[228:231], v[192:195], v[74:77]
	v_mfma_f32_16x16x32_bf16 v[70:73], v[208:211], v[200:203], v[70:73]
	v_mfma_f32_16x16x32_bf16 v[66:69], v[228:231], v[200:203], v[66:69]
	v_mfma_f32_16x16x32_bf16 v[110:113], v[224:227], v[166:169], v[110:113]
	v_mfma_f32_16x16x32_bf16 v[106:109], v[232:235], v[166:169], v[106:109]
	v_mfma_f32_16x16x32_bf16 v[94:97], v[224:227], v[174:177], v[94:97]
	v_mfma_f32_16x16x32_bf16 v[90:93], v[232:235], v[174:177], v[90:93]
	v_mfma_f32_16x16x32_bf16 v[78:81], v[224:227], v[196:199], v[78:81]
	v_mfma_f32_16x16x32_bf16 v[74:77], v[232:235], v[196:199], v[74:77]
	v_mfma_f32_16x16x32_bf16 v[70:73], v[224:227], v[204:207], v[70:73]
	v_mfma_f32_16x16x32_bf16 v[66:69], v[232:235], v[204:207], v[66:69]
	s_setprio 0
	s_mov_b32 m0, s42
	v_lshl_add_u64 v[178:179], v[236:237], 0, s[78:79]
	s_barrier
	ds_read_b128 v[162:165], v144 offset:49152
	ds_read_b128 v[170:173], v144 offset:51200
	ds_read_b128 v[192:195], v144 offset:53248
	ds_read_b128 v[200:203], v144 offset:55296
	ds_read_b128 v[166:169], v144 offset:50176
	ds_read_b128 v[174:177], v144 offset:52224
	ds_read_b128 v[196:199], v144 offset:54272
	ds_read_b128 v[204:207], v144 offset:56320
	global_load_lds_dwordx4 v[178:179], off
	v_lshl_add_u64 v[178:179], v[238:239], 0, s[78:79]
	s_mov_b32 m0, s43
	s_nop 0
	global_load_lds_dwordx4 v[178:179], off
	s_waitcnt vmcnt(10)
	s_barrier
	s_waitcnt lgkmcnt(4)
	s_setprio 1
	s_waitcnt lgkmcnt(4)
	v_mfma_f32_16x16x32_bf16 v[62:65], v[146:149], v[162:165], v[62:65]
	v_mfma_f32_16x16x32_bf16 v[58:61], v[154:157], v[162:165], v[58:61]
	v_mfma_f32_16x16x32_bf16 v[54:57], v[146:149], v[170:173], v[54:57]
	v_mfma_f32_16x16x32_bf16 v[50:53], v[154:157], v[170:173], v[50:53]
	v_mfma_f32_16x16x32_bf16 v[38:41], v[146:149], v[192:195], v[38:41]
	v_mfma_f32_16x16x32_bf16 v[34:37], v[154:157], v[192:195], v[34:37]
	v_mfma_f32_16x16x32_bf16 v[22:25], v[146:149], v[200:203], v[22:25]
	v_mfma_f32_16x16x32_bf16 v[18:21], v[154:157], v[200:203], v[18:21]
	s_waitcnt lgkmcnt(0)
	v_mfma_f32_16x16x32_bf16 v[62:65], v[150:153], v[166:169], v[62:65]
	v_mfma_f32_16x16x32_bf16 v[58:61], v[158:161], v[166:169], v[58:61]
	v_mfma_f32_16x16x32_bf16 v[54:57], v[150:153], v[174:177], v[54:57]
	v_mfma_f32_16x16x32_bf16 v[50:53], v[158:161], v[174:177], v[50:53]
	v_mfma_f32_16x16x32_bf16 v[38:41], v[150:153], v[196:199], v[38:41]
	v_mfma_f32_16x16x32_bf16 v[34:37], v[158:161], v[196:199], v[34:37]
	v_mfma_f32_16x16x32_bf16 v[22:25], v[150:153], v[204:207], v[22:25]
	v_mfma_f32_16x16x32_bf16 v[18:21], v[158:161], v[204:207], v[18:21]
	s_setprio 0
	s_barrier
	s_add_u32 s22, s82, 0x20080
	s_addc_u32 s23, s83, 0
	s_add_i32 s52, s53, s26
	v_lshl_add_u64 v[146:147], s[22:23], 0, v[134:135]
	s_mov_b32 m0, s52
	s_nop 0
	global_load_lds_dwordx4 v[146:147], off
	v_lshl_add_u64 v[146:147], s[22:23], 0, v[130:131]
	s_add_i32 m0, s52, 0x2000
	s_nop 0
	global_load_lds_dwordx4 v[146:147], off
	v_add_u32_e32 v145, 0x10000, v142
	ds_read_b128 v[146:149], v145
	ds_read_b128 v[150:153], v145 offset:1024
	ds_read_b128 v[154:157], v145 offset:2048
	ds_read_b128 v[158:161], v145 offset:3072
	s_waitcnt vmcnt(6)
	s_barrier
	s_setprio 1
	v_mfma_f32_16x16x32_bf16 v[46:49], v[208:211], v[162:165], v[46:49]
	v_mfma_f32_16x16x32_bf16 v[42:45], v[228:231], v[162:165], v[42:45]
	v_mfma_f32_16x16x32_bf16 v[30:33], v[208:211], v[170:173], v[30:33]
	v_mfma_f32_16x16x32_bf16 v[26:29], v[228:231], v[170:173], v[26:29]
	v_mfma_f32_16x16x32_bf16 v[14:17], v[208:211], v[192:195], v[14:17]
	v_mfma_f32_16x16x32_bf16 v[10:13], v[228:231], v[192:195], v[10:13]
	v_mfma_f32_16x16x32_bf16 v[6:9], v[208:211], v[200:203], v[6:9]
	v_mfma_f32_16x16x32_bf16 v[2:5], v[228:231], v[200:203], v[2:5]
	v_mfma_f32_16x16x32_bf16 v[46:49], v[224:227], v[166:169], v[46:49]
	v_mfma_f32_16x16x32_bf16 v[42:45], v[232:235], v[166:169], v[42:45]
	v_mfma_f32_16x16x32_bf16 v[30:33], v[224:227], v[174:177], v[30:33]
	v_mfma_f32_16x16x32_bf16 v[26:29], v[232:235], v[174:177], v[26:29]
	v_mfma_f32_16x16x32_bf16 v[14:17], v[224:227], v[196:199], v[14:17]
	v_mfma_f32_16x16x32_bf16 v[10:13], v[232:235], v[196:199], v[10:13]
	v_mfma_f32_16x16x32_bf16 v[6:9], v[224:227], v[204:207], v[6:9]
	v_mfma_f32_16x16x32_bf16 v[2:5], v[232:235], v[204:207], v[2:5]
	s_setprio 0
	s_add_i32 s51, s51, 2
	s_add_u32 s20, s20, 0x100
	s_addc_u32 s21, s21, 0
	s_add_u32 s49, s49, 0x100
	s_addc_u32 s50, s50, 0
	s_cmp_gt_u32 s51, 5
	s_barrier
	s_cbranch_scc0 .LBB0_373
	s_waitcnt lgkmcnt(0)
	v_lshl_add_u32 v146, s46, 8, v1
	v_lshl_or_b32 v148, s45, 8, v143
	v_ashrrev_i32_e32 v147, 31, v146
	v_readlane_b32 s48, v254, 40
	v_ashrrev_i32_e32 v149, 31, v148
	v_lshlrev_b64 v[150:151], 14, v[146:147]
	v_readlane_b32 s62, v254, 54
	v_readlane_b32 s63, v254, 55
	v_lshlrev_b64 v[148:149], 1, v[148:149]
	s_mov_b32 s19, 0x200000
	v_lshl_add_u64 v[150:151], s[62:63], 0, v[150:151]
	v_lshl_add_u64 v[150:151], v[150:151], 0, v[148:149]
	s_mov_b64 s[20:21], 0x200000
	v_cvt_pk_bf16_f32 v62, v62, v63
	v_cvt_pk_bf16_f32 v63, v64, v65
	v_cvt_pk_bf16_f32 v64, v58, v59
	v_add_co_u32_e32 v58, vcc, s19, v150
	v_cvt_pk_bf16_f32 v70, v70, v71
	v_cvt_pk_bf16_f32 v71, v72, v73
	v_cvt_pk_bf16_f32 v72, v66, v67
	v_lshl_add_u64 v[66:67], v[150:151], 0, s[20:21]
	v_addc_co_u32_e32 v59, vcc, 0, v151, vcc
	v_cvt_pk_bf16_f32 v46, v46, v47
	v_cvt_pk_bf16_f32 v47, v48, v49
	v_cvt_pk_bf16_f32 v48, v42, v43
	v_cvt_pk_bf16_f32 v49, v44, v45
	s_mov_b32 s19, 0x240000
	v_cvt_pk_bf16_f32 v110, v110, v111
	v_cvt_pk_bf16_f32 v111, v112, v113
	v_cvt_pk_bf16_f32 v112, v106, v107
	v_or_b32_e32 v106, 16, v146
	global_store_dwordx4 v[66:67], v[46:49], off offset:256
	s_mov_b64 s[20:21], 0x240000
	v_ashrrev_i32_e32 v107, 31, v106
	v_add_co_u32_e32 v48, vcc, s19, v150
	v_cvt_pk_bf16_f32 v94, v94, v95
	v_cvt_pk_bf16_f32 v95, v96, v97
	v_cvt_pk_bf16_f32 v96, v90, v91
	v_or_b32_e32 v90, 32, v146
	v_lshl_add_u64 v[46:47], v[150:151], 0, s[20:21]
	v_addc_co_u32_e32 v49, vcc, 0, v151, vcc
	v_cvt_pk_bf16_f32 v30, v30, v31
	v_cvt_pk_bf16_f32 v31, v32, v33
	v_cvt_pk_bf16_f32 v32, v26, v27
	v_cvt_pk_bf16_f32 v33, v28, v29
	s_mov_b32 s19, 0x280000
	v_lshlrev_b64 v[106:107], 14, v[106:107]
	v_ashrrev_i32_e32 v91, 31, v90
	v_cvt_pk_bf16_f32 v78, v78, v79
	v_cvt_pk_bf16_f32 v79, v80, v81
	v_cvt_pk_bf16_f32 v80, v74, v75
	v_or_b32_e32 v74, 48, v146
	global_store_dwordx4 v[46:47], v[30:33], off offset:256
	s_mov_b64 s[20:21], 0x280000
	v_cvt_pk_bf16_f32 v113, v108, v109
	v_add_co_u32_e32 v32, vcc, s19, v150
	v_lshl_add_u64 v[106:107], s[62:63], 0, v[106:107]
	v_lshlrev_b64 v[90:91], 14, v[90:91]
	v_ashrrev_i32_e32 v75, 31, v74
	v_lshl_add_u64 v[30:31], v[150:151], 0, s[20:21]
	v_addc_co_u32_e32 v33, vcc, 0, v151, vcc
	v_cvt_pk_bf16_f32 v14, v14, v15
	v_cvt_pk_bf16_f32 v15, v16, v17
	v_cvt_pk_bf16_f32 v16, v10, v11
	v_cvt_pk_bf16_f32 v17, v12, v13
	s_mov_b32 s19, 0x2c0000
	global_store_dwordx4 v[150:151], v[110:113], off offset:256
	v_cvt_pk_bf16_f32 v97, v92, v93
	v_lshl_add_u64 v[90:91], s[62:63], 0, v[90:91]
	v_lshl_add_u64 v[110:111], v[106:107], 0, v[148:149]
	v_lshlrev_b64 v[74:75], 14, v[74:75]
	global_store_dwordx4 v[30:31], v[14:17], off offset:256
	global_store_dwordx4 v[110:111], v[94:97], off offset:256
	v_cvt_pk_bf16_f32 v81, v76, v77
	v_add_co_u32_e32 v16, vcc, s19, v150
	v_lshl_add_u64 v[94:95], v[90:91], 0, v[148:149]
	v_lshl_add_u64 v[74:75], s[62:63], 0, v[74:75]
	s_mov_b64 s[20:21], 0x2c0000
	v_addc_co_u32_e32 v17, vcc, 0, v151, vcc
	v_cvt_pk_bf16_f32 v126, v126, v127
	v_cvt_pk_bf16_f32 v127, v128, v129
	v_cvt_pk_bf16_f32 v128, v122, v123
	v_cvt_pk_bf16_f32 v129, v124, v125
	v_cvt_pk_bf16_f32 v106, v118, v119
	v_cvt_pk_bf16_f32 v107, v120, v121
	v_cvt_pk_bf16_f32 v108, v114, v115
	v_cvt_pk_bf16_f32 v109, v116, v117
	v_cvt_pk_bf16_f32 v90, v102, v103
	v_cvt_pk_bf16_f32 v91, v104, v105
	v_cvt_pk_bf16_f32 v92, v98, v99
	v_cvt_pk_bf16_f32 v93, v100, v101
	global_store_dwordx4 v[94:95], v[78:81], off offset:256
	v_cvt_pk_bf16_f32 v76, v82, v83
	v_cvt_pk_bf16_f32 v77, v84, v85
	v_lshl_add_u64 v[78:79], v[74:75], 0, v[148:149]
	v_cvt_pk_bf16_f32 v74, v86, v87
	v_cvt_pk_bf16_f32 v75, v88, v89
	v_cvt_pk_bf16_f32 v73, v68, v69
	v_cvt_pk_bf16_f32 v65, v60, v61
	v_cvt_pk_bf16_f32 v42, v54, v55
	v_cvt_pk_bf16_f32 v43, v56, v57
	v_cvt_pk_bf16_f32 v44, v50, v51
	v_cvt_pk_bf16_f32 v45, v52, v53
	v_cvt_pk_bf16_f32 v26, v38, v39
	v_cvt_pk_bf16_f32 v27, v40, v41
	v_cvt_pk_bf16_f32 v28, v34, v35
	v_cvt_pk_bf16_f32 v29, v36, v37
	v_lshl_add_u64 v[14:15], v[150:151], 0, s[20:21]
	v_cvt_pk_bf16_f32 v10, v22, v23
	v_cvt_pk_bf16_f32 v11, v24, v25
	v_cvt_pk_bf16_f32 v12, v18, v19
	v_cvt_pk_bf16_f32 v13, v20, v21
	v_cvt_pk_bf16_f32 v6, v6, v7
	v_cvt_pk_bf16_f32 v7, v8, v9
	v_cvt_pk_bf16_f32 v8, v2, v3
	v_cvt_pk_bf16_f32 v9, v4, v5
	s_and_b64 vcc, exec, s[0:1]
	s_mov_b32 s45, s18
	s_mov_b32 s46, s30
	s_mov_b64 s[22:23], s[80:81]
	s_mov_b64 s[20:21], s[38:39]
	s_mov_b32 s64, 0x800000
	s_movk_i32 s65, 0x1fff
	v_readlane_b32 s49, v254, 41
	v_readlane_b32 s50, v254, 42
	v_readlane_b32 s51, v254, 43
	v_readlane_b32 s52, v254, 44
	v_readlane_b32 s53, v254, 45
	v_readlane_b32 s54, v254, 46
	v_readlane_b32 s55, v254, 47
	v_readlane_b32 s56, v254, 48
	v_readlane_b32 s57, v254, 49
	v_readlane_b32 s58, v254, 50
	v_readlane_b32 s59, v254, 51
	v_readlane_b32 s60, v254, 52
	v_readlane_b32 s61, v254, 53
	global_store_dwordx4 v[150:151], v[126:129], off
	global_store_dwordx4 v[110:111], v[106:109], off
	global_store_dwordx4 v[94:95], v[90:93], off
	global_store_dwordx4 v[78:79], v[74:77], off
	global_store_dwordx4 v[78:79], v[70:73], off offset:256
	global_store_dwordx4 v[58:59], v[62:65], off
	global_store_dwordx4 v[48:49], v[42:45], off
	global_store_dwordx4 v[32:33], v[26:29], off
	global_store_dwordx4 v[16:17], v[10:13], off
	global_store_dwordx4 v[14:15], v[6:9], off offset:256
	s_cbranch_vccz .LBB0_366
	s_waitcnt vmcnt(0)
	v_readlane_b32 s44, v255, 30
	s_mov_b32 s66, s90
	s_cmpk_gt_u32 s25, 0xff
	v_readlane_b32 s45, v255, 31
	v_readlane_b32 s42, v255, 32
	s_cbranch_scc1 .LBB0_377
	s_barrier

.LBB0_386:
	s_add_u32 s20, s18, 0xfffe0080
	s_addc_u32 s21, s19, -1
	s_add_i32 s50, 0, 0x10000
	s_cmp_eq_u32 s49, 4
	s_cselect_b32 s23, s44, s21
	s_cselect_b32 s22, s45, s20
	s_cselect_b32 s21, s39, s48
	s_cselect_b32 s20, s46, s47
	v_lshl_add_u64 v[178:179], s[18:19], 0, v[146:147]
	s_add_i32 m0, s90, 0xc000
	ds_read_b128 v[162:165], v156
	ds_read_b128 v[170:173], v156 offset:2048
	ds_read_b128 v[192:195], v156 offset:4096
	ds_read_b128 v[200:203], v156 offset:6144
	ds_read_b128 v[166:169], v156 offset:1024
	ds_read_b128 v[174:177], v156 offset:3072
	ds_read_b128 v[196:199], v156 offset:5120
	ds_read_b128 v[204:207], v156 offset:7168
	global_load_lds_dwordx4 v[178:179], off
	v_lshl_add_u64 v[178:179], s[18:19], 0, v[148:149]
	s_add_i32 m0, s90, 0xe000
	s_nop 0
	global_load_lds_dwordx4 v[178:179], off
	s_waitcnt lgkmcnt(8)
	s_barrier
	s_waitcnt lgkmcnt(4)
	s_setprio 1
	s_waitcnt lgkmcnt(4)
	v_mfma_f32_16x16x32_bf16 v[126:129], v[130:133], v[162:165], v[126:129]
	v_mfma_f32_16x16x32_bf16 v[122:125], v[150:153], v[162:165], v[122:125]
	v_mfma_f32_16x16x32_bf16 v[118:121], v[130:133], v[170:173], v[118:121]
	v_mfma_f32_16x16x32_bf16 v[110:113], v[150:153], v[170:173], v[110:113]
	v_mfma_f32_16x16x32_bf16 v[102:105], v[130:133], v[192:195], v[102:105]
	v_mfma_f32_16x16x32_bf16 v[94:97], v[150:153], v[192:195], v[94:97]
	v_mfma_f32_16x16x32_bf16 v[86:89], v[130:133], v[200:203], v[86:89]
	v_mfma_f32_16x16x32_bf16 v[78:81], v[150:153], v[200:203], v[78:81]
	s_waitcnt lgkmcnt(0)
	v_mfma_f32_16x16x32_bf16 v[126:129], v[134:137], v[166:169], v[126:129]
	v_mfma_f32_16x16x32_bf16 v[122:125], v[158:161], v[166:169], v[122:125]
	v_mfma_f32_16x16x32_bf16 v[118:121], v[134:137], v[174:177], v[118:121]
	v_mfma_f32_16x16x32_bf16 v[110:113], v[158:161], v[174:177], v[110:113]
	v_mfma_f32_16x16x32_bf16 v[102:105], v[134:137], v[196:199], v[102:105]
	v_mfma_f32_16x16x32_bf16 v[94:97], v[158:161], v[196:199], v[94:97]
	v_mfma_f32_16x16x32_bf16 v[86:89], v[134:137], v[204:207], v[86:89]
	v_mfma_f32_16x16x32_bf16 v[78:81], v[158:161], v[204:207], v[78:81]
	s_setprio 0
	s_barrier
	s_add_i32 s52, 0, 0x14000
	s_add_i32 s50, s50, s36
	v_add_u32_e32 v157, s52, v154
	v_lshl_add_u64 v[178:179], s[20:21], 0, v[142:143]
	s_mov_b32 m0, s50
	ds_read_b128 v[208:211], v157
	ds_read_b128 v[224:227], v157 offset:1024
	ds_read_b128 v[228:231], v157 offset:2048
	ds_read_b128 v[232:235], v157 offset:3072
	global_load_lds_dwordx4 v[178:179], off
	v_lshl_add_u64 v[212:213], s[20:21], 0, v[138:139]
	s_add_i32 m0, s50, 0x2000
	s_nop 0
	global_load_lds_dwordx4 v[212:213], off
	s_barrier
	s_waitcnt lgkmcnt(0)
	s_setprio 1
	s_waitcnt lgkmcnt(0)
	v_mfma_f32_16x16x32_bf16 v[114:117], v[208:211], v[162:165], v[114:117]
	v_mfma_f32_16x16x32_bf16 v[106:109], v[228:231], v[162:165], v[106:109]
	v_mfma_f32_16x16x32_bf16 v[98:101], v[208:211], v[170:173], v[98:101]
	v_mfma_f32_16x16x32_bf16 v[90:93], v[228:231], v[170:173], v[90:93]
	v_mfma_f32_16x16x32_bf16 v[82:85], v[208:211], v[192:195], v[82:85]
	v_mfma_f32_16x16x32_bf16 v[74:77], v[228:231], v[192:195], v[74:77]
	v_mfma_f32_16x16x32_bf16 v[70:73], v[208:211], v[200:203], v[70:73]
	v_mfma_f32_16x16x32_bf16 v[66:69], v[228:231], v[200:203], v[66:69]
	v_mfma_f32_16x16x32_bf16 v[114:117], v[224:227], v[166:169], v[114:117]
	v_mfma_f32_16x16x32_bf16 v[106:109], v[232:235], v[166:169], v[106:109]
	v_mfma_f32_16x16x32_bf16 v[98:101], v[224:227], v[174:177], v[98:101]
	v_mfma_f32_16x16x32_bf16 v[90:93], v[232:235], v[174:177], v[90:93]
	v_mfma_f32_16x16x32_bf16 v[82:85], v[224:227], v[196:199], v[82:85]
	v_mfma_f32_16x16x32_bf16 v[74:77], v[232:235], v[196:199], v[74:77]
	v_mfma_f32_16x16x32_bf16 v[70:73], v[224:227], v[204:207], v[70:73]
	v_mfma_f32_16x16x32_bf16 v[66:69], v[232:235], v[204:207], v[66:69]
	s_setprio 0
	s_mov_b32 m0, s90
	v_lshl_add_u64 v[236:237], s[22:23], 0, v[144:145]
	s_barrier
	ds_read_b128 v[162:165], v156 offset:16384
	ds_read_b128 v[170:173], v156 offset:18432
	ds_read_b128 v[192:195], v156 offset:20480
	ds_read_b128 v[200:203], v156 offset:22528
	ds_read_b128 v[166:169], v156 offset:17408
	ds_read_b128 v[174:177], v156 offset:19456
	ds_read_b128 v[196:199], v156 offset:21504
	ds_read_b128 v[204:207], v156 offset:23552
	global_load_lds_dwordx4 v[236:237], off
	v_lshl_add_u64 v[238:239], s[22:23], 0, v[140:141]
	s_mov_b32 m0, s91
	s_nop 0
	global_load_lds_dwordx4 v[238:239], off
	s_waitcnt vmcnt(10)
	s_barrier
	s_waitcnt lgkmcnt(4)
	s_setprio 1
	s_waitcnt lgkmcnt(4)
	v_mfma_f32_16x16x32_bf16 v[62:65], v[130:133], v[162:165], v[62:65]
	v_mfma_f32_16x16x32_bf16 v[58:61], v[150:153], v[162:165], v[58:61]
	v_mfma_f32_16x16x32_bf16 v[54:57], v[130:133], v[170:173], v[54:57]
	v_mfma_f32_16x16x32_bf16 v[46:49], v[150:153], v[170:173], v[46:49]
	v_mfma_f32_16x16x32_bf16 v[38:41], v[130:133], v[192:195], v[38:41]
	v_mfma_f32_16x16x32_bf16 v[30:33], v[150:153], v[192:195], v[30:33]
	v_mfma_f32_16x16x32_bf16 v[22:25], v[130:133], v[200:203], v[22:25]
	v_mfma_f32_16x16x32_bf16 v[14:17], v[150:153], v[200:203], v[14:17]
	s_waitcnt lgkmcnt(0)
	v_mfma_f32_16x16x32_bf16 v[62:65], v[134:137], v[166:169], v[62:65]
	v_mfma_f32_16x16x32_bf16 v[58:61], v[158:161], v[166:169], v[58:61]
	v_mfma_f32_16x16x32_bf16 v[54:57], v[134:137], v[174:177], v[54:57]
	v_mfma_f32_16x16x32_bf16 v[46:49], v[158:161], v[174:177], v[46:49]
	v_mfma_f32_16x16x32_bf16 v[38:41], v[134:137], v[196:199], v[38:41]
	v_mfma_f32_16x16x32_bf16 v[30:33], v[158:161], v[196:199], v[30:33]
	v_mfma_f32_16x16x32_bf16 v[22:25], v[134:137], v[204:207], v[22:25]
	v_mfma_f32_16x16x32_bf16 v[14:17], v[158:161], v[204:207], v[14:17]
	s_setprio 0
	s_barrier
	s_add_u32 s50, s20, 0x20000
	s_addc_u32 s51, s21, 0
	s_add_i32 s52, s52, s36
	v_lshl_add_u64 v[130:131], s[50:51], 0, v[142:143]
	s_mov_b32 m0, s52
	s_nop 0
	global_load_lds_dwordx4 v[130:131], off
	v_lshl_add_u64 v[130:131], s[50:51], 0, v[138:139]
	s_add_i32 m0, s52, 0x2000
	s_nop 0
	global_load_lds_dwordx4 v[130:131], off
	v_add_u32_e32 v157, 0x18000, v154
	ds_read_b128 v[130:133], v157
	ds_read_b128 v[134:137], v157 offset:1024
	ds_read_b128 v[150:153], v157 offset:2048
	ds_read_b128 v[158:161], v157 offset:3072
	s_waitcnt vmcnt(6)
	s_barrier
	s_setprio 1
	v_mfma_f32_16x16x32_bf16 v[50:53], v[208:211], v[162:165], v[50:53]
	v_mfma_f32_16x16x32_bf16 v[42:45], v[228:231], v[162:165], v[42:45]
	v_mfma_f32_16x16x32_bf16 v[34:37], v[208:211], v[170:173], v[34:37]
	v_mfma_f32_16x16x32_bf16 v[26:29], v[228:231], v[170:173], v[26:29]
	v_mfma_f32_16x16x32_bf16 v[18:21], v[208:211], v[192:195], v[18:21]
	v_mfma_f32_16x16x32_bf16 v[10:13], v[228:231], v[192:195], v[10:13]
	v_mfma_f32_16x16x32_bf16 v[6:9], v[208:211], v[200:203], v[6:9]
	v_mfma_f32_16x16x32_bf16 v[2:5], v[228:231], v[200:203], v[2:5]
	v_mfma_f32_16x16x32_bf16 v[50:53], v[224:227], v[166:169], v[50:53]
	v_mfma_f32_16x16x32_bf16 v[42:45], v[232:235], v[166:169], v[42:45]
	v_mfma_f32_16x16x32_bf16 v[34:37], v[224:227], v[174:177], v[34:37]
	v_mfma_f32_16x16x32_bf16 v[26:29], v[232:235], v[174:177], v[26:29]
	v_mfma_f32_16x16x32_bf16 v[18:21], v[224:227], v[196:199], v[18:21]
	v_mfma_f32_16x16x32_bf16 v[10:13], v[232:235], v[196:199], v[10:13]
	v_mfma_f32_16x16x32_bf16 v[6:9], v[224:227], v[204:207], v[6:9]
	v_mfma_f32_16x16x32_bf16 v[2:5], v[232:235], v[204:207], v[2:5]
	s_setprio 0
	s_add_i32 s50, 0, 0x18000
	s_barrier
	s_add_u32 s22, s22, 0x20000
	s_addc_u32 s23, s23, 0
	s_mov_b32 m0, s42
	v_lshl_add_u64 v[208:209], s[22:23], 0, v[144:145]
	ds_read_b128 v[162:165], v156 offset:32768
	ds_read_b128 v[170:173], v156 offset:34816
	ds_read_b128 v[192:195], v156 offset:36864
	ds_read_b128 v[200:203], v156 offset:38912
	ds_read_b128 v[166:169], v156 offset:33792
	ds_read_b128 v[174:177], v156 offset:35840
	ds_read_b128 v[196:199], v156 offset:37888
	ds_read_b128 v[204:207], v156 offset:39936
	global_load_lds_dwordx4 v[208:209], off
	v_lshl_add_u64 v[208:209], s[22:23], 0, v[140:141]
	s_mov_b32 m0, s43
	s_nop 0
	global_load_lds_dwordx4 v[208:209], off
	s_waitcnt lgkmcnt(8)
	s_barrier
	s_waitcnt lgkmcnt(4)
	s_setprio 1
	s_waitcnt lgkmcnt(4)
	v_mfma_f32_16x16x32_bf16 v[126:129], v[130:133], v[162:165], v[126:129]
	v_mfma_f32_16x16x32_bf16 v[122:125], v[150:153], v[162:165], v[122:125]
	v_mfma_f32_16x16x32_bf16 v[118:121], v[130:133], v[170:173], v[118:121]
	v_mfma_f32_16x16x32_bf16 v[110:113], v[150:153], v[170:173], v[110:113]
	v_mfma_f32_16x16x32_bf16 v[102:105], v[130:133], v[192:195], v[102:105]
	v_mfma_f32_16x16x32_bf16 v[94:97], v[150:153], v[192:195], v[94:97]
	v_mfma_f32_16x16x32_bf16 v[86:89], v[130:133], v[200:203], v[86:89]
	v_mfma_f32_16x16x32_bf16 v[78:81], v[150:153], v[200:203], v[78:81]
	s_waitcnt lgkmcnt(0)
	v_mfma_f32_16x16x32_bf16 v[126:129], v[134:137], v[166:169], v[126:129]
	v_mfma_f32_16x16x32_bf16 v[122:125], v[158:161], v[166:169], v[122:125]
	v_mfma_f32_16x16x32_bf16 v[118:121], v[134:137], v[174:177], v[118:121]
	v_mfma_f32_16x16x32_bf16 v[110:113], v[158:161], v[174:177], v[110:113]
	v_mfma_f32_16x16x32_bf16 v[102:105], v[134:137], v[196:199], v[102:105]
	v_mfma_f32_16x16x32_bf16 v[94:97], v[158:161], v[196:199], v[94:97]
	v_mfma_f32_16x16x32_bf16 v[86:89], v[134:137], v[204:207], v[86:89]
	v_mfma_f32_16x16x32_bf16 v[78:81], v[158:161], v[204:207], v[78:81]
	s_setprio 0
	s_barrier
	s_add_i32 s22, 0, 0x1c000
	s_add_i32 s23, s50, s36
	v_add_u32_e32 v157, s22, v154
	v_lshl_add_u64 v[178:179], v[178:179], 0, s[78:79]
	s_mov_b32 m0, s23
	ds_read_b128 v[208:211], v157
	ds_read_b128 v[224:227], v157 offset:1024
	ds_read_b128 v[228:231], v157 offset:2048
	ds_read_b128 v[232:235], v157 offset:3072
	global_load_lds_dwordx4 v[178:179], off
	v_lshl_add_u64 v[178:179], v[212:213], 0, s[78:79]
	s_add_i32 m0, s23, 0x2000
	s_nop 0
	global_load_lds_dwordx4 v[178:179], off
	s_barrier
	s_waitcnt lgkmcnt(0)
	s_setprio 1
	s_waitcnt lgkmcnt(0)
	v_mfma_f32_16x16x32_bf16 v[114:117], v[208:211], v[162:165], v[114:117]
	v_mfma_f32_16x16x32_bf16 v[106:109], v[228:231], v[162:165], v[106:109]
	v_mfma_f32_16x16x32_bf16 v[98:101], v[208:211], v[170:173], v[98:101]
	v_mfma_f32_16x16x32_bf16 v[90:93], v[228:231], v[170:173], v[90:93]
	v_mfma_f32_16x16x32_bf16 v[82:85], v[208:211], v[192:195], v[82:85]
	v_mfma_f32_16x16x32_bf16 v[74:77], v[228:231], v[192:195], v[74:77]
	v_mfma_f32_16x16x32_bf16 v[70:73], v[208:211], v[200:203], v[70:73]
	v_mfma_f32_16x16x32_bf16 v[66:69], v[228:231], v[200:203], v[66:69]
	v_mfma_f32_16x16x32_bf16 v[114:117], v[224:227], v[166:169], v[114:117]
	v_mfma_f32_16x16x32_bf16 v[106:109], v[232:235], v[166:169], v[106:109]
	v_mfma_f32_16x16x32_bf16 v[98:101], v[224:227], v[174:177], v[98:101]
	v_mfma_f32_16x16x32_bf16 v[90:93], v[232:235], v[174:177], v[90:93]
	v_mfma_f32_16x16x32_bf16 v[82:85], v[224:227], v[196:199], v[82:85]
	v_mfma_f32_16x16x32_bf16 v[74:77], v[232:235], v[196:199], v[74:77]
	v_mfma_f32_16x16x32_bf16 v[70:73], v[224:227], v[204:207], v[70:73]
	v_mfma_f32_16x16x32_bf16 v[66:69], v[232:235], v[204:207], v[66:69]
	s_setprio 0
	s_mov_b32 m0, s25
	v_lshl_add_u64 v[178:179], v[236:237], 0, s[78:79]
	s_barrier
	ds_read_b128 v[162:165], v156 offset:49152
	ds_read_b128 v[170:173], v156 offset:51200
	ds_read_b128 v[192:195], v156 offset:53248
	ds_read_b128 v[200:203], v156 offset:55296
	ds_read_b128 v[166:169], v156 offset:50176
	ds_read_b128 v[174:177], v156 offset:52224
	ds_read_b128 v[196:199], v156 offset:54272
	ds_read_b128 v[204:207], v156 offset:56320
	global_load_lds_dwordx4 v[178:179], off
	v_lshl_add_u64 v[178:179], v[238:239], 0, s[78:79]
	s_mov_b32 m0, s26
	s_nop 0
	global_load_lds_dwordx4 v[178:179], off
	s_waitcnt vmcnt(10)
	s_barrier
	s_waitcnt lgkmcnt(4)
	s_setprio 1
	s_waitcnt lgkmcnt(4)
	v_mfma_f32_16x16x32_bf16 v[62:65], v[130:133], v[162:165], v[62:65]
	v_mfma_f32_16x16x32_bf16 v[58:61], v[150:153], v[162:165], v[58:61]
	v_mfma_f32_16x16x32_bf16 v[54:57], v[130:133], v[170:173], v[54:57]
	v_mfma_f32_16x16x32_bf16 v[46:49], v[150:153], v[170:173], v[46:49]
	v_mfma_f32_16x16x32_bf16 v[38:41], v[130:133], v[192:195], v[38:41]
	v_mfma_f32_16x16x32_bf16 v[30:33], v[150:153], v[192:195], v[30:33]
	v_mfma_f32_16x16x32_bf16 v[22:25], v[130:133], v[200:203], v[22:25]
	v_mfma_f32_16x16x32_bf16 v[14:17], v[150:153], v[200:203], v[14:17]
	s_waitcnt lgkmcnt(0)
	v_mfma_f32_16x16x32_bf16 v[62:65], v[134:137], v[166:169], v[62:65]
	v_mfma_f32_16x16x32_bf16 v[58:61], v[158:161], v[166:169], v[58:61]
	v_mfma_f32_16x16x32_bf16 v[54:57], v[134:137], v[174:177], v[54:57]
	v_mfma_f32_16x16x32_bf16 v[46:49], v[158:161], v[174:177], v[46:49]
	v_mfma_f32_16x16x32_bf16 v[38:41], v[134:137], v[196:199], v[38:41]
	v_mfma_f32_16x16x32_bf16 v[30:33], v[158:161], v[196:199], v[30:33]
	v_mfma_f32_16x16x32_bf16 v[22:25], v[134:137], v[204:207], v[22:25]
	v_mfma_f32_16x16x32_bf16 v[14:17], v[158:161], v[204:207], v[14:17]
	s_setprio 0
	s_barrier
	s_add_u32 s20, s20, 0x20080
	s_addc_u32 s21, s21, 0
	s_add_i32 s22, s22, s36
	v_lshl_add_u64 v[130:131], s[20:21], 0, v[142:143]
	s_mov_b32 m0, s22
	s_nop 0
	global_load_lds_dwordx4 v[130:131], off
	v_lshl_add_u64 v[130:131], s[20:21], 0, v[138:139]
	s_add_i32 m0, s22, 0x2000
	s_nop 0
	global_load_lds_dwordx4 v[130:131], off
	v_add_u32_e32 v157, 0x10000, v154
	ds_read_b128 v[130:133], v157
	ds_read_b128 v[134:137], v157 offset:1024
	ds_read_b128 v[150:153], v157 offset:2048
	ds_read_b128 v[158:161], v157 offset:3072
	s_waitcnt vmcnt(6)
	s_barrier
	s_setprio 1
	v_mfma_f32_16x16x32_bf16 v[50:53], v[208:211], v[162:165], v[50:53]
	v_mfma_f32_16x16x32_bf16 v[42:45], v[228:231], v[162:165], v[42:45]
	v_mfma_f32_16x16x32_bf16 v[34:37], v[208:211], v[170:173], v[34:37]
	v_mfma_f32_16x16x32_bf16 v[26:29], v[228:231], v[170:173], v[26:29]
	v_mfma_f32_16x16x32_bf16 v[18:21], v[208:211], v[192:195], v[18:21]
	v_mfma_f32_16x16x32_bf16 v[10:13], v[228:231], v[192:195], v[10:13]
	v_mfma_f32_16x16x32_bf16 v[6:9], v[208:211], v[200:203], v[6:9]
	v_mfma_f32_16x16x32_bf16 v[2:5], v[228:231], v[200:203], v[2:5]
	v_mfma_f32_16x16x32_bf16 v[50:53], v[224:227], v[166:169], v[50:53]
	v_mfma_f32_16x16x32_bf16 v[42:45], v[232:235], v[166:169], v[42:45]
	v_mfma_f32_16x16x32_bf16 v[34:37], v[224:227], v[174:177], v[34:37]
	v_mfma_f32_16x16x32_bf16 v[26:29], v[232:235], v[174:177], v[26:29]
	v_mfma_f32_16x16x32_bf16 v[18:21], v[224:227], v[196:199], v[18:21]
	v_mfma_f32_16x16x32_bf16 v[10:13], v[232:235], v[196:199], v[10:13]
	v_mfma_f32_16x16x32_bf16 v[6:9], v[224:227], v[204:207], v[6:9]
	v_mfma_f32_16x16x32_bf16 v[2:5], v[232:235], v[204:207], v[2:5]
	s_setprio 0
	s_add_i32 s49, s49, 2
	s_add_u32 s18, s18, 0x100
	s_addc_u32 s19, s19, 0
	s_add_u32 s47, s47, 0x100
	s_addc_u32 s48, s48, 0
	s_cmp_gt_u32 s49, 5
	s_barrier
	s_cbranch_scc0 .LBB0_386
	s_waitcnt lgkmcnt(0)
	v_lshl_add_u32 v164, s29, 8, v1
	v_lshl_or_b32 v150, s28, 8, v155
	s_mov_b64 s[18:19], -1
	s_cmp_lt_i32 s28, 8
	v_or_b32_e32 v163, 16, v164
	v_or_b32_e32 v162, 32, v164
	v_or_b32_e32 v161, 48, v164
	v_add_u32_e32 v160, 0x80, v164
	v_add_u32_e32 v159, 0x90, v164
	v_add_u32_e32 v158, 0xa0, v164
	v_add_u32_e32 v157, 0xb0, v164
	s_cbranch_scc1 .LBB0_389
	v_lshlrev_b32_e32 v130, 7, v164
	v_readlane_b32 s4, v255, 4
	v_and_b32_e32 v132, 0x3e780, v130
	v_mov_b32_e32 v133, v0
	v_readlane_b32 s5, v255, 5
	v_readlane_b32 s6, v255, 6
	v_readlane_b32 s7, v255, 7
	v_lshlrev_b32_e32 v130, 1, v150
	v_lshl_add_u64 v[134:135], s[4:5], 0, v[132:133]
	v_and_b32_e32 v130, 0x70, v130
	v_mov_b32_e32 v131, v0
	v_lshl_add_u64 v[132:133], s[6:7], 0, v[132:133]
	v_lshl_add_u64 v[152:153], v[132:133], 0, v[130:131]
	v_lshl_add_u64 v[136:137], v[134:135], 0, v[130:131]
	global_load_dwordx4 v[170:173], v[152:153], off
	global_load_dwordx4 v[166:169], v[136:137], off
	v_readlane_b32 s8, v255, 8
	v_readlane_b32 s9, v255, 9
	v_mov_b32_e32 v151, v0
	v_lshlrev_b64 v[134:135], 1, v[150:151]
	v_mov_b64_e32 v[132:133], s[8:9]
	v_mad_i64_i32 v[174:175], s[18:19], v164, s24, v[132:133]
	v_lshl_add_u64 v[174:175], v[174:175], 0, v[134:135]
	v_readlane_b32 s10, v255, 10
	v_readlane_b32 s11, v255, 11
	s_waitcnt vmcnt(0)
	v_pk_mul_f32 v[172:173], v[172:173], s[86:87] op_sel_hi:[1,0]
	v_pk_mul_f32 v[170:171], v[170:171], s[86:87] op_sel_hi:[1,0]
	v_pk_mul_f32 v[168:169], v[168:169], s[86:87] op_sel_hi:[1,0]
	v_pk_mul_f32 v[166:167], v[166:167], s[86:87] op_sel_hi:[1,0]
	v_pk_mul_f32 v[176:177], v[124:125], v[172:173]
	v_pk_mul_f32 v[178:179], v[122:123], v[170:171]
	v_pk_mul_f32 v[172:173], v[128:129], v[172:173]
	v_pk_mul_f32 v[170:171], v[126:127], v[170:171]
	v_pk_fma_f32 v[176:177], v[128:129], v[168:169], v[176:177] neg_lo:[0,0,1] neg_hi:[0,0,1]
	v_pk_fma_f32 v[178:179], v[126:127], v[166:167], v[178:179] neg_lo:[0,0,1] neg_hi:[0,0,1]
	v_pk_fma_f32 v[172:173], v[124:125], v[168:169], v[172:173]
	v_pk_fma_f32 v[168:169], v[122:123], v[166:167], v[170:171]
	v_cvt_pk_bf16_f32 v166, v178, v179
	v_cvt_pk_bf16_f32 v167, v176, v177
	v_cvt_pk_bf16_f32 v168, v168, v169
	v_cvt_pk_bf16_f32 v169, v172, v173
	global_store_dwordx4 v[174:175], v[166:169], off
	global_load_dwordx4 v[166:169], v[136:137], off
	s_nop 0
	global_load_dwordx4 v[170:173], v[152:153], off
	v_lshlrev_b32_e32 v136, 7, v163
	v_mov_b32_e32 v137, v0
	v_and_b32_e32 v136, 0x3ef80, v136
	v_lshl_add_u64 v[152:153], s[4:5], 0, v[136:137]
	v_lshl_add_u64 v[136:137], s[6:7], 0, v[136:137]
	v_lshl_add_u64 v[136:137], v[136:137], 0, v[130:131]
	v_lshl_add_u64 v[152:153], v[152:153], 0, v[130:131]
	s_waitcnt vmcnt(0)
	v_pk_mul_f32 v[168:169], v[168:169], s[86:87] op_sel_hi:[1,0]
	v_pk_mul_f32 v[172:173], v[172:173], s[86:87] op_sel_hi:[1,0]
	v_pk_mul_f32 v[170:171], v[170:171], s[86:87] op_sel_hi:[1,0]
	v_pk_mul_f32 v[166:167], v[166:167], s[86:87] op_sel_hi:[1,0]
	v_pk_mul_f32 v[176:177], v[108:109], v[172:173]
	v_pk_mul_f32 v[178:179], v[106:107], v[170:171]
	v_pk_mul_f32 v[172:173], v[116:117], v[172:173]
	v_pk_mul_f32 v[170:171], v[114:115], v[170:171]
	v_pk_fma_f32 v[176:177], v[116:117], v[168:169], v[176:177] neg_lo:[0,0,1] neg_hi:[0,0,1]
	v_pk_fma_f32 v[178:179], v[114:115], v[166:167], v[178:179] neg_lo:[0,0,1] neg_hi:[0,0,1]
	v_pk_fma_f32 v[172:173], v[108:109], v[168:169], v[172:173]
	v_pk_fma_f32 v[168:169], v[106:107], v[166:167], v[170:171]
	v_cvt_pk_bf16_f32 v166, v178, v179
	v_cvt_pk_bf16_f32 v167, v176, v177
	v_cvt_pk_bf16_f32 v168, v168, v169
	v_cvt_pk_bf16_f32 v169, v172, v173
	global_store_dwordx4 v[174:175], v[166:169], off offset:256
	global_load_dwordx4 v[170:173], v[136:137], off
	v_mad_i64_i32 v[174:175], s[18:19], v163, s24, v[132:133]
	global_load_dwordx4 v[166:169], v[152:153], off
	v_lshl_add_u64 v[174:175], v[174:175], 0, v[134:135]
	s_waitcnt vmcnt(0)
	v_pk_mul_f32 v[172:173], v[172:173], s[86:87] op_sel_hi:[1,0]
	v_pk_mul_f32 v[170:171], v[170:171], s[86:87] op_sel_hi:[1,0]
	v_pk_mul_f32 v[176:177], v[112:113], v[172:173]
	v_pk_mul_f32 v[168:169], v[168:169], s[86:87] op_sel_hi:[1,0]
	v_pk_mul_f32 v[166:167], v[166:167], s[86:87] op_sel_hi:[1,0]
	v_pk_mul_f32 v[178:179], v[110:111], v[170:171]
	v_pk_mul_f32 v[172:173], v[120:121], v[172:173]
	v_pk_mul_f32 v[170:171], v[118:119], v[170:171]
	v_pk_fma_f32 v[176:177], v[120:121], v[168:169], v[176:177] neg_lo:[0,0,1] neg_hi:[0,0,1]
	v_pk_fma_f32 v[178:179], v[118:119], v[166:167], v[178:179] neg_lo:[0,0,1] neg_hi:[0,0,1]
	v_pk_fma_f32 v[172:173], v[112:113], v[168:169], v[172:173]
	v_pk_fma_f32 v[168:169], v[110:111], v[166:167], v[170:171]
	v_cvt_pk_bf16_f32 v166, v178, v179
	v_cvt_pk_bf16_f32 v167, v176, v177
	v_cvt_pk_bf16_f32 v168, v168, v169
	v_cvt_pk_bf16_f32 v169, v172, v173
	global_store_dwordx4 v[174:175], v[166:169], off
	global_load_dwordx4 v[166:169], v[152:153], off
	s_nop 0
	global_load_dwordx4 v[170:173], v[136:137], off
	v_lshlrev_b32_e32 v136, 7, v162
	v_mov_b32_e32 v137, v0
	v_and_b32_e32 v136, 0x3f780, v136
	v_lshl_add_u64 v[152:153], s[4:5], 0, v[136:137]
	v_lshl_add_u64 v[136:137], s[6:7], 0, v[136:137]
	v_lshl_add_u64 v[136:137], v[136:137], 0, v[130:131]
	v_lshl_add_u64 v[152:153], v[152:153], 0, v[130:131]
	s_waitcnt vmcnt(0)
	v_pk_mul_f32 v[168:169], v[168:169], s[86:87] op_sel_hi:[1,0]
	v_pk_mul_f32 v[172:173], v[172:173], s[86:87] op_sel_hi:[1,0]
	v_pk_mul_f32 v[170:171], v[170:171], s[86:87] op_sel_hi:[1,0]
	v_pk_mul_f32 v[166:167], v[166:167], s[86:87] op_sel_hi:[1,0]
	v_pk_mul_f32 v[176:177], v[92:93], v[172:173]
	v_pk_mul_f32 v[178:179], v[90:91], v[170:171]
	v_pk_mul_f32 v[172:173], v[100:101], v[172:173]
	v_pk_mul_f32 v[170:171], v[98:99], v[170:171]
	v_pk_fma_f32 v[176:177], v[100:101], v[168:169], v[176:177] neg_lo:[0,0,1] neg_hi:[0,0,1]
	v_pk_fma_f32 v[178:179], v[98:99], v[166:167], v[178:179] neg_lo:[0,0,1] neg_hi:[0,0,1]
	v_pk_fma_f32 v[172:173], v[92:93], v[168:169], v[172:173]
	v_pk_fma_f32 v[168:169], v[90:91], v[166:167], v[170:171]
	v_cvt_pk_bf16_f32 v166, v178, v179
	v_cvt_pk_bf16_f32 v167, v176, v177
	v_cvt_pk_bf16_f32 v168, v168, v169
	v_cvt_pk_bf16_f32 v169, v172, v173
	global_store_dwordx4 v[174:175], v[166:169], off offset:256
	global_load_dwordx4 v[170:173], v[136:137], off
	v_mad_i64_i32 v[174:175], s[18:19], v162, s24, v[132:133]
	global_load_dwordx4 v[166:169], v[152:153], off
	v_lshl_add_u64 v[174:175], v[174:175], 0, v[134:135]
	s_waitcnt vmcnt(0)
	v_pk_mul_f32 v[172:173], v[172:173], s[86:87] op_sel_hi:[1,0]
	v_pk_mul_f32 v[170:171], v[170:171], s[86:87] op_sel_hi:[1,0]
	v_pk_mul_f32 v[176:177], v[96:97], v[172:173]
	v_pk_mul_f32 v[168:169], v[168:169], s[86:87] op_sel_hi:[1,0]
	v_pk_mul_f32 v[166:167], v[166:167], s[86:87] op_sel_hi:[1,0]
	v_pk_mul_f32 v[178:179], v[94:95], v[170:171]
	v_pk_mul_f32 v[172:173], v[104:105], v[172:173]
	v_pk_mul_f32 v[170:171], v[102:103], v[170:171]
	v_pk_fma_f32 v[176:177], v[104:105], v[168:169], v[176:177] neg_lo:[0,0,1] neg_hi:[0,0,1]
	v_pk_fma_f32 v[178:179], v[102:103], v[166:167], v[178:179] neg_lo:[0,0,1] neg_hi:[0,0,1]
	v_pk_fma_f32 v[172:173], v[96:97], v[168:169], v[172:173]
	v_pk_fma_f32 v[168:169], v[94:95], v[166:167], v[170:171]
	v_cvt_pk_bf16_f32 v166, v178, v179
	v_cvt_pk_bf16_f32 v167, v176, v177
	v_cvt_pk_bf16_f32 v168, v168, v169
	v_cvt_pk_bf16_f32 v169, v172, v173
	global_store_dwordx4 v[174:175], v[166:169], off
	global_load_dwordx4 v[166:169], v[152:153], off
	s_nop 0
	global_load_dwordx4 v[170:173], v[136:137], off
	v_lshlrev_b32_e32 v136, 7, v161
	v_mov_b32_e32 v137, v0
	v_and_b32_e32 v136, 0x3ff80, v136
	v_lshl_add_u64 v[152:153], s[4:5], 0, v[136:137]
	v_lshl_add_u64 v[136:137], s[6:7], 0, v[136:137]
	v_lshl_add_u64 v[136:137], v[136:137], 0, v[130:131]
	v_lshl_add_u64 v[152:153], v[152:153], 0, v[130:131]
	s_waitcnt vmcnt(0)
	v_pk_mul_f32 v[168:169], v[168:169], s[86:87] op_sel_hi:[1,0]
	v_pk_mul_f32 v[172:173], v[172:173], s[86:87] op_sel_hi:[1,0]
	v_pk_mul_f32 v[170:171], v[170:171], s[86:87] op_sel_hi:[1,0]
	v_pk_mul_f32 v[166:167], v[166:167], s[86:87] op_sel_hi:[1,0]
	v_pk_mul_f32 v[176:177], v[76:77], v[172:173]
	v_pk_mul_f32 v[178:179], v[74:75], v[170:171]
	v_pk_mul_f32 v[172:173], v[84:85], v[172:173]
	v_pk_mul_f32 v[170:171], v[82:83], v[170:171]
	v_pk_fma_f32 v[176:177], v[84:85], v[168:169], v[176:177] neg_lo:[0,0,1] neg_hi:[0,0,1]
	v_pk_fma_f32 v[178:179], v[82:83], v[166:167], v[178:179] neg_lo:[0,0,1] neg_hi:[0,0,1]
	v_pk_fma_f32 v[172:173], v[76:77], v[168:169], v[172:173]
	v_pk_fma_f32 v[168:169], v[74:75], v[166:167], v[170:171]
	v_cvt_pk_bf16_f32 v166, v178, v179
	v_cvt_pk_bf16_f32 v167, v176, v177
	v_cvt_pk_bf16_f32 v168, v168, v169
	v_cvt_pk_bf16_f32 v169, v172, v173
	global_store_dwordx4 v[174:175], v[166:169], off offset:256
	global_load_dwordx4 v[170:173], v[136:137], off
	v_mad_i64_i32 v[174:175], s[18:19], v161, s24, v[132:133]
	global_load_dwordx4 v[166:169], v[152:153], off
	v_lshl_add_u64 v[174:175], v[174:175], 0, v[134:135]
	s_waitcnt vmcnt(0)
	v_pk_mul_f32 v[172:173], v[172:173], s[86:87] op_sel_hi:[1,0]
	v_pk_mul_f32 v[170:171], v[170:171], s[86:87] op_sel_hi:[1,0]
	v_pk_mul_f32 v[176:177], v[80:81], v[172:173]
	v_pk_mul_f32 v[168:169], v[168:169], s[86:87] op_sel_hi:[1,0]
	v_pk_mul_f32 v[166:167], v[166:167], s[86:87] op_sel_hi:[1,0]
	v_pk_mul_f32 v[178:179], v[78:79], v[170:171]
	v_pk_mul_f32 v[172:173], v[88:89], v[172:173]
	v_pk_mul_f32 v[170:171], v[86:87], v[170:171]
	v_pk_fma_f32 v[176:177], v[88:89], v[168:169], v[176:177] neg_lo:[0,0,1] neg_hi:[0,0,1]
	v_pk_fma_f32 v[178:179], v[86:87], v[166:167], v[178:179] neg_lo:[0,0,1] neg_hi:[0,0,1]
	v_pk_fma_f32 v[172:173], v[80:81], v[168:169], v[172:173]
	v_pk_fma_f32 v[168:169], v[78:79], v[166:167], v[170:171]
	v_cvt_pk_bf16_f32 v166, v178, v179
	v_cvt_pk_bf16_f32 v167, v176, v177
	v_cvt_pk_bf16_f32 v168, v168, v169
	v_cvt_pk_bf16_f32 v169, v172, v173
	global_store_dwordx4 v[174:175], v[166:169], off
	global_load_dwordx4 v[166:169], v[152:153], off
	s_nop 0
	global_load_dwordx4 v[170:173], v[136:137], off
	v_lshlrev_b32_e32 v136, 7, v160
	v_mov_b32_e32 v137, v0
	v_and_b32_e32 v136, 0x3e780, v136
	v_lshl_add_u64 v[152:153], s[4:5], 0, v[136:137]
	v_lshl_add_u64 v[136:137], s[6:7], 0, v[136:137]
	v_lshl_add_u64 v[136:137], v[136:137], 0, v[130:131]
	v_lshl_add_u64 v[152:153], v[152:153], 0, v[130:131]
	s_waitcnt vmcnt(0)
	v_pk_mul_f32 v[168:169], v[168:169], s[86:87] op_sel_hi:[1,0]
	v_pk_mul_f32 v[172:173], v[172:173], s[86:87] op_sel_hi:[1,0]
	v_pk_mul_f32 v[170:171], v[170:171], s[86:87] op_sel_hi:[1,0]
	v_pk_mul_f32 v[166:167], v[166:167], s[86:87] op_sel_hi:[1,0]
	v_pk_mul_f32 v[176:177], v[68:69], v[172:173]
	v_pk_mul_f32 v[178:179], v[66:67], v[170:171]
	v_pk_mul_f32 v[172:173], v[72:73], v[172:173]
	v_pk_mul_f32 v[170:171], v[70:71], v[170:171]
	v_pk_fma_f32 v[176:177], v[72:73], v[168:169], v[176:177] neg_lo:[0,0,1] neg_hi:[0,0,1]
	v_pk_fma_f32 v[178:179], v[70:71], v[166:167], v[178:179] neg_lo:[0,0,1] neg_hi:[0,0,1]
	v_pk_fma_f32 v[172:173], v[68:69], v[168:169], v[172:173]
	v_pk_fma_f32 v[168:169], v[66:67], v[166:167], v[170:171]
	v_cvt_pk_bf16_f32 v166, v178, v179
	v_cvt_pk_bf16_f32 v167, v176, v177
	v_cvt_pk_bf16_f32 v168, v168, v169
	v_cvt_pk_bf16_f32 v169, v172, v173
	global_store_dwordx4 v[174:175], v[166:169], off offset:256
	global_load_dwordx4 v[170:173], v[136:137], off
	v_mad_i64_i32 v[174:175], s[18:19], v160, s24, v[132:133]
	global_load_dwordx4 v[166:169], v[152:153], off
	v_lshl_add_u64 v[174:175], v[174:175], 0, v[134:135]
	s_waitcnt vmcnt(0)
	v_pk_mul_f32 v[172:173], v[172:173], s[86:87] op_sel_hi:[1,0]
	v_pk_mul_f32 v[170:171], v[170:171], s[86:87] op_sel_hi:[1,0]
	v_pk_mul_f32 v[176:177], v[60:61], v[172:173]
	v_pk_mul_f32 v[168:169], v[168:169], s[86:87] op_sel_hi:[1,0]
	v_pk_mul_f32 v[166:167], v[166:167], s[86:87] op_sel_hi:[1,0]
	v_pk_mul_f32 v[178:179], v[58:59], v[170:171]
	v_pk_mul_f32 v[172:173], v[64:65], v[172:173]
	v_pk_mul_f32 v[170:171], v[62:63], v[170:171]
	v_pk_fma_f32 v[176:177], v[64:65], v[168:169], v[176:177] neg_lo:[0,0,1] neg_hi:[0,0,1]
	v_pk_fma_f32 v[178:179], v[62:63], v[166:167], v[178:179] neg_lo:[0,0,1] neg_hi:[0,0,1]
	v_pk_fma_f32 v[172:173], v[60:61], v[168:169], v[172:173]
	v_pk_fma_f32 v[168:169], v[58:59], v[166:167], v[170:171]
	v_cvt_pk_bf16_f32 v166, v178, v179
	v_cvt_pk_bf16_f32 v167, v176, v177
	v_cvt_pk_bf16_f32 v168, v168, v169
	v_cvt_pk_bf16_f32 v169, v172, v173
	global_store_dwordx4 v[174:175], v[166:169], off
	global_load_dwordx4 v[166:169], v[152:153], off
	s_nop 0
	global_load_dwordx4 v[170:173], v[136:137], off
	v_lshlrev_b32_e32 v136, 7, v159
	v_mov_b32_e32 v137, v0
	v_and_b32_e32 v136, 0x3ef80, v136
	v_lshl_add_u64 v[152:153], s[4:5], 0, v[136:137]
	v_lshl_add_u64 v[136:137], s[6:7], 0, v[136:137]
	v_lshl_add_u64 v[136:137], v[136:137], 0, v[130:131]
	v_lshl_add_u64 v[152:153], v[152:153], 0, v[130:131]
	s_waitcnt vmcnt(0)
	v_pk_mul_f32 v[168:169], v[168:169], s[86:87] op_sel_hi:[1,0]
	v_pk_mul_f32 v[172:173], v[172:173], s[86:87] op_sel_hi:[1,0]
	v_pk_mul_f32 v[170:171], v[170:171], s[86:87] op_sel_hi:[1,0]
	v_pk_mul_f32 v[166:167], v[166:167], s[86:87] op_sel_hi:[1,0]
	v_pk_mul_f32 v[176:177], v[44:45], v[172:173]
	v_pk_mul_f32 v[178:179], v[42:43], v[170:171]
	v_pk_mul_f32 v[172:173], v[52:53], v[172:173]
	v_pk_mul_f32 v[170:171], v[50:51], v[170:171]
	v_pk_fma_f32 v[176:177], v[52:53], v[168:169], v[176:177] neg_lo:[0,0,1] neg_hi:[0,0,1]
	v_pk_fma_f32 v[178:179], v[50:51], v[166:167], v[178:179] neg_lo:[0,0,1] neg_hi:[0,0,1]
	v_pk_fma_f32 v[172:173], v[44:45], v[168:169], v[172:173]
	v_pk_fma_f32 v[168:169], v[42:43], v[166:167], v[170:171]
	v_cvt_pk_bf16_f32 v166, v178, v179
	v_cvt_pk_bf16_f32 v167, v176, v177
	v_cvt_pk_bf16_f32 v168, v168, v169
	v_cvt_pk_bf16_f32 v169, v172, v173
	global_store_dwordx4 v[174:175], v[166:169], off offset:256
	global_load_dwordx4 v[170:173], v[136:137], off
	v_mad_i64_i32 v[174:175], s[18:19], v159, s24, v[132:133]
	global_load_dwordx4 v[166:169], v[152:153], off
	v_lshl_add_u64 v[174:175], v[174:175], 0, v[134:135]
	s_waitcnt vmcnt(0)
	v_pk_mul_f32 v[172:173], v[172:173], s[86:87] op_sel_hi:[1,0]
	v_pk_mul_f32 v[170:171], v[170:171], s[86:87] op_sel_hi:[1,0]
	v_pk_mul_f32 v[176:177], v[48:49], v[172:173]
	v_pk_mul_f32 v[168:169], v[168:169], s[86:87] op_sel_hi:[1,0]
	v_pk_mul_f32 v[166:167], v[166:167], s[86:87] op_sel_hi:[1,0]
	v_pk_mul_f32 v[178:179], v[46:47], v[170:171]
	v_pk_mul_f32 v[172:173], v[56:57], v[172:173]
	v_pk_mul_f32 v[170:171], v[54:55], v[170:171]
	v_pk_fma_f32 v[176:177], v[56:57], v[168:169], v[176:177] neg_lo:[0,0,1] neg_hi:[0,0,1]
	v_pk_fma_f32 v[178:179], v[54:55], v[166:167], v[178:179] neg_lo:[0,0,1] neg_hi:[0,0,1]
	v_pk_fma_f32 v[172:173], v[48:49], v[168:169], v[172:173]
	v_pk_fma_f32 v[168:169], v[46:47], v[166:167], v[170:171]
	v_cvt_pk_bf16_f32 v166, v178, v179
	v_cvt_pk_bf16_f32 v167, v176, v177
	v_cvt_pk_bf16_f32 v168, v168, v169
	v_cvt_pk_bf16_f32 v169, v172, v173
	global_store_dwordx4 v[174:175], v[166:169], off
	global_load_dwordx4 v[166:169], v[152:153], off
	s_nop 0
	global_load_dwordx4 v[170:173], v[136:137], off
	v_lshlrev_b32_e32 v136, 7, v158
	v_mov_b32_e32 v137, v0
	v_and_b32_e32 v136, 0x3f780, v136
	v_lshl_add_u64 v[152:153], s[4:5], 0, v[136:137]
	v_lshl_add_u64 v[136:137], s[6:7], 0, v[136:137]
	v_lshl_add_u64 v[136:137], v[136:137], 0, v[130:131]
	v_lshl_add_u64 v[152:153], v[152:153], 0, v[130:131]
	s_waitcnt vmcnt(0)
	v_pk_mul_f32 v[168:169], v[168:169], s[86:87] op_sel_hi:[1,0]
	v_pk_mul_f32 v[172:173], v[172:173], s[86:87] op_sel_hi:[1,0]
	v_pk_mul_f32 v[170:171], v[170:171], s[86:87] op_sel_hi:[1,0]
	v_pk_mul_f32 v[166:167], v[166:167], s[86:87] op_sel_hi:[1,0]
	v_pk_mul_f32 v[176:177], v[28:29], v[172:173]
	v_pk_mul_f32 v[178:179], v[26:27], v[170:171]
	v_pk_mul_f32 v[172:173], v[36:37], v[172:173]
	v_pk_mul_f32 v[170:171], v[34:35], v[170:171]
	v_pk_fma_f32 v[176:177], v[36:37], v[168:169], v[176:177] neg_lo:[0,0,1] neg_hi:[0,0,1]
	v_pk_fma_f32 v[178:179], v[34:35], v[166:167], v[178:179] neg_lo:[0,0,1] neg_hi:[0,0,1]
	v_pk_fma_f32 v[172:173], v[28:29], v[168:169], v[172:173]
	v_pk_fma_f32 v[168:169], v[26:27], v[166:167], v[170:171]
	v_cvt_pk_bf16_f32 v166, v178, v179
	v_cvt_pk_bf16_f32 v167, v176, v177
	v_cvt_pk_bf16_f32 v168, v168, v169
	v_cvt_pk_bf16_f32 v169, v172, v173
	global_store_dwordx4 v[174:175], v[166:169], off offset:256
	global_load_dwordx4 v[170:173], v[136:137], off
	v_mad_i64_i32 v[174:175], s[18:19], v158, s24, v[132:133]
	global_load_dwordx4 v[166:169], v[152:153], off
	v_lshl_add_u64 v[174:175], v[174:175], 0, v[134:135]
	s_waitcnt vmcnt(0)
	v_pk_mul_f32 v[172:173], v[172:173], s[86:87] op_sel_hi:[1,0]
	v_pk_mul_f32 v[170:171], v[170:171], s[86:87] op_sel_hi:[1,0]
	v_pk_mul_f32 v[176:177], v[32:33], v[172:173]
	v_pk_mul_f32 v[168:169], v[168:169], s[86:87] op_sel_hi:[1,0]
	v_pk_mul_f32 v[166:167], v[166:167], s[86:87] op_sel_hi:[1,0]
	v_pk_mul_f32 v[178:179], v[30:31], v[170:171]
	v_pk_mul_f32 v[172:173], v[40:41], v[172:173]
	v_pk_mul_f32 v[170:171], v[38:39], v[170:171]
	v_pk_fma_f32 v[176:177], v[40:41], v[168:169], v[176:177] neg_lo:[0,0,1] neg_hi:[0,0,1]
	v_pk_fma_f32 v[178:179], v[38:39], v[166:167], v[178:179] neg_lo:[0,0,1] neg_hi:[0,0,1]
	v_pk_fma_f32 v[172:173], v[32:33], v[168:169], v[172:173]
	v_pk_fma_f32 v[168:169], v[30:31], v[166:167], v[170:171]
	v_cvt_pk_bf16_f32 v166, v178, v179
	v_cvt_pk_bf16_f32 v167, v176, v177
	v_cvt_pk_bf16_f32 v168, v168, v169
	v_cvt_pk_bf16_f32 v169, v172, v173
	global_store_dwordx4 v[174:175], v[166:169], off
	global_load_dwordx4 v[166:169], v[152:153], off
	s_nop 0
	global_load_dwordx4 v[170:173], v[136:137], off
	v_lshlrev_b32_e32 v136, 7, v157
	v_mov_b32_e32 v137, v0
	v_and_b32_e32 v136, 0x3ff80, v136
	v_lshl_add_u64 v[152:153], s[4:5], 0, v[136:137]
	v_lshl_add_u64 v[176:177], v[152:153], 0, v[130:131]
	v_lshl_add_u64 v[136:137], s[6:7], 0, v[136:137]
	v_lshl_add_u64 v[136:137], v[136:137], 0, v[130:131]
	v_mad_i64_i32 v[130:131], s[18:19], v157, s24, v[132:133]
	s_mov_b64 s[18:19], 0
	s_waitcnt vmcnt(0)
	v_pk_mul_f32 v[152:153], v[168:169], s[86:87] op_sel_hi:[1,0]
	v_pk_mul_f32 v[168:169], v[172:173], s[86:87] op_sel_hi:[1,0]
	v_pk_mul_f32 v[170:171], v[170:171], s[86:87] op_sel_hi:[1,0]
	v_pk_mul_f32 v[166:167], v[166:167], s[86:87] op_sel_hi:[1,0]
	v_pk_mul_f32 v[172:173], v[12:13], v[168:169]
	v_pk_mul_f32 v[178:179], v[10:11], v[170:171]
	v_pk_mul_f32 v[168:169], v[20:21], v[168:169]
	v_pk_mul_f32 v[170:171], v[18:19], v[170:171]
	v_pk_fma_f32 v[172:173], v[20:21], v[152:153], v[172:173] neg_lo:[0,0,1] neg_hi:[0,0,1]
	v_pk_fma_f32 v[178:179], v[18:19], v[166:167], v[178:179] neg_lo:[0,0,1] neg_hi:[0,0,1]
	v_pk_fma_f32 v[152:153], v[12:13], v[152:153], v[168:169]
	v_pk_fma_f32 v[168:169], v[10:11], v[166:167], v[170:171]
	v_cvt_pk_bf16_f32 v166, v178, v179
	v_cvt_pk_bf16_f32 v167, v172, v173
	v_cvt_pk_bf16_f32 v168, v168, v169
	v_cvt_pk_bf16_f32 v169, v152, v153
	global_store_dwordx4 v[174:175], v[166:169], off offset:256
	global_load_dwordx4 v[166:169], v[176:177], off
	v_lshl_add_u64 v[152:153], v[130:131], 0, v[134:135]
	global_load_dwordx4 v[170:173], v[136:137], off
	s_waitcnt vmcnt(0)
	v_pk_mul_f32 v[132:133], v[166:167], s[86:87] op_sel_hi:[1,0]
	v_pk_mul_f32 v[130:131], v[168:169], s[86:87] op_sel_hi:[1,0]
	v_pk_mul_f32 v[134:135], v[172:173], s[86:87] op_sel_hi:[1,0]
	v_pk_mul_f32 v[166:167], v[170:171], s[86:87] op_sel_hi:[1,0]
	v_pk_mul_f32 v[168:169], v[16:17], v[134:135]
	v_pk_mul_f32 v[170:171], v[14:15], v[166:167]
	v_pk_mul_f32 v[134:135], v[24:25], v[134:135]
	v_pk_mul_f32 v[166:167], v[22:23], v[166:167]
	v_pk_fma_f32 v[168:169], v[24:25], v[130:131], v[168:169] neg_lo:[0,0,1] neg_hi:[0,0,1]
	v_pk_fma_f32 v[170:171], v[22:23], v[132:133], v[170:171] neg_lo:[0,0,1] neg_hi:[0,0,1]
	v_pk_fma_f32 v[134:135], v[16:17], v[130:131], v[134:135]
	v_pk_fma_f32 v[132:133], v[14:15], v[132:133], v[166:167]
	v_cvt_pk_bf16_f32 v130, v170, v171
	v_cvt_pk_bf16_f32 v131, v168, v169
	v_cvt_pk_bf16_f32 v132, v132, v133
	v_cvt_pk_bf16_f32 v133, v134, v135
	global_store_dwordx4 v[152:153], v[130:133], off
	global_load_dwordx4 v[130:133], v[176:177], off
	s_nop 0
	global_load_dwordx4 v[134:137], v[136:137], off
	s_waitcnt vmcnt(0)
	v_pk_mul_f32 v[166:167], v[132:133], s[86:87] op_sel_hi:[1,0]
	v_pk_mul_f32 v[168:169], v[130:131], s[86:87] op_sel_hi:[1,0]
	v_pk_mul_f32 v[130:131], v[136:137], s[86:87] op_sel_hi:[1,0]
	v_pk_mul_f32 v[132:133], v[134:135], s[86:87] op_sel_hi:[1,0]
	v_pk_mul_f32 v[134:135], v[4:5], v[130:131]
	v_pk_mul_f32 v[136:137], v[2:3], v[132:133]
	v_pk_mul_f32 v[170:171], v[8:9], v[130:131]
	v_pk_mul_f32 v[172:173], v[6:7], v[132:133]
	v_pk_fma_f32 v[132:133], v[8:9], v[166:167], v[134:135] neg_lo:[0,0,1] neg_hi:[0,0,1]
	v_pk_fma_f32 v[130:131], v[6:7], v[168:169], v[136:137] neg_lo:[0,0,1] neg_hi:[0,0,1]
	v_pk_fma_f32 v[136:137], v[4:5], v[166:167], v[170:171]
	v_pk_fma_f32 v[134:135], v[2:3], v[168:169], v[172:173]

.LBB0_526:
	s_add_u32 s20, s18, 0xfff80080
	s_addc_u32 s21, s19, -1
	s_add_i32 s56, 0, 0x10000
	s_cmp_eq_u32 s55, 28
	s_cselect_b32 s23, s39, s21
	s_cselect_b32 s22, s51, s20
	s_cselect_b32 s21, s31, s54
	s_cselect_b32 s20, s52, s53
	v_lshl_add_u64 v[152:153], s[18:19], 0, v[140:141]
	s_add_i32 m0, s29, 0xc000
	ds_read_b128 v[164:167], v154
	ds_read_b128 v[172:175], v154 offset:2048
	ds_read_b128 v[192:195], v154 offset:4096
	ds_read_b128 v[200:203], v154 offset:6144
	ds_read_b128 v[168:171], v154 offset:1024
	ds_read_b128 v[176:179], v154 offset:3072
	ds_read_b128 v[196:199], v154 offset:5120
	ds_read_b128 v[204:207], v154 offset:7168
	global_load_lds_dwordx4 v[152:153], off
	v_lshl_add_u64 v[152:153], s[18:19], 0, v[142:143]
	s_add_i32 m0, s29, 0xe000
	s_nop 0
	global_load_lds_dwordx4 v[152:153], off
	s_waitcnt lgkmcnt(8)
	s_barrier
	s_waitcnt lgkmcnt(4)
	s_setprio 1
	s_waitcnt lgkmcnt(4)
	v_mfma_f32_16x16x32_bf16 v[126:129], v[144:147], v[164:167], v[126:129]
	v_mfma_f32_16x16x32_bf16 v[122:125], v[156:159], v[164:167], v[122:125]
	v_mfma_f32_16x16x32_bf16 v[118:121], v[144:147], v[172:175], v[118:121]
	v_mfma_f32_16x16x32_bf16 v[114:117], v[156:159], v[172:175], v[114:117]
	v_mfma_f32_16x16x32_bf16 v[102:105], v[144:147], v[192:195], v[102:105]
	v_mfma_f32_16x16x32_bf16 v[98:101], v[156:159], v[192:195], v[98:101]
	v_mfma_f32_16x16x32_bf16 v[86:89], v[144:147], v[200:203], v[86:89]
	v_mfma_f32_16x16x32_bf16 v[82:85], v[156:159], v[200:203], v[82:85]
	s_waitcnt lgkmcnt(0)
	v_mfma_f32_16x16x32_bf16 v[126:129], v[148:151], v[168:171], v[126:129]
	v_mfma_f32_16x16x32_bf16 v[122:125], v[160:163], v[168:171], v[122:125]
	v_mfma_f32_16x16x32_bf16 v[118:121], v[148:151], v[176:179], v[118:121]
	v_mfma_f32_16x16x32_bf16 v[114:117], v[160:163], v[176:179], v[114:117]
	v_mfma_f32_16x16x32_bf16 v[102:105], v[148:151], v[196:199], v[102:105]
	v_mfma_f32_16x16x32_bf16 v[98:101], v[160:163], v[196:199], v[98:101]
	v_mfma_f32_16x16x32_bf16 v[86:89], v[148:151], v[204:207], v[86:89]
	v_mfma_f32_16x16x32_bf16 v[82:85], v[160:163], v[204:207], v[82:85]
	s_setprio 0
	s_barrier
	s_add_i32 s58, 0, 0x14000
	v_add_u32_e32 v152, s58, v139
	s_add_i32 s56, s56, s28
	ds_read_b128 v[208:211], v152
	ds_read_b128 v[224:227], v152 offset:1024
	ds_read_b128 v[228:231], v152 offset:2048
	ds_read_b128 v[232:235], v152 offset:3072
	v_lshl_add_u64 v[152:153], s[20:21], 0, v[134:135]
	s_mov_b32 m0, s56
	v_lshl_add_u64 v[212:213], s[20:21], 0, v[130:131]
	global_load_lds_dwordx4 v[152:153], off
	s_add_i32 m0, s56, 0x2000
	s_nop 0
	global_load_lds_dwordx4 v[212:213], off
	s_barrier
	s_waitcnt lgkmcnt(0)
	s_setprio 1
	s_waitcnt lgkmcnt(0)
	v_mfma_f32_16x16x32_bf16 v[110:113], v[208:211], v[164:167], v[110:113]
	v_mfma_f32_16x16x32_bf16 v[106:109], v[228:231], v[164:167], v[106:109]
	v_mfma_f32_16x16x32_bf16 v[94:97], v[208:211], v[172:175], v[94:97]
	v_mfma_f32_16x16x32_bf16 v[90:93], v[228:231], v[172:175], v[90:93]
	v_mfma_f32_16x16x32_bf16 v[78:81], v[208:211], v[192:195], v[78:81]
	v_mfma_f32_16x16x32_bf16 v[74:77], v[228:231], v[192:195], v[74:77]
	v_mfma_f32_16x16x32_bf16 v[70:73], v[208:211], v[200:203], v[70:73]
	v_mfma_f32_16x16x32_bf16 v[66:69], v[228:231], v[200:203], v[66:69]
	v_mfma_f32_16x16x32_bf16 v[110:113], v[224:227], v[168:171], v[110:113]
	v_mfma_f32_16x16x32_bf16 v[106:109], v[232:235], v[168:171], v[106:109]
	v_mfma_f32_16x16x32_bf16 v[94:97], v[224:227], v[176:179], v[94:97]
	v_mfma_f32_16x16x32_bf16 v[90:93], v[232:235], v[176:179], v[90:93]
	v_mfma_f32_16x16x32_bf16 v[78:81], v[224:227], v[196:199], v[78:81]
	v_mfma_f32_16x16x32_bf16 v[74:77], v[232:235], v[196:199], v[74:77]
	v_mfma_f32_16x16x32_bf16 v[70:73], v[224:227], v[204:207], v[70:73]
	v_mfma_f32_16x16x32_bf16 v[66:69], v[232:235], v[204:207], v[66:69]
	s_setprio 0
	s_mov_b32 m0, s29
	v_lshl_add_u64 v[236:237], s[22:23], 0, v[136:137]
	s_barrier
	ds_read_b128 v[164:167], v154 offset:16384
	ds_read_b128 v[172:175], v154 offset:18432
	ds_read_b128 v[192:195], v154 offset:20480
	ds_read_b128 v[200:203], v154 offset:22528
	ds_read_b128 v[168:171], v154 offset:17408
	ds_read_b128 v[176:179], v154 offset:19456
	ds_read_b128 v[196:199], v154 offset:21504
	ds_read_b128 v[204:207], v154 offset:23552
	global_load_lds_dwordx4 v[236:237], off
	v_lshl_add_u64 v[238:239], s[22:23], 0, v[132:133]
	s_mov_b32 m0, s44
	s_nop 0
	global_load_lds_dwordx4 v[238:239], off
	s_waitcnt vmcnt(10)
	s_barrier
	s_waitcnt lgkmcnt(4)
	s_setprio 1
	s_waitcnt lgkmcnt(4)
	v_mfma_f32_16x16x32_bf16 v[62:65], v[144:147], v[164:167], v[62:65]
	v_mfma_f32_16x16x32_bf16 v[58:61], v[156:159], v[164:167], v[58:61]
	v_mfma_f32_16x16x32_bf16 v[54:57], v[144:147], v[172:175], v[54:57]
	v_mfma_f32_16x16x32_bf16 v[50:53], v[156:159], v[172:175], v[50:53]
	v_mfma_f32_16x16x32_bf16 v[38:41], v[144:147], v[192:195], v[38:41]
	v_mfma_f32_16x16x32_bf16 v[34:37], v[156:159], v[192:195], v[34:37]
	v_mfma_f32_16x16x32_bf16 v[22:25], v[144:147], v[200:203], v[22:25]
	v_mfma_f32_16x16x32_bf16 v[18:21], v[156:159], v[200:203], v[18:21]
	s_waitcnt lgkmcnt(0)
	v_mfma_f32_16x16x32_bf16 v[62:65], v[148:151], v[168:171], v[62:65]
	v_mfma_f32_16x16x32_bf16 v[58:61], v[160:163], v[168:171], v[58:61]
	v_mfma_f32_16x16x32_bf16 v[54:57], v[148:151], v[176:179], v[54:57]
	v_mfma_f32_16x16x32_bf16 v[50:53], v[160:163], v[176:179], v[50:53]
	v_mfma_f32_16x16x32_bf16 v[38:41], v[148:151], v[196:199], v[38:41]
	v_mfma_f32_16x16x32_bf16 v[34:37], v[160:163], v[196:199], v[34:37]
	v_mfma_f32_16x16x32_bf16 v[22:25], v[148:151], v[204:207], v[22:25]
	v_mfma_f32_16x16x32_bf16 v[18:21], v[160:163], v[204:207], v[18:21]
	s_setprio 0
	s_barrier
	s_add_u32 s56, s20, 0x80000
	s_addc_u32 s57, s21, 0
	s_add_i32 s58, s58, s28
	v_lshl_add_u64 v[144:145], s[56:57], 0, v[134:135]
	s_mov_b32 m0, s58
	s_nop 0
	global_load_lds_dwordx4 v[144:145], off
	v_lshl_add_u64 v[144:145], s[56:57], 0, v[130:131]
	s_add_i32 m0, s58, 0x2000
	s_nop 0
	global_load_lds_dwordx4 v[144:145], off
	v_add_u32_e32 v155, 0x18000, v139
	ds_read_b128 v[144:147], v155
	ds_read_b128 v[148:151], v155 offset:1024
	ds_read_b128 v[156:159], v155 offset:2048
	ds_read_b128 v[160:163], v155 offset:3072
	s_waitcnt vmcnt(6)
	s_barrier
	s_setprio 1
	v_mfma_f32_16x16x32_bf16 v[46:49], v[208:211], v[164:167], v[46:49]
	v_mfma_f32_16x16x32_bf16 v[42:45], v[228:231], v[164:167], v[42:45]
	v_mfma_f32_16x16x32_bf16 v[30:33], v[208:211], v[172:175], v[30:33]
	v_mfma_f32_16x16x32_bf16 v[26:29], v[228:231], v[172:175], v[26:29]
	v_mfma_f32_16x16x32_bf16 v[14:17], v[208:211], v[192:195], v[14:17]
	v_mfma_f32_16x16x32_bf16 v[10:13], v[228:231], v[192:195], v[10:13]
	v_mfma_f32_16x16x32_bf16 v[6:9], v[208:211], v[200:203], v[6:9]
	v_mfma_f32_16x16x32_bf16 v[2:5], v[228:231], v[200:203], v[2:5]
	v_mfma_f32_16x16x32_bf16 v[46:49], v[224:227], v[168:171], v[46:49]
	v_mfma_f32_16x16x32_bf16 v[42:45], v[232:235], v[168:171], v[42:45]
	v_mfma_f32_16x16x32_bf16 v[30:33], v[224:227], v[176:179], v[30:33]
	v_mfma_f32_16x16x32_bf16 v[26:29], v[232:235], v[176:179], v[26:29]
	v_mfma_f32_16x16x32_bf16 v[14:17], v[224:227], v[196:199], v[14:17]
	v_mfma_f32_16x16x32_bf16 v[10:13], v[232:235], v[196:199], v[10:13]
	v_mfma_f32_16x16x32_bf16 v[6:9], v[224:227], v[204:207], v[6:9]
	v_mfma_f32_16x16x32_bf16 v[2:5], v[232:235], v[204:207], v[2:5]
	s_setprio 0
	s_add_i32 s56, 0, 0x18000
	s_barrier
	s_add_u32 s22, s22, 0x80000
	s_addc_u32 s23, s23, 0
	s_mov_b32 m0, s45
	v_lshl_add_u64 v[208:209], s[22:23], 0, v[136:137]
	ds_read_b128 v[164:167], v154 offset:32768
	ds_read_b128 v[172:175], v154 offset:34816
	ds_read_b128 v[192:195], v154 offset:36864
	ds_read_b128 v[200:203], v154 offset:38912
	ds_read_b128 v[168:171], v154 offset:33792
	ds_read_b128 v[176:179], v154 offset:35840
	ds_read_b128 v[196:199], v154 offset:37888
	ds_read_b128 v[204:207], v154 offset:39936
	global_load_lds_dwordx4 v[208:209], off
	v_lshl_add_u64 v[208:209], s[22:23], 0, v[132:133]
	s_mov_b32 m0, s46
	s_nop 0
	global_load_lds_dwordx4 v[208:209], off
	s_waitcnt lgkmcnt(8)
	s_barrier
	s_waitcnt lgkmcnt(4)
	s_setprio 1
	s_waitcnt lgkmcnt(4)
	v_mfma_f32_16x16x32_bf16 v[126:129], v[144:147], v[164:167], v[126:129]
	v_mfma_f32_16x16x32_bf16 v[122:125], v[156:159], v[164:167], v[122:125]
	v_mfma_f32_16x16x32_bf16 v[118:121], v[144:147], v[172:175], v[118:121]
	v_mfma_f32_16x16x32_bf16 v[114:117], v[156:159], v[172:175], v[114:117]
	v_mfma_f32_16x16x32_bf16 v[102:105], v[144:147], v[192:195], v[102:105]
	v_mfma_f32_16x16x32_bf16 v[98:101], v[156:159], v[192:195], v[98:101]
	v_mfma_f32_16x16x32_bf16 v[86:89], v[144:147], v[200:203], v[86:89]
	v_mfma_f32_16x16x32_bf16 v[82:85], v[156:159], v[200:203], v[82:85]
	s_waitcnt lgkmcnt(0)
	v_mfma_f32_16x16x32_bf16 v[126:129], v[148:151], v[168:171], v[126:129]
	v_mfma_f32_16x16x32_bf16 v[122:125], v[160:163], v[168:171], v[122:125]
	v_mfma_f32_16x16x32_bf16 v[118:121], v[148:151], v[176:179], v[118:121]
	v_mfma_f32_16x16x32_bf16 v[114:117], v[160:163], v[176:179], v[114:117]
	v_mfma_f32_16x16x32_bf16 v[102:105], v[148:151], v[196:199], v[102:105]
	v_mfma_f32_16x16x32_bf16 v[98:101], v[160:163], v[196:199], v[98:101]
	v_mfma_f32_16x16x32_bf16 v[86:89], v[148:151], v[204:207], v[86:89]
	v_mfma_f32_16x16x32_bf16 v[82:85], v[160:163], v[204:207], v[82:85]
	s_setprio 0
	s_barrier
	s_add_i32 s22, 0, 0x1c000
	s_add_i32 s23, s56, s28
	v_add_u32_e32 v155, s22, v139
	v_lshl_add_u64 v[152:153], v[152:153], 0, s[78:79]
	s_mov_b32 m0, s23
	ds_read_b128 v[208:211], v155
	ds_read_b128 v[224:227], v155 offset:1024
	ds_read_b128 v[228:231], v155 offset:2048
	ds_read_b128 v[232:235], v155 offset:3072
	global_load_lds_dwordx4 v[152:153], off
	v_lshl_add_u64 v[152:153], v[212:213], 0, s[78:79]
	s_add_i32 m0, s23, 0x2000
	s_nop 0
	global_load_lds_dwordx4 v[152:153], off
	s_barrier
	s_waitcnt lgkmcnt(0)
	s_setprio 1
	s_waitcnt lgkmcnt(0)
	v_mfma_f32_16x16x32_bf16 v[110:113], v[208:211], v[164:167], v[110:113]
	v_mfma_f32_16x16x32_bf16 v[106:109], v[228:231], v[164:167], v[106:109]
	v_mfma_f32_16x16x32_bf16 v[94:97], v[208:211], v[172:175], v[94:97]
	v_mfma_f32_16x16x32_bf16 v[90:93], v[228:231], v[172:175], v[90:93]
	v_mfma_f32_16x16x32_bf16 v[78:81], v[208:211], v[192:195], v[78:81]
	v_mfma_f32_16x16x32_bf16 v[74:77], v[228:231], v[192:195], v[74:77]
	v_mfma_f32_16x16x32_bf16 v[70:73], v[208:211], v[200:203], v[70:73]
	v_mfma_f32_16x16x32_bf16 v[66:69], v[228:231], v[200:203], v[66:69]
	v_mfma_f32_16x16x32_bf16 v[110:113], v[224:227], v[168:171], v[110:113]
	v_mfma_f32_16x16x32_bf16 v[106:109], v[232:235], v[168:171], v[106:109]
	v_mfma_f32_16x16x32_bf16 v[94:97], v[224:227], v[176:179], v[94:97]
	v_mfma_f32_16x16x32_bf16 v[90:93], v[232:235], v[176:179], v[90:93]
	v_mfma_f32_16x16x32_bf16 v[78:81], v[224:227], v[196:199], v[78:81]
	v_mfma_f32_16x16x32_bf16 v[74:77], v[232:235], v[196:199], v[74:77]
	v_mfma_f32_16x16x32_bf16 v[70:73], v[224:227], v[204:207], v[70:73]
	v_mfma_f32_16x16x32_bf16 v[66:69], v[232:235], v[204:207], v[66:69]
	s_setprio 0
	s_mov_b32 m0, s47
	v_lshl_add_u64 v[152:153], v[236:237], 0, s[78:79]
	s_barrier
	ds_read_b128 v[164:167], v154 offset:49152
	ds_read_b128 v[172:175], v154 offset:51200
	ds_read_b128 v[192:195], v154 offset:53248
	ds_read_b128 v[200:203], v154 offset:55296
	ds_read_b128 v[168:171], v154 offset:50176
	ds_read_b128 v[176:179], v154 offset:52224
	ds_read_b128 v[196:199], v154 offset:54272
	ds_read_b128 v[204:207], v154 offset:56320
	global_load_lds_dwordx4 v[152:153], off
	v_lshl_add_u64 v[152:153], v[238:239], 0, s[78:79]
	s_mov_b32 m0, s48
	s_nop 0
	global_load_lds_dwordx4 v[152:153], off
	s_waitcnt vmcnt(10)
	s_barrier
	s_waitcnt lgkmcnt(4)
	s_setprio 1
	s_waitcnt lgkmcnt(4)
	v_mfma_f32_16x16x32_bf16 v[62:65], v[144:147], v[164:167], v[62:65]
	v_mfma_f32_16x16x32_bf16 v[58:61], v[156:159], v[164:167], v[58:61]
	v_mfma_f32_16x16x32_bf16 v[54:57], v[144:147], v[172:175], v[54:57]
	v_mfma_f32_16x16x32_bf16 v[50:53], v[156:159], v[172:175], v[50:53]
	v_mfma_f32_16x16x32_bf16 v[38:41], v[144:147], v[192:195], v[38:41]
	v_mfma_f32_16x16x32_bf16 v[34:37], v[156:159], v[192:195], v[34:37]
	v_mfma_f32_16x16x32_bf16 v[22:25], v[144:147], v[200:203], v[22:25]
	v_mfma_f32_16x16x32_bf16 v[18:21], v[156:159], v[200:203], v[18:21]
	s_waitcnt lgkmcnt(0)
	v_mfma_f32_16x16x32_bf16 v[62:65], v[148:151], v[168:171], v[62:65]
	v_mfma_f32_16x16x32_bf16 v[58:61], v[160:163], v[168:171], v[58:61]
	v_mfma_f32_16x16x32_bf16 v[54:57], v[148:151], v[176:179], v[54:57]
	v_mfma_f32_16x16x32_bf16 v[50:53], v[160:163], v[176:179], v[50:53]
	v_mfma_f32_16x16x32_bf16 v[38:41], v[148:151], v[196:199], v[38:41]
	v_mfma_f32_16x16x32_bf16 v[34:37], v[160:163], v[196:199], v[34:37]
	v_mfma_f32_16x16x32_bf16 v[22:25], v[148:151], v[204:207], v[22:25]
	v_mfma_f32_16x16x32_bf16 v[18:21], v[160:163], v[204:207], v[18:21]
	s_setprio 0
	s_barrier
	s_add_u32 s20, s20, 0x80080
	s_addc_u32 s21, s21, 0
	s_add_i32 s22, s22, s28
	v_lshl_add_u64 v[144:145], s[20:21], 0, v[134:135]
	s_mov_b32 m0, s22
	s_nop 0
	global_load_lds_dwordx4 v[144:145], off
	v_lshl_add_u64 v[144:145], s[20:21], 0, v[130:131]
	s_add_i32 m0, s22, 0x2000
	s_nop 0
	global_load_lds_dwordx4 v[144:145], off
	v_add_u32_e32 v152, 0x10000, v139
	ds_read_b128 v[144:147], v152
	ds_read_b128 v[148:151], v152 offset:1024
	ds_read_b128 v[156:159], v152 offset:2048
	ds_read_b128 v[160:163], v152 offset:3072
	s_waitcnt vmcnt(6)
	s_barrier
	s_setprio 1
	v_mfma_f32_16x16x32_bf16 v[46:49], v[208:211], v[164:167], v[46:49]
	v_mfma_f32_16x16x32_bf16 v[42:45], v[228:231], v[164:167], v[42:45]
	v_mfma_f32_16x16x32_bf16 v[30:33], v[208:211], v[172:175], v[30:33]
	v_mfma_f32_16x16x32_bf16 v[26:29], v[228:231], v[172:175], v[26:29]
	v_mfma_f32_16x16x32_bf16 v[14:17], v[208:211], v[192:195], v[14:17]
	v_mfma_f32_16x16x32_bf16 v[10:13], v[228:231], v[192:195], v[10:13]
	v_mfma_f32_16x16x32_bf16 v[6:9], v[208:211], v[200:203], v[6:9]
	v_mfma_f32_16x16x32_bf16 v[2:5], v[228:231], v[200:203], v[2:5]
	v_mfma_f32_16x16x32_bf16 v[46:49], v[224:227], v[168:171], v[46:49]
	v_mfma_f32_16x16x32_bf16 v[42:45], v[232:235], v[168:171], v[42:45]
	v_mfma_f32_16x16x32_bf16 v[30:33], v[224:227], v[176:179], v[30:33]
	v_mfma_f32_16x16x32_bf16 v[26:29], v[232:235], v[176:179], v[26:29]
	v_mfma_f32_16x16x32_bf16 v[14:17], v[224:227], v[196:199], v[14:17]
	v_mfma_f32_16x16x32_bf16 v[10:13], v[232:235], v[196:199], v[10:13]
	v_mfma_f32_16x16x32_bf16 v[6:9], v[224:227], v[204:207], v[6:9]
	v_mfma_f32_16x16x32_bf16 v[2:5], v[232:235], v[204:207], v[2:5]
	s_setprio 0
	s_add_i32 s55, s55, 2
	s_add_u32 s18, s18, 0x100
	s_addc_u32 s19, s19, 0
	s_add_u32 s53, s53, 0x100
	s_addc_u32 s54, s54, 0
	s_cmp_gt_u32 s55, 29
	s_barrier
	s_cbranch_scc0 .LBB0_526
	s_waitcnt lgkmcnt(0)
	v_lshl_add_u32 v152, s36, 8, v1
	v_or_b32_e32 v150, 16, v152
	v_or_b32_e32 v148, 32, v152
	v_or_b32_e32 v146, 48, v152
	s_mov_b64 s[18:19], -1
	s_cmp_lt_i32 s50, 8
	v_ashrrev_i32_e32 v153, 31, v152
	v_lshlrev_b32_e32 v144, 1, v138
	v_ashrrev_i32_e32 v151, 31, v150
	v_ashrrev_i32_e32 v149, 31, v148
	v_ashrrev_i32_e32 v147, 31, v146
	s_cbranch_scc1 .LBB0_529
	s_lshl_b32 s18, s50, 7
	s_add_i32 s36, s18, 0xfffffc00
	v_lshlrev_b64 v[156:157], 12, v[152:153]
	v_lshl_add_u64 v[156:157], s[72:73], 0, v[156:157]
	s_lshl_b64 s[18:19], s[36:37], 1
	v_lshl_add_u64 v[156:157], v[156:157], 0, s[18:19]
	v_mov_b32_e32 v145, v0
	v_lshl_add_u64 v[160:161], v[156:157], 0, v[144:145]
	v_pk_mul_f32 v[158:159], v[128:129], v[112:113]
	v_pk_mul_f32 v[156:157], v[126:127], v[110:111]
	v_pk_mul_f32 v[162:163], v[124:125], v[108:109]
	v_pk_mul_f32 v[164:165], v[122:123], v[106:107]
	v_cvt_pk_bf16_f32 v156, v156, v157
	v_cvt_pk_bf16_f32 v157, v158, v159
	v_cvt_pk_bf16_f32 v158, v164, v165
	v_cvt_pk_bf16_f32 v159, v162, v163
	global_store_dwordx4 v[160:161], v[156:159], off
	v_pk_mul_f32 v[164:165], v[116:117], v[92:93]
	v_pk_mul_f32 v[166:167], v[114:115], v[90:91]
	v_lshlrev_b64 v[156:157], 12, v[150:151]
	v_lshl_add_u64 v[156:157], s[72:73], 0, v[156:157]
	v_lshl_add_u64 v[156:157], v[156:157], 0, s[18:19]
	v_lshl_add_u64 v[162:163], v[156:157], 0, v[144:145]
	v_pk_mul_f32 v[158:159], v[120:121], v[96:97]
	v_pk_mul_f32 v[156:157], v[118:119], v[94:95]
	s_nop 0
	v_cvt_pk_bf16_f32 v156, v156, v157
	v_cvt_pk_bf16_f32 v157, v158, v159
	v_cvt_pk_bf16_f32 v158, v166, v167
	v_cvt_pk_bf16_f32 v159, v164, v165
	global_store_dwordx4 v[162:163], v[156:159], off
	v_pk_mul_f32 v[164:165], v[100:101], v[76:77]
	v_pk_mul_f32 v[166:167], v[98:99], v[74:75]
	v_lshlrev_b64 v[156:157], 12, v[148:149]
	v_lshl_add_u64 v[156:157], s[72:73], 0, v[156:157]
	v_lshl_add_u64 v[156:157], v[156:157], 0, s[18:19]
	v_lshl_add_u64 v[162:163], v[156:157], 0, v[144:145]
	v_pk_mul_f32 v[158:159], v[104:105], v[80:81]
	v_pk_mul_f32 v[156:157], v[102:103], v[78:79]
	s_nop 0
	v_cvt_pk_bf16_f32 v156, v156, v157
	v_cvt_pk_bf16_f32 v157, v158, v159
	v_cvt_pk_bf16_f32 v158, v166, v167
	v_cvt_pk_bf16_f32 v159, v164, v165
	global_store_dwordx4 v[162:163], v[156:159], off
	v_pk_mul_f32 v[164:165], v[84:85], v[68:69]
	v_pk_mul_f32 v[166:167], v[82:83], v[66:67]
	v_lshlrev_b64 v[156:157], 12, v[146:147]
	v_lshl_add_u64 v[156:157], s[72:73], 0, v[156:157]
	v_lshl_add_u64 v[156:157], v[156:157], 0, s[18:19]
	v_lshl_add_u64 v[162:163], v[156:157], 0, v[144:145]
	v_pk_mul_f32 v[158:159], v[88:89], v[72:73]
	v_pk_mul_f32 v[156:157], v[86:87], v[70:71]
	s_mov_b32 s18, 0x80000
	v_cvt_pk_bf16_f32 v156, v156, v157
	v_cvt_pk_bf16_f32 v157, v158, v159
	v_cvt_pk_bf16_f32 v158, v166, v167
	v_cvt_pk_bf16_f32 v159, v164, v165
	global_store_dwordx4 v[162:163], v[156:159], off
	v_pk_mul_f32 v[162:163], v[60:61], v[44:45]
	v_pk_mul_f32 v[164:165], v[58:59], v[42:43]
	v_pk_mul_f32 v[158:159], v[64:65], v[48:49]
	v_pk_mul_f32 v[156:157], v[62:63], v[46:47]
	s_nop 0
	v_cvt_pk_bf16_f32 v156, v156, v157
	v_cvt_pk_bf16_f32 v157, v158, v159
	v_cvt_pk_bf16_f32 v159, v162, v163
	v_add_co_u32_e32 v162, vcc, s18, v160
	v_cvt_pk_bf16_f32 v158, v164, v165
	s_nop 0
	v_addc_co_u32_e32 v163, vcc, 0, v161, vcc
	global_store_dwordx4 v[162:163], v[156:159], off
	v_pk_mul_f32 v[162:163], v[52:53], v[28:29]
	s_mov_b32 s18, 0x90000
	v_pk_mul_f32 v[158:159], v[56:57], v[32:33]
	v_pk_mul_f32 v[156:157], v[54:55], v[30:31]
	v_pk_mul_f32 v[164:165], v[50:51], v[26:27]
	v_cvt_pk_bf16_f32 v156, v156, v157
	v_cvt_pk_bf16_f32 v157, v158, v159
	v_cvt_pk_bf16_f32 v159, v162, v163
	v_add_co_u32_e32 v162, vcc, s18, v160
	v_cvt_pk_bf16_f32 v158, v164, v165
	s_nop 0
	v_addc_co_u32_e32 v163, vcc, 0, v161, vcc
	global_store_dwordx4 v[162:163], v[156:159], off
	v_pk_mul_f32 v[162:163], v[36:37], v[12:13]
	s_mov_b32 s18, 0xa0000
	v_pk_mul_f32 v[158:159], v[40:41], v[16:17]
	v_pk_mul_f32 v[156:157], v[38:39], v[14:15]
	v_pk_mul_f32 v[164:165], v[34:35], v[10:11]
	v_cvt_pk_bf16_f32 v156, v156, v157
	v_cvt_pk_bf16_f32 v157, v158, v159
	v_cvt_pk_bf16_f32 v159, v162, v163
	v_add_co_u32_e32 v162, vcc, s18, v160
	v_cvt_pk_bf16_f32 v158, v164, v165
	s_nop 0
	v_addc_co_u32_e32 v163, vcc, 0, v161, vcc
	global_store_dwordx4 v[162:163], v[156:159], off
	v_pk_mul_f32 v[162:163], v[20:21], v[4:5]
	v_pk_mul_f32 v[164:165], v[18:19], v[2:3]
	v_pk_mul_f32 v[158:159], v[24:25], v[8:9]
	v_pk_mul_f32 v[156:157], v[22:23], v[6:7]
	v_add_co_u32_e32 v160, vcc, 0xb0000, v160
	v_cvt_pk_bf16_f32 v156, v156, v157
	v_cvt_pk_bf16_f32 v157, v158, v159
	v_cvt_pk_bf16_f32 v158, v164, v165
	v_cvt_pk_bf16_f32 v159, v162, v163
	v_addc_co_u32_e32 v161, vcc, 0, v161, vcc
	s_mov_b64 s[18:19], 0
	global_store_dwordx4 v[160:161], v[156:159], off

.LBB0_649:
	s_add_u32 s18, s38, vcc_lo
	s_addc_u32 s19, s39, vcc_hi
	s_add_u32 s18, s18, 0x100
	s_addc_u32 s19, s19, 0
	s_add_u32 s57, s50, vcc_lo
	s_addc_u32 s58, s51, vcc_hi
	s_add_i32 s59, 0, 0x10000
	s_cmpk_eq_i32 vcc_lo, 0xf00
	s_cselect_b32 s23, s52, s19
	s_cselect_b32 s22, s53, s18
	s_cselect_b32 s19, s54, s58
	s_cselect_b32 s18, s55, s57
	v_lshl_add_u64 v[162:163], v[142:143], 0, vcc
	s_add_i32 m0, s28, 0xc000
	ds_read_b128 v[170:173], v148
	ds_read_b128 v[192:195], v148 offset:2048
	ds_read_b128 v[200:203], v148 offset:4096
	ds_read_b128 v[208:211], v148 offset:6144
	ds_read_b128 v[174:177], v148 offset:1024
	ds_read_b128 v[196:199], v148 offset:3072
	ds_read_b128 v[204:207], v148 offset:5120
	ds_read_b128 v[224:227], v148 offset:7168
	global_load_lds_dwordx4 v[162:163], off
	v_lshl_add_u64 v[162:163], v[144:145], 0, vcc
	s_add_i32 m0, s28, 0xe000
	s_nop 0
	global_load_lds_dwordx4 v[162:163], off
	s_waitcnt lgkmcnt(8)
	s_barrier
	s_waitcnt lgkmcnt(4)
	s_setprio 1
	s_waitcnt lgkmcnt(4)
	v_mfma_f32_16x16x32_bf16 v[90:93], v[150:153], v[170:173], v[90:93]
	v_mfma_f32_16x16x32_bf16 v[94:97], v[158:161], v[170:173], v[94:97]
	v_mfma_f32_16x16x32_bf16 v[102:105], v[150:153], v[192:195], v[102:105]
	v_mfma_f32_16x16x32_bf16 v[106:109], v[158:161], v[192:195], v[106:109]
	v_mfma_f32_16x16x32_bf16 v[114:117], v[150:153], v[200:203], v[114:117]
	v_mfma_f32_16x16x32_bf16 v[118:121], v[158:161], v[200:203], v[118:121]
	v_mfma_f32_16x16x32_bf16 v[122:125], v[150:153], v[208:211], v[122:125]
	v_mfma_f32_16x16x32_bf16 v[126:129], v[158:161], v[208:211], v[126:129]
	s_waitcnt lgkmcnt(0)
	v_mfma_f32_16x16x32_bf16 v[90:93], v[154:157], v[174:177], v[90:93]
	v_mfma_f32_16x16x32_bf16 v[94:97], v[166:169], v[174:177], v[94:97]
	v_mfma_f32_16x16x32_bf16 v[102:105], v[154:157], v[196:199], v[102:105]
	v_mfma_f32_16x16x32_bf16 v[106:109], v[166:169], v[196:199], v[106:109]
	v_mfma_f32_16x16x32_bf16 v[114:117], v[154:157], v[204:207], v[114:117]
	v_mfma_f32_16x16x32_bf16 v[118:121], v[166:169], v[204:207], v[118:121]
	v_mfma_f32_16x16x32_bf16 v[122:125], v[154:157], v[224:227], v[122:125]
	v_mfma_f32_16x16x32_bf16 v[126:129], v[166:169], v[224:227], v[126:129]
	s_setprio 0
	s_barrier
	s_add_i32 s57, 0, 0x14000
	s_add_i32 s58, s59, s85
	v_add_u32_e32 v149, s57, v147
	v_lshl_add_u64 v[162:163], s[18:19], 0, v[134:135]
	s_mov_b32 m0, s58
	ds_read_b128 v[228:231], v149
	ds_read_b128 v[232:235], v149 offset:1024
	ds_read_b128 v[236:239], v149 offset:2048
	ds_read_b128 v[240:243], v149 offset:3072
	global_load_lds_dwordx4 v[162:163], off
	v_lshl_add_u64 v[178:179], s[18:19], 0, v[130:131]
	s_add_i32 m0, s58, 0x2000
	s_nop 0
	global_load_lds_dwordx4 v[178:179], off
	s_barrier
	s_waitcnt lgkmcnt(0)
	s_setprio 1
	s_waitcnt lgkmcnt(0)
	v_mfma_f32_16x16x32_bf16 v[10:13], v[228:231], v[170:173], v[10:13]
	v_mfma_f32_16x16x32_bf16 v[14:17], v[236:239], v[170:173], v[14:17]
	v_mfma_f32_16x16x32_bf16 v[26:29], v[228:231], v[192:195], v[26:29]
	v_mfma_f32_16x16x32_bf16 v[38:41], v[236:239], v[192:195], v[38:41]
	v_mfma_f32_16x16x32_bf16 v[58:61], v[228:231], v[200:203], v[58:61]
	v_mfma_f32_16x16x32_bf16 v[62:65], v[236:239], v[200:203], v[62:65]
	v_mfma_f32_16x16x32_bf16 v[74:77], v[228:231], v[208:211], v[74:77]
	v_mfma_f32_16x16x32_bf16 v[78:81], v[236:239], v[208:211], v[78:81]
	v_mfma_f32_16x16x32_bf16 v[10:13], v[232:235], v[174:177], v[10:13]
	v_mfma_f32_16x16x32_bf16 v[14:17], v[240:243], v[174:177], v[14:17]
	v_mfma_f32_16x16x32_bf16 v[26:29], v[232:235], v[196:199], v[26:29]
	v_mfma_f32_16x16x32_bf16 v[38:41], v[240:243], v[196:199], v[38:41]
	v_mfma_f32_16x16x32_bf16 v[58:61], v[232:235], v[204:207], v[58:61]
	v_mfma_f32_16x16x32_bf16 v[62:65], v[240:243], v[204:207], v[62:65]
	v_mfma_f32_16x16x32_bf16 v[74:77], v[232:235], v[224:227], v[74:77]
	v_mfma_f32_16x16x32_bf16 v[78:81], v[240:243], v[224:227], v[78:81]
	s_setprio 0
	s_mov_b32 m0, s28
	v_lshl_add_u64 v[212:213], s[22:23], 0, v[136:137]
	s_barrier
	ds_read_b128 v[170:173], v148 offset:16384
	ds_read_b128 v[192:195], v148 offset:18432
	ds_read_b128 v[200:203], v148 offset:20480
	ds_read_b128 v[208:211], v148 offset:22528
	ds_read_b128 v[174:177], v148 offset:17408
	ds_read_b128 v[196:199], v148 offset:19456
	ds_read_b128 v[204:207], v148 offset:21504
	ds_read_b128 v[224:227], v148 offset:23552
	global_load_lds_dwordx4 v[212:213], off
	v_lshl_add_u64 v[244:245], s[22:23], 0, v[132:133]
	s_mov_b32 m0, s29
	s_nop 0
	global_load_lds_dwordx4 v[244:245], off
	s_waitcnt vmcnt(10)
	s_barrier
	s_waitcnt lgkmcnt(4)
	s_setprio 1
	s_waitcnt lgkmcnt(4)
	v_mfma_f32_16x16x32_bf16 v[110:113], v[150:153], v[170:173], v[110:113]
	v_mfma_f32_16x16x32_bf16 v[98:101], v[158:161], v[170:173], v[98:101]
	v_mfma_f32_16x16x32_bf16 v[82:85], v[150:153], v[192:195], v[82:85]
	v_mfma_f32_16x16x32_bf16 v[66:69], v[158:161], v[192:195], v[66:69]
	v_mfma_f32_16x16x32_bf16 v[50:53], v[150:153], v[200:203], v[50:53]
	v_mfma_f32_16x16x32_bf16 v[42:45], v[158:161], v[200:203], v[42:45]
	v_mfma_f32_16x16x32_bf16 v[30:33], v[150:153], v[208:211], v[30:33]
	v_mfma_f32_16x16x32_bf16 v[18:21], v[158:161], v[208:211], v[18:21]
	s_waitcnt lgkmcnt(0)
	v_mfma_f32_16x16x32_bf16 v[110:113], v[154:157], v[174:177], v[110:113]
	v_mfma_f32_16x16x32_bf16 v[98:101], v[166:169], v[174:177], v[98:101]
	v_mfma_f32_16x16x32_bf16 v[82:85], v[154:157], v[196:199], v[82:85]
	v_mfma_f32_16x16x32_bf16 v[66:69], v[166:169], v[196:199], v[66:69]
	v_mfma_f32_16x16x32_bf16 v[50:53], v[154:157], v[204:207], v[50:53]
	v_mfma_f32_16x16x32_bf16 v[42:45], v[166:169], v[204:207], v[42:45]
	v_mfma_f32_16x16x32_bf16 v[30:33], v[154:157], v[224:227], v[30:33]
	v_mfma_f32_16x16x32_bf16 v[18:21], v[166:169], v[224:227], v[18:21]
	s_setprio 0
	s_barrier
	s_add_u32 s58, s18, 0x80000
	s_addc_u32 s59, s19, 0
	s_add_i32 s57, s57, s85
	v_lshl_add_u64 v[150:151], s[58:59], 0, v[134:135]
	s_mov_b32 m0, s57
	s_nop 0
	global_load_lds_dwordx4 v[150:151], off
	v_lshl_add_u64 v[150:151], s[58:59], 0, v[130:131]
	s_add_i32 m0, s57, 0x2000
	s_nop 0
	global_load_lds_dwordx4 v[150:151], off
	v_add_u32_e32 v149, 0x18000, v147
	ds_read_b128 v[150:153], v149
	ds_read_b128 v[154:157], v149 offset:1024
	ds_read_b128 v[158:161], v149 offset:2048
	ds_read_b128 v[166:169], v149 offset:3072
	s_waitcnt vmcnt(6)
	s_barrier
	s_setprio 1
	v_mfma_f32_16x16x32_bf16 v[86:89], v[228:231], v[170:173], v[86:89]
	v_mfma_f32_16x16x32_bf16 v[70:73], v[236:239], v[170:173], v[70:73]
	v_mfma_f32_16x16x32_bf16 v[54:57], v[228:231], v[192:195], v[54:57]
	v_mfma_f32_16x16x32_bf16 v[46:49], v[236:239], v[192:195], v[46:49]
	v_mfma_f32_16x16x32_bf16 v[34:37], v[228:231], v[200:203], v[34:37]
	v_mfma_f32_16x16x32_bf16 v[22:25], v[236:239], v[200:203], v[22:25]
	v_mfma_f32_16x16x32_bf16 v[6:9], v[228:231], v[208:211], v[6:9]
	v_mfma_f32_16x16x32_bf16 v[2:5], v[236:239], v[208:211], v[2:5]
	v_mfma_f32_16x16x32_bf16 v[86:89], v[232:235], v[174:177], v[86:89]
	v_mfma_f32_16x16x32_bf16 v[70:73], v[240:243], v[174:177], v[70:73]
	v_mfma_f32_16x16x32_bf16 v[54:57], v[232:235], v[196:199], v[54:57]
	v_mfma_f32_16x16x32_bf16 v[46:49], v[240:243], v[196:199], v[46:49]
	v_mfma_f32_16x16x32_bf16 v[34:37], v[232:235], v[204:207], v[34:37]
	v_mfma_f32_16x16x32_bf16 v[22:25], v[240:243], v[204:207], v[22:25]
	v_mfma_f32_16x16x32_bf16 v[6:9], v[232:235], v[224:227], v[6:9]
	v_mfma_f32_16x16x32_bf16 v[2:5], v[240:243], v[224:227], v[2:5]
	s_setprio 0
	s_add_i32 s57, 0, 0x18000
	s_barrier
	s_add_u32 s22, s22, 0x80000
	s_addc_u32 s23, s23, 0
	s_mov_b32 m0, s97
	v_lshl_add_u64 v[228:229], s[22:23], 0, v[136:137]
	ds_read_b128 v[170:173], v148 offset:32768
	ds_read_b128 v[192:195], v148 offset:34816
	ds_read_b128 v[200:203], v148 offset:36864
	ds_read_b128 v[208:211], v148 offset:38912
	ds_read_b128 v[174:177], v148 offset:33792
	ds_read_b128 v[196:199], v148 offset:35840
	ds_read_b128 v[204:207], v148 offset:37888
	ds_read_b128 v[224:227], v148 offset:39936
	global_load_lds_dwordx4 v[228:229], off
	v_lshl_add_u64 v[228:229], s[22:23], 0, v[132:133]
	s_mov_b32 m0, s44
	s_nop 0
	global_load_lds_dwordx4 v[228:229], off
	s_waitcnt lgkmcnt(8)
	s_barrier
	s_waitcnt lgkmcnt(4)
	s_setprio 1
	s_waitcnt lgkmcnt(4)
	v_mfma_f32_16x16x32_bf16 v[90:93], v[150:153], v[170:173], v[90:93]
	v_mfma_f32_16x16x32_bf16 v[94:97], v[158:161], v[170:173], v[94:97]
	v_mfma_f32_16x16x32_bf16 v[102:105], v[150:153], v[192:195], v[102:105]
	v_mfma_f32_16x16x32_bf16 v[106:109], v[158:161], v[192:195], v[106:109]
	v_mfma_f32_16x16x32_bf16 v[114:117], v[150:153], v[200:203], v[114:117]
	v_mfma_f32_16x16x32_bf16 v[118:121], v[158:161], v[200:203], v[118:121]
	v_mfma_f32_16x16x32_bf16 v[122:125], v[150:153], v[208:211], v[122:125]
	v_mfma_f32_16x16x32_bf16 v[126:129], v[158:161], v[208:211], v[126:129]
	s_waitcnt lgkmcnt(0)
	v_mfma_f32_16x16x32_bf16 v[90:93], v[154:157], v[174:177], v[90:93]
	v_mfma_f32_16x16x32_bf16 v[94:97], v[166:169], v[174:177], v[94:97]
	v_mfma_f32_16x16x32_bf16 v[102:105], v[154:157], v[196:199], v[102:105]
	v_mfma_f32_16x16x32_bf16 v[106:109], v[166:169], v[196:199], v[106:109]
	v_mfma_f32_16x16x32_bf16 v[114:117], v[154:157], v[204:207], v[114:117]
	v_mfma_f32_16x16x32_bf16 v[118:121], v[166:169], v[204:207], v[118:121]
	v_mfma_f32_16x16x32_bf16 v[122:125], v[154:157], v[224:227], v[122:125]
	v_mfma_f32_16x16x32_bf16 v[126:129], v[166:169], v[224:227], v[126:129]
	s_setprio 0
	s_barrier
	s_add_i32 s22, 0, 0x1c000
	s_add_i32 s23, s57, s85
	v_add_u32_e32 v149, s22, v147
	v_lshl_add_u64 v[162:163], v[162:163], 0, s[78:79]
	s_mov_b32 m0, s23
	ds_read_b128 v[228:231], v149
	ds_read_b128 v[232:235], v149 offset:1024
	ds_read_b128 v[236:239], v149 offset:2048
	ds_read_b128 v[240:243], v149 offset:3072
	global_load_lds_dwordx4 v[162:163], off
	v_lshl_add_u64 v[162:163], v[178:179], 0, s[78:79]
	s_add_i32 m0, s23, 0x2000
	s_nop 0
	global_load_lds_dwordx4 v[162:163], off
	s_barrier
	s_waitcnt lgkmcnt(0)
	s_setprio 1
	s_waitcnt lgkmcnt(0)
	v_mfma_f32_16x16x32_bf16 v[10:13], v[228:231], v[170:173], v[10:13]
	v_mfma_f32_16x16x32_bf16 v[14:17], v[236:239], v[170:173], v[14:17]
	v_mfma_f32_16x16x32_bf16 v[26:29], v[228:231], v[192:195], v[26:29]
	v_mfma_f32_16x16x32_bf16 v[38:41], v[236:239], v[192:195], v[38:41]
	v_mfma_f32_16x16x32_bf16 v[58:61], v[228:231], v[200:203], v[58:61]
	v_mfma_f32_16x16x32_bf16 v[62:65], v[236:239], v[200:203], v[62:65]
	v_mfma_f32_16x16x32_bf16 v[74:77], v[228:231], v[208:211], v[74:77]
	v_mfma_f32_16x16x32_bf16 v[78:81], v[236:239], v[208:211], v[78:81]
	v_mfma_f32_16x16x32_bf16 v[10:13], v[232:235], v[174:177], v[10:13]
	v_mfma_f32_16x16x32_bf16 v[14:17], v[240:243], v[174:177], v[14:17]
	v_mfma_f32_16x16x32_bf16 v[26:29], v[232:235], v[196:199], v[26:29]
	v_mfma_f32_16x16x32_bf16 v[38:41], v[240:243], v[196:199], v[38:41]
	v_mfma_f32_16x16x32_bf16 v[58:61], v[232:235], v[204:207], v[58:61]
	v_mfma_f32_16x16x32_bf16 v[62:65], v[240:243], v[204:207], v[62:65]
	v_mfma_f32_16x16x32_bf16 v[74:77], v[232:235], v[224:227], v[74:77]
	v_mfma_f32_16x16x32_bf16 v[78:81], v[240:243], v[224:227], v[78:81]
	s_setprio 0
	s_mov_b32 m0, s46
	v_lshl_add_u64 v[162:163], v[212:213], 0, s[78:79]
	s_barrier
	ds_read_b128 v[170:173], v148 offset:49152
	ds_read_b128 v[192:195], v148 offset:51200
	ds_read_b128 v[200:203], v148 offset:53248
	ds_read_b128 v[208:211], v148 offset:55296
	ds_read_b128 v[174:177], v148 offset:50176
	ds_read_b128 v[196:199], v148 offset:52224
	ds_read_b128 v[204:207], v148 offset:54272
	ds_read_b128 v[224:227], v148 offset:56320
	global_load_lds_dwordx4 v[162:163], off
	v_lshl_add_u64 v[162:163], v[244:245], 0, s[78:79]
	s_mov_b32 m0, s47
	s_nop 0
	global_load_lds_dwordx4 v[162:163], off
	s_waitcnt vmcnt(10)
	s_barrier
	s_waitcnt lgkmcnt(4)
	s_setprio 1
	s_waitcnt lgkmcnt(4)
	v_mfma_f32_16x16x32_bf16 v[110:113], v[150:153], v[170:173], v[110:113]
	v_mfma_f32_16x16x32_bf16 v[98:101], v[158:161], v[170:173], v[98:101]
	v_mfma_f32_16x16x32_bf16 v[82:85], v[150:153], v[192:195], v[82:85]
	v_mfma_f32_16x16x32_bf16 v[66:69], v[158:161], v[192:195], v[66:69]
	v_mfma_f32_16x16x32_bf16 v[50:53], v[150:153], v[200:203], v[50:53]
	v_mfma_f32_16x16x32_bf16 v[42:45], v[158:161], v[200:203], v[42:45]
	v_mfma_f32_16x16x32_bf16 v[30:33], v[150:153], v[208:211], v[30:33]
	v_mfma_f32_16x16x32_bf16 v[18:21], v[158:161], v[208:211], v[18:21]
	s_waitcnt lgkmcnt(0)
	v_mfma_f32_16x16x32_bf16 v[110:113], v[154:157], v[174:177], v[110:113]
	v_mfma_f32_16x16x32_bf16 v[98:101], v[166:169], v[174:177], v[98:101]
	v_mfma_f32_16x16x32_bf16 v[82:85], v[154:157], v[196:199], v[82:85]
	v_mfma_f32_16x16x32_bf16 v[66:69], v[166:169], v[196:199], v[66:69]
	v_mfma_f32_16x16x32_bf16 v[50:53], v[154:157], v[204:207], v[50:53]
	v_mfma_f32_16x16x32_bf16 v[42:45], v[166:169], v[204:207], v[42:45]
	v_mfma_f32_16x16x32_bf16 v[30:33], v[154:157], v[224:227], v[30:33]
	v_mfma_f32_16x16x32_bf16 v[18:21], v[166:169], v[224:227], v[18:21]
	s_setprio 0
	s_barrier
	s_add_u32 s18, s18, 0x80080
	s_addc_u32 s19, s19, 0
	s_add_i32 s22, s22, s85
	v_lshl_add_u64 v[150:151], s[18:19], 0, v[134:135]
	s_mov_b32 m0, s22
	s_nop 0
	global_load_lds_dwordx4 v[150:151], off
	v_lshl_add_u64 v[150:151], s[18:19], 0, v[130:131]
	s_add_i32 m0, s22, 0x2000
	s_nop 0
	global_load_lds_dwordx4 v[150:151], off
	v_add_u32_e32 v149, 0x10000, v147
	ds_read_b128 v[150:153], v149
	ds_read_b128 v[154:157], v149 offset:1024
	ds_read_b128 v[158:161], v149 offset:2048
	ds_read_b128 v[166:169], v149 offset:3072
	s_waitcnt vmcnt(6)
	s_barrier
	s_setprio 1
	v_mfma_f32_16x16x32_bf16 v[86:89], v[228:231], v[170:173], v[86:89]
	v_mfma_f32_16x16x32_bf16 v[70:73], v[236:239], v[170:173], v[70:73]
	v_mfma_f32_16x16x32_bf16 v[54:57], v[228:231], v[192:195], v[54:57]
	v_mfma_f32_16x16x32_bf16 v[46:49], v[236:239], v[192:195], v[46:49]
	v_mfma_f32_16x16x32_bf16 v[34:37], v[228:231], v[200:203], v[34:37]
	v_mfma_f32_16x16x32_bf16 v[22:25], v[236:239], v[200:203], v[22:25]
	v_mfma_f32_16x16x32_bf16 v[6:9], v[228:231], v[208:211], v[6:9]
	v_mfma_f32_16x16x32_bf16 v[2:5], v[236:239], v[208:211], v[2:5]
	v_mfma_f32_16x16x32_bf16 v[86:89], v[232:235], v[174:177], v[86:89]
	v_mfma_f32_16x16x32_bf16 v[70:73], v[240:243], v[174:177], v[70:73]
	v_mfma_f32_16x16x32_bf16 v[54:57], v[232:235], v[196:199], v[54:57]
	v_mfma_f32_16x16x32_bf16 v[46:49], v[240:243], v[196:199], v[46:49]
	v_mfma_f32_16x16x32_bf16 v[34:37], v[232:235], v[204:207], v[34:37]
	v_mfma_f32_16x16x32_bf16 v[22:25], v[240:243], v[204:207], v[22:25]
	v_mfma_f32_16x16x32_bf16 v[6:9], v[232:235], v[224:227], v[6:9]
	v_mfma_f32_16x16x32_bf16 v[2:5], v[240:243], v[224:227], v[2:5]
	s_setprio 0
	s_add_i32 s56, s56, 2
	s_add_u32 vcc_lo, vcc_lo, 0x100
	s_addc_u32 vcc_hi, vcc_hi, 0
	s_cmp_gt_u32 s56, 29
	s_barrier
	s_cbranch_scc0 .LBB0_649
	s_waitcnt lgkmcnt(0)
	s_add_u32 s18, s50, 0xffffff00
	s_addc_u32 s19, s51, -1
	s_andn2_b64 vcc, exec, s[42:43]
	s_cbranch_vccnz .LBB0_652
	v_mov_b32_e32 v2, 0
	s_mov_b32 s84, s80
	s_mov_b32 s25, s82
	s_mov_b64 s[38:39], s[20:21]
	s_mov_b32 s48, s49
	v_mov_b32_e32 v3, v2
	v_mov_b32_e32 v4, v2
	v_mov_b32_e32 v5, v2
	v_mov_b32_e32 v6, v2
	v_mov_b32_e32 v7, v2
	v_mov_b32_e32 v8, v2
	v_mov_b32_e32 v9, v2
	v_mov_b32_e32 v22, v2
	v_mov_b32_e32 v23, v2
	v_mov_b32_e32 v24, v2
	v_mov_b32_e32 v25, v2
	v_mov_b32_e32 v34, v2
	v_mov_b32_e32 v35, v2
	v_mov_b32_e32 v36, v2
	v_mov_b32_e32 v37, v2
	v_mov_b32_e32 v46, v2
	v_mov_b32_e32 v47, v2
	v_mov_b32_e32 v48, v2
	v_mov_b32_e32 v49, v2
	v_mov_b32_e32 v54, v2
	v_mov_b32_e32 v55, v2
	v_mov_b32_e32 v56, v2
	v_mov_b32_e32 v57, v2
	v_mov_b32_e32 v70, v2
	v_mov_b32_e32 v71, v2
	v_mov_b32_e32 v72, v2
	v_mov_b32_e32 v73, v2
	v_mov_b32_e32 v86, v2
	v_mov_b32_e32 v87, v2
	v_mov_b32_e32 v88, v2
	v_mov_b32_e32 v89, v2
	v_mov_b32_e32 v18, v2
	v_mov_b32_e32 v19, v2
	v_mov_b32_e32 v20, v2
	v_mov_b32_e32 v21, v2
	v_mov_b32_e32 v30, v2
	v_mov_b32_e32 v31, v2
	v_mov_b32_e32 v32, v2
	v_mov_b32_e32 v33, v2
	v_mov_b32_e32 v42, v2
	v_mov_b32_e32 v43, v2
	v_mov_b32_e32 v44, v2
	v_mov_b32_e32 v45, v2
	v_mov_b32_e32 v50, v2
	v_mov_b32_e32 v51, v2
	v_mov_b32_e32 v52, v2
	v_mov_b32_e32 v53, v2
	v_mov_b32_e32 v66, v2
	v_mov_b32_e32 v67, v2
	v_mov_b32_e32 v68, v2
	v_mov_b32_e32 v69, v2
	v_mov_b32_e32 v82, v2
	v_mov_b32_e32 v83, v2
	v_mov_b32_e32 v84, v2
	v_mov_b32_e32 v85, v2
	v_mov_b32_e32 v98, v2
	v_mov_b32_e32 v99, v2
	v_mov_b32_e32 v100, v2
	v_mov_b32_e32 v101, v2
	v_mov_b32_e32 v110, v2
	v_mov_b32_e32 v111, v2
	v_mov_b32_e32 v112, v2
	v_mov_b32_e32 v113, v2
	v_mov_b32_e32 v78, v2
	v_mov_b32_e32 v79, v2
	v_mov_b32_e32 v80, v2
	v_mov_b32_e32 v81, v2
	v_mov_b32_e32 v74, v2
	v_mov_b32_e32 v75, v2
	v_mov_b32_e32 v76, v2
	v_mov_b32_e32 v77, v2
	v_mov_b32_e32 v62, v2
	v_mov_b32_e32 v63, v2
	v_mov_b32_e32 v64, v2
	v_mov_b32_e32 v65, v2
	v_mov_b32_e32 v58, v2
	v_mov_b32_e32 v59, v2
	v_mov_b32_e32 v60, v2
	v_mov_b32_e32 v61, v2
	v_mov_b32_e32 v38, v2
	v_mov_b32_e32 v39, v2
	v_mov_b32_e32 v40, v2
	v_mov_b32_e32 v41, v2
	v_mov_b32_e32 v26, v2
	v_mov_b32_e32 v27, v2
	v_mov_b32_e32 v28, v2
	v_mov_b32_e32 v29, v2
	v_mov_b32_e32 v14, v2
	v_mov_b32_e32 v15, v2
	v_mov_b32_e32 v16, v2
	v_mov_b32_e32 v17, v2
	v_mov_b32_e32 v10, v2
	v_mov_b32_e32 v11, v2
	v_mov_b32_e32 v12, v2
	v_mov_b32_e32 v13, v2
	v_mov_b32_e32 v126, v2
	v_mov_b32_e32 v127, v2
	v_mov_b32_e32 v128, v2
	v_mov_b32_e32 v129, v2
	v_mov_b32_e32 v122, v2
	v_mov_b32_e32 v123, v2
	v_mov_b32_e32 v124, v2
	v_mov_b32_e32 v125, v2
	v_mov_b32_e32 v118, v2
	v_mov_b32_e32 v119, v2
	v_mov_b32_e32 v120, v2
	v_mov_b32_e32 v121, v2
	v_mov_b32_e32 v114, v2
	v_mov_b32_e32 v115, v2
	v_mov_b32_e32 v116, v2
	v_mov_b32_e32 v117, v2
	v_mov_b32_e32 v106, v2
	v_mov_b32_e32 v107, v2
	v_mov_b32_e32 v108, v2
	v_mov_b32_e32 v109, v2
	v_mov_b32_e32 v102, v2
	v_mov_b32_e32 v103, v2
	v_mov_b32_e32 v104, v2
	v_mov_b32_e32 v105, v2
	v_mov_b32_e32 v94, v2
	v_mov_b32_e32 v95, v2
	v_mov_b32_e32 v96, v2
	v_mov_b32_e32 v97, v2
	v_mov_b32_e32 v90, v2
	v_mov_b32_e32 v91, v2
	v_mov_b32_e32 v92, v2
	v_mov_b32_e32 v93, v2
	s_andn2_b64 vcc, exec, s[0:1]
	s_cbranch_vccnz .LBB0_653
	s_branch .LBB0_654

.LBB0_749:
	s_add_u32 s20, s18, 0xfff80080
	s_addc_u32 s21, s19, -1
	s_add_i32 s58, 0, 0x10000
	s_cmp_eq_u32 s57, 28
	s_cselect_b32 s23, s39, s21
	s_cselect_b32 s22, s53, s20
	s_cselect_b32 s21, s31, s56
	s_cselect_b32 s20, s54, s55
	v_lshl_add_u64 v[212:213], s[18:19], 0, v[154:155]
	s_add_i32 m0, s44, 0xc000
	ds_read_b128 v[176:179], v158
	ds_read_b128 v[196:199], v158 offset:2048
	ds_read_b128 v[204:207], v158 offset:4096
	ds_read_b128 v[224:227], v158 offset:6144
	ds_read_b128 v[192:195], v158 offset:1024
	ds_read_b128 v[200:203], v158 offset:3072
	ds_read_b128 v[208:211], v158 offset:5120
	ds_read_b128 v[228:231], v158 offset:7168
	global_load_lds_dwordx4 v[212:213], off
	v_lshl_add_u64 v[212:213], s[18:19], 0, v[156:157]
	s_add_i32 m0, s44, 0xe000
	s_nop 0
	global_load_lds_dwordx4 v[212:213], off
	s_waitcnt lgkmcnt(8)
	s_barrier
	s_waitcnt lgkmcnt(4)
	s_setprio 1
	s_waitcnt lgkmcnt(4)
	v_mfma_f32_16x16x32_bf16 v[126:129], v[160:163], v[176:179], v[126:129]
	v_mfma_f32_16x16x32_bf16 v[122:125], v[168:171], v[176:179], v[122:125]
	v_mfma_f32_16x16x32_bf16 v[110:113], v[160:163], v[196:199], v[110:113]
	v_mfma_f32_16x16x32_bf16 v[106:109], v[168:171], v[196:199], v[106:109]
	v_mfma_f32_16x16x32_bf16 v[94:97], v[160:163], v[204:207], v[94:97]
	v_mfma_f32_16x16x32_bf16 v[90:93], v[168:171], v[204:207], v[90:93]
	v_mfma_f32_16x16x32_bf16 v[78:81], v[160:163], v[224:227], v[78:81]
	v_mfma_f32_16x16x32_bf16 v[74:77], v[168:171], v[224:227], v[74:77]
	s_waitcnt lgkmcnt(0)
	v_mfma_f32_16x16x32_bf16 v[126:129], v[164:167], v[192:195], v[126:129]
	v_mfma_f32_16x16x32_bf16 v[122:125], v[172:175], v[192:195], v[122:125]
	v_mfma_f32_16x16x32_bf16 v[110:113], v[164:167], v[200:203], v[110:113]
	v_mfma_f32_16x16x32_bf16 v[106:109], v[172:175], v[200:203], v[106:109]
	v_mfma_f32_16x16x32_bf16 v[94:97], v[164:167], v[208:211], v[94:97]
	v_mfma_f32_16x16x32_bf16 v[90:93], v[172:175], v[208:211], v[90:93]
	v_mfma_f32_16x16x32_bf16 v[78:81], v[164:167], v[228:231], v[78:81]
	v_mfma_f32_16x16x32_bf16 v[74:77], v[172:175], v[228:231], v[74:77]
	s_setprio 0
	s_barrier
	s_add_i32 s82, 0, 0x14000
	s_add_i32 s58, s58, s29
	v_add_u32_e32 v159, s82, v1
	v_lshl_add_u64 v[212:213], s[20:21], 0, v[134:135]
	s_mov_b32 m0, s58
	ds_read_b128 v[232:235], v159
	ds_read_b128 v[236:239], v159 offset:1024
	ds_read_b128 v[240:243], v159 offset:2048
	ds_read_b128 v[244:247], v159 offset:3072
	global_load_lds_dwordx4 v[212:213], off
	v_lshl_add_u64 v[248:249], s[20:21], 0, v[130:131]
	s_add_i32 m0, s58, 0x2000
	s_nop 0
	global_load_lds_dwordx4 v[248:249], off
	s_barrier
	s_waitcnt lgkmcnt(0)
	s_setprio 1
	s_waitcnt lgkmcnt(0)
	v_mfma_f32_16x16x32_bf16 v[118:121], v[232:235], v[176:179], v[118:121]
	v_mfma_f32_16x16x32_bf16 v[114:117], v[240:243], v[176:179], v[114:117]
	v_mfma_f32_16x16x32_bf16 v[102:105], v[232:235], v[196:199], v[102:105]
	v_mfma_f32_16x16x32_bf16 v[98:101], v[240:243], v[196:199], v[98:101]
	v_mfma_f32_16x16x32_bf16 v[86:89], v[232:235], v[204:207], v[86:89]
	v_mfma_f32_16x16x32_bf16 v[82:85], v[240:243], v[204:207], v[82:85]
	v_mfma_f32_16x16x32_bf16 v[70:73], v[232:235], v[224:227], v[70:73]
	v_mfma_f32_16x16x32_bf16 v[66:69], v[240:243], v[224:227], v[66:69]
	v_mfma_f32_16x16x32_bf16 v[118:121], v[236:239], v[192:195], v[118:121]
	v_mfma_f32_16x16x32_bf16 v[114:117], v[244:247], v[192:195], v[114:117]
	v_mfma_f32_16x16x32_bf16 v[102:105], v[236:239], v[200:203], v[102:105]
	v_mfma_f32_16x16x32_bf16 v[98:101], v[244:247], v[200:203], v[98:101]
	v_mfma_f32_16x16x32_bf16 v[86:89], v[236:239], v[208:211], v[86:89]
	v_mfma_f32_16x16x32_bf16 v[82:85], v[244:247], v[208:211], v[82:85]
	v_mfma_f32_16x16x32_bf16 v[70:73], v[236:239], v[228:231], v[70:73]
	v_mfma_f32_16x16x32_bf16 v[66:69], v[244:247], v[228:231], v[66:69]
	s_setprio 0
	s_mov_b32 m0, s44
	v_lshl_add_u64 v[250:251], s[22:23], 0, v[136:137]
	s_barrier
	ds_read_b128 v[176:179], v158 offset:16384
	ds_read_b128 v[196:199], v158 offset:18432
	ds_read_b128 v[204:207], v158 offset:20480
	ds_read_b128 v[224:227], v158 offset:22528
	ds_read_b128 v[192:195], v158 offset:17408
	ds_read_b128 v[200:203], v158 offset:19456
	ds_read_b128 v[208:211], v158 offset:21504
	ds_read_b128 v[228:231], v158 offset:23552
	global_load_lds_dwordx4 v[250:251], off
	v_lshl_add_u64 v[222:223], s[22:23], 0, v[132:133]
	s_mov_b32 m0, s45
	s_nop 0
	global_load_lds_dwordx4 v[222:223], off
	s_waitcnt vmcnt(10)
	s_barrier
	s_waitcnt lgkmcnt(4)
	s_setprio 1
	s_waitcnt lgkmcnt(4)
	v_mfma_f32_16x16x32_bf16 v[62:65], v[160:163], v[176:179], v[62:65]
	v_mfma_f32_16x16x32_bf16 v[58:61], v[168:171], v[176:179], v[58:61]
	v_mfma_f32_16x16x32_bf16 v[46:49], v[160:163], v[196:199], v[46:49]
	v_mfma_f32_16x16x32_bf16 v[42:45], v[168:171], v[196:199], v[42:45]
	v_mfma_f32_16x16x32_bf16 v[30:33], v[160:163], v[204:207], v[30:33]
	v_mfma_f32_16x16x32_bf16 v[26:29], v[168:171], v[204:207], v[26:29]
	v_mfma_f32_16x16x32_bf16 v[14:17], v[160:163], v[224:227], v[14:17]
	v_mfma_f32_16x16x32_bf16 v[10:13], v[168:171], v[224:227], v[10:13]
	s_waitcnt lgkmcnt(0)
	v_mfma_f32_16x16x32_bf16 v[62:65], v[164:167], v[192:195], v[62:65]
	v_mfma_f32_16x16x32_bf16 v[58:61], v[172:175], v[192:195], v[58:61]
	v_mfma_f32_16x16x32_bf16 v[46:49], v[164:167], v[200:203], v[46:49]
	v_mfma_f32_16x16x32_bf16 v[42:45], v[172:175], v[200:203], v[42:45]
	v_mfma_f32_16x16x32_bf16 v[30:33], v[164:167], v[208:211], v[30:33]
	v_mfma_f32_16x16x32_bf16 v[26:29], v[172:175], v[208:211], v[26:29]
	v_mfma_f32_16x16x32_bf16 v[14:17], v[164:167], v[228:231], v[14:17]
	v_mfma_f32_16x16x32_bf16 v[10:13], v[172:175], v[228:231], v[10:13]
	s_setprio 0
	s_barrier
	s_add_u32 s58, s20, 0x80000
	s_addc_u32 s59, s21, 0
	s_add_i32 s82, s82, s29
	v_lshl_add_u64 v[160:161], s[58:59], 0, v[134:135]
	s_mov_b32 m0, s82
	s_nop 0
	global_load_lds_dwordx4 v[160:161], off
	v_lshl_add_u64 v[160:161], s[58:59], 0, v[130:131]
	s_add_i32 m0, s82, 0x2000
	s_nop 0
	global_load_lds_dwordx4 v[160:161], off
	v_add_u32_e32 v159, 0x18000, v1
	ds_read_b128 v[160:163], v159
	ds_read_b128 v[164:167], v159 offset:1024
	ds_read_b128 v[168:171], v159 offset:2048
	ds_read_b128 v[172:175], v159 offset:3072
	s_waitcnt vmcnt(6)
	s_barrier
	s_setprio 1
	v_mfma_f32_16x16x32_bf16 v[54:57], v[232:235], v[176:179], v[54:57]
	v_mfma_f32_16x16x32_bf16 v[50:53], v[240:243], v[176:179], v[50:53]
	v_mfma_f32_16x16x32_bf16 v[38:41], v[232:235], v[196:199], v[38:41]
	v_mfma_f32_16x16x32_bf16 v[34:37], v[240:243], v[196:199], v[34:37]
	v_mfma_f32_16x16x32_bf16 v[22:25], v[232:235], v[204:207], v[22:25]
	v_mfma_f32_16x16x32_bf16 v[18:21], v[240:243], v[204:207], v[18:21]
	v_mfma_f32_16x16x32_bf16 v[6:9], v[232:235], v[224:227], v[6:9]
	v_mfma_f32_16x16x32_bf16 v[2:5], v[240:243], v[224:227], v[2:5]
	v_mfma_f32_16x16x32_bf16 v[54:57], v[236:239], v[192:195], v[54:57]
	v_mfma_f32_16x16x32_bf16 v[50:53], v[244:247], v[192:195], v[50:53]
	v_mfma_f32_16x16x32_bf16 v[38:41], v[236:239], v[200:203], v[38:41]
	v_mfma_f32_16x16x32_bf16 v[34:37], v[244:247], v[200:203], v[34:37]
	v_mfma_f32_16x16x32_bf16 v[22:25], v[236:239], v[208:211], v[22:25]
	v_mfma_f32_16x16x32_bf16 v[18:21], v[244:247], v[208:211], v[18:21]
	v_mfma_f32_16x16x32_bf16 v[6:9], v[236:239], v[228:231], v[6:9]
	v_mfma_f32_16x16x32_bf16 v[2:5], v[244:247], v[228:231], v[2:5]
	s_setprio 0
	s_add_i32 s58, 0, 0x18000
	s_barrier
	s_add_u32 s22, s22, 0x80000
	s_addc_u32 s23, s23, 0
	s_mov_b32 m0, s46
	v_lshl_add_u64 v[232:233], s[22:23], 0, v[136:137]
	ds_read_b128 v[176:179], v158 offset:32768
	ds_read_b128 v[196:199], v158 offset:34816
	ds_read_b128 v[204:207], v158 offset:36864
	ds_read_b128 v[224:227], v158 offset:38912
	ds_read_b128 v[192:195], v158 offset:33792
	ds_read_b128 v[200:203], v158 offset:35840
	ds_read_b128 v[208:211], v158 offset:37888
	ds_read_b128 v[228:231], v158 offset:39936
	global_load_lds_dwordx4 v[232:233], off
	v_lshl_add_u64 v[232:233], s[22:23], 0, v[132:133]
	s_mov_b32 m0, s47
	s_nop 0
	global_load_lds_dwordx4 v[232:233], off
	s_waitcnt lgkmcnt(8)
	s_barrier
	s_waitcnt lgkmcnt(4)
	s_setprio 1
	s_waitcnt lgkmcnt(4)
	v_mfma_f32_16x16x32_bf16 v[126:129], v[160:163], v[176:179], v[126:129]
	v_mfma_f32_16x16x32_bf16 v[122:125], v[168:171], v[176:179], v[122:125]
	v_mfma_f32_16x16x32_bf16 v[110:113], v[160:163], v[196:199], v[110:113]
	v_mfma_f32_16x16x32_bf16 v[106:109], v[168:171], v[196:199], v[106:109]
	v_mfma_f32_16x16x32_bf16 v[94:97], v[160:163], v[204:207], v[94:97]
	v_mfma_f32_16x16x32_bf16 v[90:93], v[168:171], v[204:207], v[90:93]
	v_mfma_f32_16x16x32_bf16 v[78:81], v[160:163], v[224:227], v[78:81]
	v_mfma_f32_16x16x32_bf16 v[74:77], v[168:171], v[224:227], v[74:77]
	s_waitcnt lgkmcnt(0)
	v_mfma_f32_16x16x32_bf16 v[126:129], v[164:167], v[192:195], v[126:129]
	v_mfma_f32_16x16x32_bf16 v[122:125], v[172:175], v[192:195], v[122:125]
	v_mfma_f32_16x16x32_bf16 v[110:113], v[164:167], v[200:203], v[110:113]
	v_mfma_f32_16x16x32_bf16 v[106:109], v[172:175], v[200:203], v[106:109]
	v_mfma_f32_16x16x32_bf16 v[94:97], v[164:167], v[208:211], v[94:97]
	v_mfma_f32_16x16x32_bf16 v[90:93], v[172:175], v[208:211], v[90:93]
	v_mfma_f32_16x16x32_bf16 v[78:81], v[164:167], v[228:231], v[78:81]
	v_mfma_f32_16x16x32_bf16 v[74:77], v[172:175], v[228:231], v[74:77]
	s_setprio 0
	s_barrier
	s_add_i32 s22, 0, 0x1c000
	s_add_i32 s23, s58, s29
	v_add_u32_e32 v159, s22, v1
	v_lshl_add_u64 v[212:213], v[212:213], 0, s[78:79]
	s_mov_b32 m0, s23
	ds_read_b128 v[232:235], v159
	ds_read_b128 v[236:239], v159 offset:1024
	ds_read_b128 v[240:243], v159 offset:2048
	ds_read_b128 v[244:247], v159 offset:3072
	global_load_lds_dwordx4 v[212:213], off
	v_lshl_add_u64 v[212:213], v[248:249], 0, s[78:79]
	s_add_i32 m0, s23, 0x2000
	s_nop 0
	global_load_lds_dwordx4 v[212:213], off
	s_barrier
	s_waitcnt lgkmcnt(0)
	s_setprio 1
	s_waitcnt lgkmcnt(0)
	v_mfma_f32_16x16x32_bf16 v[118:121], v[232:235], v[176:179], v[118:121]
	v_mfma_f32_16x16x32_bf16 v[114:117], v[240:243], v[176:179], v[114:117]
	v_mfma_f32_16x16x32_bf16 v[102:105], v[232:235], v[196:199], v[102:105]
	v_mfma_f32_16x16x32_bf16 v[98:101], v[240:243], v[196:199], v[98:101]
	v_mfma_f32_16x16x32_bf16 v[86:89], v[232:235], v[204:207], v[86:89]
	v_mfma_f32_16x16x32_bf16 v[82:85], v[240:243], v[204:207], v[82:85]
	v_mfma_f32_16x16x32_bf16 v[70:73], v[232:235], v[224:227], v[70:73]
	v_mfma_f32_16x16x32_bf16 v[66:69], v[240:243], v[224:227], v[66:69]
	v_mfma_f32_16x16x32_bf16 v[118:121], v[236:239], v[192:195], v[118:121]
	v_mfma_f32_16x16x32_bf16 v[114:117], v[244:247], v[192:195], v[114:117]
	v_mfma_f32_16x16x32_bf16 v[102:105], v[236:239], v[200:203], v[102:105]
	v_mfma_f32_16x16x32_bf16 v[98:101], v[244:247], v[200:203], v[98:101]
	v_mfma_f32_16x16x32_bf16 v[86:89], v[236:239], v[208:211], v[86:89]
	v_mfma_f32_16x16x32_bf16 v[82:85], v[244:247], v[208:211], v[82:85]
	v_mfma_f32_16x16x32_bf16 v[70:73], v[236:239], v[228:231], v[70:73]
	v_mfma_f32_16x16x32_bf16 v[66:69], v[244:247], v[228:231], v[66:69]
	s_setprio 0
	s_mov_b32 m0, s48
	v_lshl_add_u64 v[212:213], v[250:251], 0, s[78:79]
	s_barrier
	ds_read_b128 v[176:179], v158 offset:49152
	ds_read_b128 v[196:199], v158 offset:51200
	ds_read_b128 v[204:207], v158 offset:53248
	ds_read_b128 v[224:227], v158 offset:55296
	ds_read_b128 v[192:195], v158 offset:50176
	ds_read_b128 v[200:203], v158 offset:52224
	ds_read_b128 v[208:211], v158 offset:54272
	ds_read_b128 v[228:231], v158 offset:56320
	global_load_lds_dwordx4 v[212:213], off
	v_lshl_add_u64 v[212:213], v[222:223], 0, s[78:79]
	s_mov_b32 m0, s49
	s_nop 0
	global_load_lds_dwordx4 v[212:213], off
	s_waitcnt vmcnt(10)
	s_barrier
	s_waitcnt lgkmcnt(4)
	s_setprio 1
	s_waitcnt lgkmcnt(4)
	v_mfma_f32_16x16x32_bf16 v[62:65], v[160:163], v[176:179], v[62:65]
	v_mfma_f32_16x16x32_bf16 v[58:61], v[168:171], v[176:179], v[58:61]
	v_mfma_f32_16x16x32_bf16 v[46:49], v[160:163], v[196:199], v[46:49]
	v_mfma_f32_16x16x32_bf16 v[42:45], v[168:171], v[196:199], v[42:45]
	v_mfma_f32_16x16x32_bf16 v[30:33], v[160:163], v[204:207], v[30:33]
	v_mfma_f32_16x16x32_bf16 v[26:29], v[168:171], v[204:207], v[26:29]
	v_mfma_f32_16x16x32_bf16 v[14:17], v[160:163], v[224:227], v[14:17]
	v_mfma_f32_16x16x32_bf16 v[10:13], v[168:171], v[224:227], v[10:13]
	s_waitcnt lgkmcnt(0)
	v_mfma_f32_16x16x32_bf16 v[62:65], v[164:167], v[192:195], v[62:65]
	v_mfma_f32_16x16x32_bf16 v[58:61], v[172:175], v[192:195], v[58:61]
	v_mfma_f32_16x16x32_bf16 v[46:49], v[164:167], v[200:203], v[46:49]
	v_mfma_f32_16x16x32_bf16 v[42:45], v[172:175], v[200:203], v[42:45]
	v_mfma_f32_16x16x32_bf16 v[30:33], v[164:167], v[208:211], v[30:33]
	v_mfma_f32_16x16x32_bf16 v[26:29], v[172:175], v[208:211], v[26:29]
	v_mfma_f32_16x16x32_bf16 v[14:17], v[164:167], v[228:231], v[14:17]
	v_mfma_f32_16x16x32_bf16 v[10:13], v[172:175], v[228:231], v[10:13]
	s_setprio 0
	s_barrier
	s_add_u32 s20, s20, 0x80080
	s_addc_u32 s21, s21, 0
	s_add_i32 s22, s22, s29
	v_lshl_add_u64 v[160:161], s[20:21], 0, v[134:135]
	s_mov_b32 m0, s22
	s_nop 0
	global_load_lds_dwordx4 v[160:161], off
	v_lshl_add_u64 v[160:161], s[20:21], 0, v[130:131]
	s_add_i32 m0, s22, 0x2000
	s_nop 0
	global_load_lds_dwordx4 v[160:161], off
	v_add_u32_e32 v159, 0x10000, v1
	ds_read_b128 v[160:163], v159
	ds_read_b128 v[164:167], v159 offset:1024
	ds_read_b128 v[168:171], v159 offset:2048
	ds_read_b128 v[172:175], v159 offset:3072
	s_waitcnt vmcnt(6)
	s_barrier
	s_setprio 1
	v_mfma_f32_16x16x32_bf16 v[54:57], v[232:235], v[176:179], v[54:57]
	v_mfma_f32_16x16x32_bf16 v[50:53], v[240:243], v[176:179], v[50:53]
	v_mfma_f32_16x16x32_bf16 v[38:41], v[232:235], v[196:199], v[38:41]
	v_mfma_f32_16x16x32_bf16 v[34:37], v[240:243], v[196:199], v[34:37]
	v_mfma_f32_16x16x32_bf16 v[22:25], v[232:235], v[204:207], v[22:25]
	v_mfma_f32_16x16x32_bf16 v[18:21], v[240:243], v[204:207], v[18:21]
	v_mfma_f32_16x16x32_bf16 v[6:9], v[232:235], v[224:227], v[6:9]
	v_mfma_f32_16x16x32_bf16 v[2:5], v[240:243], v[224:227], v[2:5]
	v_mfma_f32_16x16x32_bf16 v[54:57], v[236:239], v[192:195], v[54:57]
	v_mfma_f32_16x16x32_bf16 v[50:53], v[244:247], v[192:195], v[50:53]
	v_mfma_f32_16x16x32_bf16 v[38:41], v[236:239], v[200:203], v[38:41]
	v_mfma_f32_16x16x32_bf16 v[34:37], v[244:247], v[200:203], v[34:37]
	v_mfma_f32_16x16x32_bf16 v[22:25], v[236:239], v[208:211], v[22:25]
	v_mfma_f32_16x16x32_bf16 v[18:21], v[244:247], v[208:211], v[18:21]
	v_mfma_f32_16x16x32_bf16 v[6:9], v[236:239], v[228:231], v[6:9]
	v_mfma_f32_16x16x32_bf16 v[2:5], v[244:247], v[228:231], v[2:5]
	s_setprio 0
	s_add_i32 s57, s57, 2
	s_add_u32 s18, s18, 0x100
	s_addc_u32 s19, s19, 0
	s_add_u32 s55, s55, 0x100
	s_addc_u32 s56, s56, 0
	s_cmp_gt_u32 s57, 29
	s_barrier
	s_cbranch_scc0 .LBB0_749
	s_waitcnt lgkmcnt(0)
	s_lshl_b32 s18, s52, 5
	s_add_i32 s18, s18, s51
	v_max_f32_e32 v122, 0, v122
	v_max_f32_e32 v123, 0, v123
	s_ashr_i32 s19, s18, 31
	v_pk_mul_f32 v[162:163], v[122:123], v[122:123]
	v_max_f32_e32 v123, v124, v124
	s_lshl_b64 s[18:19], s[18:19], 17
	v_max_f32_e32 v122, v128, v128
	v_max_f32_e32 v124, 0, v123
	v_max_f32_e32 v123, v129, v129
	s_add_u32 s18, s68, s18
	v_max_f32_e32 v126, 0, v126
	v_max_f32_e32 v127, 0, v127
	v_max_f32_e32 v122, 0, v122
	v_max_f32_e32 v123, 0, v123
	v_max_f32_e32 v125, 0, v125
	s_addc_u32 s19, s69, s19
	v_pk_mul_f32 v[126:127], v[126:127], v[126:127]
	v_pk_mul_f32 v[128:129], v[122:123], v[122:123]
	v_pk_mul_f32 v[164:165], v[124:125], v[124:125]
	v_lshl_add_u64 v[160:161], v[138:139], 1, s[18:19]
	v_cvt_pk_bf16_f32 v122, v126, v127
	v_cvt_pk_bf16_f32 v123, v128, v129
	v_cvt_pk_bf16_f32 v124, v162, v163
	v_cvt_pk_bf16_f32 v125, v164, v165
	v_max_f32_e32 v114, 0, v114
	v_max_f32_e32 v115, 0, v115
	global_store_dwordx4 v[160:161], v[122:125], off
	v_max_f32_e32 v118, v118, v118
	v_max_f32_e32 v119, v119, v119
	v_pk_mul_f32 v[122:123], v[114:115], v[114:115]
	v_max_f32_e32 v115, v116, v116
	v_max_f32_e32 v114, v120, v120
	v_max_f32_e32 v116, 0, v115
	v_max_f32_e32 v115, v121, v121
	v_max_f32_e32 v118, 0, v118
	v_max_f32_e32 v119, 0, v119
	v_max_f32_e32 v114, 0, v114
	v_max_f32_e32 v115, 0, v115
	v_max_f32_e32 v117, 0, v117
	v_pk_mul_f32 v[118:119], v[118:119], v[118:119]
	v_pk_mul_f32 v[120:121], v[114:115], v[114:115]
	v_pk_mul_f32 v[124:125], v[116:117], v[116:117]
	v_cvt_pk_bf16_f32 v114, v118, v119
	v_cvt_pk_bf16_f32 v115, v120, v121
	v_cvt_pk_bf16_f32 v116, v122, v123
	v_cvt_pk_bf16_f32 v117, v124, v125
	v_max_f32_e32 v106, 0, v106
	v_max_f32_e32 v107, 0, v107
	global_store_dwordx4 v[160:161], v[114:117], off offset:256
	v_max_f32_e32 v110, v110, v110
	v_max_f32_e32 v111, v111, v111
	v_pk_mul_f32 v[116:117], v[106:107], v[106:107]
	v_max_f32_e32 v107, v108, v108
	v_max_f32_e32 v106, v112, v112
	v_max_f32_e32 v108, 0, v107
	v_max_f32_e32 v107, v113, v113
	v_max_f32_e32 v110, 0, v110
	v_max_f32_e32 v111, 0, v111
	v_max_f32_e32 v106, 0, v106
	v_max_f32_e32 v107, 0, v107
	v_max_f32_e32 v109, 0, v109
	v_pk_mul_f32 v[110:111], v[110:111], v[110:111]
	v_pk_mul_f32 v[112:113], v[106:107], v[106:107]
	v_pk_mul_f32 v[118:119], v[108:109], v[108:109]
	v_lshl_add_u64 v[114:115], v[140:141], 1, s[18:19]
	v_cvt_pk_bf16_f32 v106, v110, v111
	v_cvt_pk_bf16_f32 v107, v112, v113
	v_cvt_pk_bf16_f32 v108, v116, v117
	v_cvt_pk_bf16_f32 v109, v118, v119
	v_max_f32_e32 v98, 0, v98
	v_max_f32_e32 v99, 0, v99
	global_store_dwordx4 v[114:115], v[106:109], off
	v_max_f32_e32 v102, v102, v102
	v_max_f32_e32 v103, v103, v103
	v_pk_mul_f32 v[106:107], v[98:99], v[98:99]
	v_max_f32_e32 v99, v100, v100
	v_max_f32_e32 v98, v104, v104
	v_max_f32_e32 v100, 0, v99
	v_max_f32_e32 v99, v105, v105
	v_max_f32_e32 v102, 0, v102
	v_max_f32_e32 v103, 0, v103
	v_max_f32_e32 v98, 0, v98
	v_max_f32_e32 v99, 0, v99
	v_max_f32_e32 v101, 0, v101
	v_pk_mul_f32 v[102:103], v[102:103], v[102:103]
	v_pk_mul_f32 v[104:105], v[98:99], v[98:99]
	v_pk_mul_f32 v[108:109], v[100:101], v[100:101]
	v_cvt_pk_bf16_f32 v98, v102, v103
	v_cvt_pk_bf16_f32 v99, v104, v105
	v_cvt_pk_bf16_f32 v100, v106, v107
	v_cvt_pk_bf16_f32 v101, v108, v109
	v_max_f32_e32 v90, 0, v90
	v_max_f32_e32 v91, 0, v91
	global_store_dwordx4 v[114:115], v[98:101], off offset:256
	v_max_f32_e32 v94, v94, v94
	v_max_f32_e32 v95, v95, v95
	v_pk_mul_f32 v[100:101], v[90:91], v[90:91]
	v_max_f32_e32 v91, v92, v92
	v_max_f32_e32 v90, v96, v96
	v_max_f32_e32 v92, 0, v91
	v_max_f32_e32 v91, v97, v97
	v_max_f32_e32 v94, 0, v94
	v_max_f32_e32 v95, 0, v95
	v_max_f32_e32 v90, 0, v90
	v_max_f32_e32 v91, 0, v91
	v_max_f32_e32 v93, 0, v93
	v_pk_mul_f32 v[94:95], v[94:95], v[94:95]
	v_pk_mul_f32 v[96:97], v[90:91], v[90:91]
	v_pk_mul_f32 v[102:103], v[92:93], v[92:93]
	v_lshl_add_u64 v[98:99], v[142:143], 1, s[18:19]
	v_cvt_pk_bf16_f32 v90, v94, v95
	v_cvt_pk_bf16_f32 v91, v96, v97
	v_cvt_pk_bf16_f32 v92, v100, v101
	v_cvt_pk_bf16_f32 v93, v102, v103
	v_max_f32_e32 v82, 0, v82
	v_max_f32_e32 v83, 0, v83
	global_store_dwordx4 v[98:99], v[90:93], off
	v_max_f32_e32 v86, v86, v86
	v_max_f32_e32 v87, v87, v87
	v_pk_mul_f32 v[90:91], v[82:83], v[82:83]
	v_max_f32_e32 v83, v84, v84
	v_max_f32_e32 v82, v88, v88
	v_max_f32_e32 v84, 0, v83
	v_max_f32_e32 v83, v89, v89
	v_max_f32_e32 v86, 0, v86
	v_max_f32_e32 v87, 0, v87
	v_max_f32_e32 v82, 0, v82
	v_max_f32_e32 v83, 0, v83
	v_max_f32_e32 v85, 0, v85
	v_pk_mul_f32 v[86:87], v[86:87], v[86:87]
	v_pk_mul_f32 v[88:89], v[82:83], v[82:83]
	v_pk_mul_f32 v[92:93], v[84:85], v[84:85]
	v_cvt_pk_bf16_f32 v82, v86, v87
	v_cvt_pk_bf16_f32 v83, v88, v89
	v_cvt_pk_bf16_f32 v84, v90, v91
	v_cvt_pk_bf16_f32 v85, v92, v93
	v_max_f32_e32 v74, 0, v74
	v_max_f32_e32 v75, 0, v75
	global_store_dwordx4 v[98:99], v[82:85], off offset:256
	v_max_f32_e32 v78, v78, v78
	v_max_f32_e32 v79, v79, v79
	v_pk_mul_f32 v[84:85], v[74:75], v[74:75]
	v_max_f32_e32 v75, v76, v76
	v_max_f32_e32 v74, v80, v80
	v_max_f32_e32 v76, 0, v75
	v_max_f32_e32 v75, v81, v81
	v_max_f32_e32 v78, 0, v78
	v_max_f32_e32 v79, 0, v79
	v_max_f32_e32 v74, 0, v74
	v_max_f32_e32 v75, 0, v75
	v_max_f32_e32 v77, 0, v77
	v_pk_mul_f32 v[78:79], v[78:79], v[78:79]
	v_pk_mul_f32 v[80:81], v[74:75], v[74:75]
	v_pk_mul_f32 v[86:87], v[76:77], v[76:77]
	v_lshl_add_u64 v[82:83], v[144:145], 1, s[18:19]
	v_cvt_pk_bf16_f32 v74, v78, v79
	v_cvt_pk_bf16_f32 v75, v80, v81
	v_cvt_pk_bf16_f32 v76, v84, v85
	v_cvt_pk_bf16_f32 v77, v86, v87
	v_max_f32_e32 v66, 0, v66
	v_max_f32_e32 v67, 0, v67
	global_store_dwordx4 v[82:83], v[74:77], off
	v_max_f32_e32 v70, v70, v70
	v_max_f32_e32 v71, v71, v71
	v_pk_mul_f32 v[74:75], v[66:67], v[66:67]
	v_max_f32_e32 v67, v68, v68
	v_max_f32_e32 v66, v72, v72
	v_max_f32_e32 v68, 0, v67
	v_max_f32_e32 v67, v73, v73
	v_max_f32_e32 v70, 0, v70
	v_max_f32_e32 v71, 0, v71
	v_max_f32_e32 v66, 0, v66
	v_max_f32_e32 v67, 0, v67
	v_max_f32_e32 v69, 0, v69
	v_pk_mul_f32 v[70:71], v[70:71], v[70:71]
	v_pk_mul_f32 v[72:73], v[66:67], v[66:67]
	v_pk_mul_f32 v[76:77], v[68:69], v[68:69]
	v_cvt_pk_bf16_f32 v66, v70, v71
	v_cvt_pk_bf16_f32 v67, v72, v73
	v_cvt_pk_bf16_f32 v68, v74, v75
	v_cvt_pk_bf16_f32 v69, v76, v77
	v_max_f32_e32 v58, 0, v58
	v_max_f32_e32 v59, 0, v59
	global_store_dwordx4 v[82:83], v[66:69], off offset:256
	v_max_f32_e32 v62, v62, v62
	v_max_f32_e32 v63, v63, v63
	v_pk_mul_f32 v[68:69], v[58:59], v[58:59]
	v_max_f32_e32 v59, v60, v60
	v_max_f32_e32 v58, v64, v64
	v_max_f32_e32 v60, 0, v59
	v_max_f32_e32 v59, v65, v65
	v_max_f32_e32 v62, 0, v62
	v_max_f32_e32 v63, 0, v63
	v_max_f32_e32 v58, 0, v58
	v_max_f32_e32 v59, 0, v59
	v_max_f32_e32 v61, 0, v61
	v_pk_mul_f32 v[62:63], v[62:63], v[62:63]
	v_pk_mul_f32 v[64:65], v[58:59], v[58:59]
	v_pk_mul_f32 v[70:71], v[60:61], v[60:61]
	v_lshl_add_u64 v[66:67], v[146:147], 1, s[18:19]
	v_cvt_pk_bf16_f32 v58, v62, v63
	v_cvt_pk_bf16_f32 v59, v64, v65
	v_cvt_pk_bf16_f32 v60, v68, v69
	v_cvt_pk_bf16_f32 v61, v70, v71
	v_max_f32_e32 v50, 0, v50
	v_max_f32_e32 v51, 0, v51
	global_store_dwordx4 v[66:67], v[58:61], off
	v_max_f32_e32 v54, v54, v54
	v_max_f32_e32 v55, v55, v55
	v_pk_mul_f32 v[58:59], v[50:51], v[50:51]
	v_max_f32_e32 v51, v52, v52
	v_max_f32_e32 v50, v56, v56
	v_max_f32_e32 v52, 0, v51
	v_max_f32_e32 v51, v57, v57
	v_max_f32_e32 v54, 0, v54
	v_max_f32_e32 v55, 0, v55
	v_max_f32_e32 v50, 0, v50
	v_max_f32_e32 v51, 0, v51
	v_max_f32_e32 v53, 0, v53
	v_pk_mul_f32 v[54:55], v[54:55], v[54:55]
	v_pk_mul_f32 v[56:57], v[50:51], v[50:51]
	v_pk_mul_f32 v[60:61], v[52:53], v[52:53]
	v_cvt_pk_bf16_f32 v50, v54, v55
	v_cvt_pk_bf16_f32 v51, v56, v57
	v_cvt_pk_bf16_f32 v52, v58, v59
	v_cvt_pk_bf16_f32 v53, v60, v61
	v_max_f32_e32 v42, 0, v42
	v_max_f32_e32 v43, 0, v43
	global_store_dwordx4 v[66:67], v[50:53], off offset:256
	v_max_f32_e32 v46, v46, v46
	v_max_f32_e32 v47, v47, v47
	v_pk_mul_f32 v[52:53], v[42:43], v[42:43]
	v_max_f32_e32 v43, v44, v44
	v_max_f32_e32 v42, v48, v48
	v_max_f32_e32 v44, 0, v43
	v_max_f32_e32 v43, v49, v49
	v_max_f32_e32 v46, 0, v46
	v_max_f32_e32 v47, 0, v47
	v_max_f32_e32 v42, 0, v42
	v_max_f32_e32 v43, 0, v43
	v_max_f32_e32 v45, 0, v45
	v_pk_mul_f32 v[46:47], v[46:47], v[46:47]
	v_pk_mul_f32 v[48:49], v[42:43], v[42:43]
	v_pk_mul_f32 v[54:55], v[44:45], v[44:45]
	v_lshl_add_u64 v[50:51], v[148:149], 1, s[18:19]
	v_cvt_pk_bf16_f32 v42, v46, v47
	v_cvt_pk_bf16_f32 v43, v48, v49
	v_cvt_pk_bf16_f32 v44, v52, v53
	v_cvt_pk_bf16_f32 v45, v54, v55
	v_max_f32_e32 v34, 0, v34
	v_max_f32_e32 v35, 0, v35
	global_store_dwordx4 v[50:51], v[42:45], off
	v_max_f32_e32 v38, v38, v38
	v_max_f32_e32 v39, v39, v39
	v_pk_mul_f32 v[42:43], v[34:35], v[34:35]
	v_max_f32_e32 v35, v36, v36
	v_max_f32_e32 v34, v40, v40
	v_max_f32_e32 v36, 0, v35
	v_max_f32_e32 v35, v41, v41
	v_max_f32_e32 v38, 0, v38
	v_max_f32_e32 v39, 0, v39
	v_max_f32_e32 v34, 0, v34
	v_max_f32_e32 v35, 0, v35
	v_max_f32_e32 v37, 0, v37
	v_pk_mul_f32 v[38:39], v[38:39], v[38:39]
	v_pk_mul_f32 v[40:41], v[34:35], v[34:35]
	v_pk_mul_f32 v[44:45], v[36:37], v[36:37]
	v_cvt_pk_bf16_f32 v34, v38, v39
	v_cvt_pk_bf16_f32 v35, v40, v41
	v_cvt_pk_bf16_f32 v36, v42, v43
	v_cvt_pk_bf16_f32 v37, v44, v45
	v_max_f32_e32 v26, 0, v26
	v_max_f32_e32 v27, 0, v27
	global_store_dwordx4 v[50:51], v[34:37], off offset:256
	v_max_f32_e32 v30, v30, v30
	v_max_f32_e32 v31, v31, v31
	v_pk_mul_f32 v[36:37], v[26:27], v[26:27]
	v_max_f32_e32 v27, v28, v28
	v_max_f32_e32 v26, v32, v32
	v_max_f32_e32 v28, 0, v27
	v_max_f32_e32 v27, v33, v33
	v_max_f32_e32 v30, 0, v30
	v_max_f32_e32 v31, 0, v31
	v_max_f32_e32 v26, 0, v26
	v_max_f32_e32 v27, 0, v27
	v_max_f32_e32 v29, 0, v29
	v_pk_mul_f32 v[30:31], v[30:31], v[30:31]
	v_pk_mul_f32 v[32:33], v[26:27], v[26:27]
	v_pk_mul_f32 v[38:39], v[28:29], v[28:29]
	v_lshl_add_u64 v[34:35], v[150:151], 1, s[18:19]
	v_cvt_pk_bf16_f32 v26, v30, v31
	v_cvt_pk_bf16_f32 v27, v32, v33
	v_cvt_pk_bf16_f32 v28, v36, v37
	v_cvt_pk_bf16_f32 v29, v38, v39
	v_max_f32_e32 v18, 0, v18
	v_max_f32_e32 v19, 0, v19
	global_store_dwordx4 v[34:35], v[26:29], off
	v_max_f32_e32 v22, v22, v22
	v_max_f32_e32 v23, v23, v23
	v_pk_mul_f32 v[26:27], v[18:19], v[18:19]
	v_max_f32_e32 v19, v20, v20
	v_max_f32_e32 v18, v24, v24
	v_max_f32_e32 v20, 0, v19
	v_max_f32_e32 v19, v25, v25
	v_max_f32_e32 v22, 0, v22
	v_max_f32_e32 v23, 0, v23
	v_max_f32_e32 v18, 0, v18
	v_max_f32_e32 v19, 0, v19
	v_max_f32_e32 v21, 0, v21
	v_pk_mul_f32 v[22:23], v[22:23], v[22:23]
	v_pk_mul_f32 v[24:25], v[18:19], v[18:19]
	v_pk_mul_f32 v[28:29], v[20:21], v[20:21]
	v_cvt_pk_bf16_f32 v18, v22, v23
	v_cvt_pk_bf16_f32 v19, v24, v25
	v_cvt_pk_bf16_f32 v20, v26, v27
	v_cvt_pk_bf16_f32 v21, v28, v29
	v_max_f32_e32 v10, 0, v10
	v_max_f32_e32 v11, 0, v11
	global_store_dwordx4 v[34:35], v[18:21], off offset:256
	v_max_f32_e32 v14, v14, v14
	v_max_f32_e32 v15, v15, v15
	v_pk_mul_f32 v[20:21], v[10:11], v[10:11]
	v_max_f32_e32 v11, v12, v12
	v_max_f32_e32 v10, v16, v16
	v_max_f32_e32 v12, 0, v11
	v_max_f32_e32 v11, v17, v17
	v_max_f32_e32 v14, 0, v14
	v_max_f32_e32 v15, 0, v15
	v_max_f32_e32 v10, 0, v10
	v_max_f32_e32 v11, 0, v11
	v_max_f32_e32 v13, 0, v13
	v_pk_mul_f32 v[14:15], v[14:15], v[14:15]
	v_pk_mul_f32 v[16:17], v[10:11], v[10:11]
	v_pk_mul_f32 v[22:23], v[12:13], v[12:13]
	v_lshl_add_u64 v[18:19], v[152:153], 1, s[18:19]
	v_cvt_pk_bf16_f32 v10, v14, v15
	v_cvt_pk_bf16_f32 v11, v16, v17
	v_cvt_pk_bf16_f32 v12, v20, v21
	v_cvt_pk_bf16_f32 v13, v22, v23
	v_max_f32_e32 v2, 0, v2
	v_max_f32_e32 v3, 0, v3
	global_store_dwordx4 v[18:19], v[10:13], off
	v_max_f32_e32 v6, v6, v6
	v_max_f32_e32 v7, v7, v7
	v_pk_mul_f32 v[10:11], v[2:3], v[2:3]
	v_max_f32_e32 v3, v4, v4
	v_max_f32_e32 v2, v8, v8
	v_max_f32_e32 v4, 0, v3
	v_max_f32_e32 v3, v9, v9
	v_max_f32_e32 v6, 0, v6
	v_max_f32_e32 v7, 0, v7
	v_max_f32_e32 v2, 0, v2
	v_max_f32_e32 v3, 0, v3
	v_max_f32_e32 v5, 0, v5
	v_pk_mul_f32 v[6:7], v[6:7], v[6:7]
	v_pk_mul_f32 v[8:9], v[2:3], v[2:3]
	v_pk_mul_f32 v[12:13], v[4:5], v[4:5]
	v_cvt_pk_bf16_f32 v2, v6, v7
	v_cvt_pk_bf16_f32 v3, v8, v9
	v_cvt_pk_bf16_f32 v4, v10, v11
	v_cvt_pk_bf16_f32 v5, v12, v13
	s_and_b64 vcc, exec, s[0:1]
	s_mov_b32 s51, s30
	s_mov_b32 s52, s38
	s_mov_b64 s[20:21], s[80:81]
	s_mov_b64 s[18:19], s[42:43]
	global_store_dwordx4 v[18:19], v[2:5], off offset:256
	s_cbranch_vccz .LBB0_742
	s_waitcnt vmcnt(0)
	v_readlane_b32 s38, v255, 28
	s_cmpk_gt_u32 s26, 0xff
	v_readlane_b32 s39, v255, 29
	v_readlane_b32 s42, v255, 32
	s_cbranch_scc1 .LBB0_753
	s_barrier

.LBB0_814:
	s_add_i32 s22, s55, 0xffff0000
	s_and_b32 s22, s22, 0x3e0000
	s_and_b32 s23, s90, 0x100
	s_or_b32 s56, s23, s22
	s_and_b32 s22, s55, 0x7e0000
	s_add_u32 vcc_lo, s90, 0x100
	s_addc_u32 vcc_hi, s91, 0
	s_and_b32 s23, vcc_lo, 0x100
	s_or_b32 s22, s22, s23
	s_add_u32 s22, s84, s22
	s_addc_u32 s23, s85, 0
	s_add_u32 s57, s30, s90
	s_addc_u32 s58, s31, s91
	s_add_u32 s57, s57, 0x100
	s_addc_u32 s58, s58, 0
	s_add_i32 s59, 0, 0x10000
	s_cmpk_eq_i32 s54, 0x7c
	s_cselect_b32 s91, s43, s58
	s_cselect_b32 s90, s53, s57
	s_cselect_b32 s23, s51, s23
	s_cselect_b32 s22, s52, s22
	s_add_u32 s56, s84, s56
	s_addc_u32 s57, s85, 0
	s_add_u32 s56, s56, 0x10080
	s_addc_u32 s57, s57, 0
	v_lshl_add_u64 v[204:205], s[56:57], 0, v[136:137]
	s_add_i32 m0, s28, 0xc000
	ds_read_b128 v[158:161], v140
	ds_read_b128 v[168:171], v140 offset:2048
	ds_read_b128 v[176:179], v140 offset:4096
	ds_read_b128 v[196:199], v140 offset:6144
	ds_read_b128 v[162:165], v140 offset:1024
	ds_read_b128 v[172:175], v140 offset:3072
	ds_read_b128 v[192:195], v140 offset:5120
	ds_read_b128 v[200:203], v140 offset:7168
	global_load_lds_dwordx4 v[204:205], off
	v_lshl_add_u64 v[204:205], s[56:57], 0, v[132:133]
	s_add_i32 m0, s28, 0xe000
	s_nop 0
	global_load_lds_dwordx4 v[204:205], off
	s_waitcnt lgkmcnt(8)
	s_barrier
	s_waitcnt lgkmcnt(4)
	s_setprio 1
	s_waitcnt lgkmcnt(4)
	v_mfma_f32_16x16x32_bf16 v[86:89], v[142:145], v[158:161], v[86:89]
	v_mfma_f32_16x16x32_bf16 v[94:97], v[150:153], v[158:161], v[94:97]
	v_mfma_f32_16x16x32_bf16 v[98:101], v[142:145], v[168:171], v[98:101]
	v_mfma_f32_16x16x32_bf16 v[102:105], v[150:153], v[168:171], v[102:105]
	v_mfma_f32_16x16x32_bf16 v[114:117], v[142:145], v[176:179], v[114:117]
	v_mfma_f32_16x16x32_bf16 v[122:125], v[150:153], v[176:179], v[122:125]
	v_mfma_f32_16x16x32_bf16 v[126:129], v[142:145], v[196:199], v[126:129]
	v_mfma_f32_16x16x32_bf16 v[118:121], v[150:153], v[196:199], v[118:121]
	s_waitcnt lgkmcnt(0)
	v_mfma_f32_16x16x32_bf16 v[86:89], v[146:149], v[162:165], v[86:89]
	v_mfma_f32_16x16x32_bf16 v[94:97], v[154:157], v[162:165], v[94:97]
	v_mfma_f32_16x16x32_bf16 v[98:101], v[146:149], v[172:175], v[98:101]
	v_mfma_f32_16x16x32_bf16 v[102:105], v[154:157], v[172:175], v[102:105]
	v_mfma_f32_16x16x32_bf16 v[114:117], v[146:149], v[192:195], v[114:117]
	v_mfma_f32_16x16x32_bf16 v[122:125], v[154:157], v[192:195], v[122:125]
	v_mfma_f32_16x16x32_bf16 v[126:129], v[146:149], v[200:203], v[126:129]
	v_mfma_f32_16x16x32_bf16 v[118:121], v[154:157], v[200:203], v[118:121]
	s_setprio 0
	s_barrier
	s_add_i32 s58, 0, 0x14000
	s_add_i32 s56, s59, s81
	v_add_u32_e32 v141, s58, v139
	v_lshl_add_u64 v[212:213], s[90:91], 0, v[134:135]
	s_mov_b32 m0, s56
	ds_read_b128 v[204:207], v141
	ds_read_b128 v[208:211], v141 offset:1024
	ds_read_b128 v[224:227], v141 offset:2048
	ds_read_b128 v[228:231], v141 offset:3072
	global_load_lds_dwordx4 v[212:213], off
	v_lshl_add_u64 v[222:223], s[90:91], 0, v[130:131]
	s_add_i32 m0, s56, 0x2000
	s_nop 0
	global_load_lds_dwordx4 v[222:223], off
	s_barrier
	s_waitcnt lgkmcnt(0)
	s_setprio 1
	s_waitcnt lgkmcnt(0)
	v_mfma_f32_16x16x32_bf16 v[2:5], v[204:207], v[158:161], v[2:5]
	v_mfma_f32_16x16x32_bf16 v[6:9], v[224:227], v[158:161], v[6:9]
	v_mfma_f32_16x16x32_bf16 v[10:13], v[204:207], v[168:171], v[10:13]
	v_mfma_f32_16x16x32_bf16 v[14:17], v[224:227], v[168:171], v[14:17]
	v_mfma_f32_16x16x32_bf16 v[22:25], v[204:207], v[176:179], v[22:25]
	v_mfma_f32_16x16x32_bf16 v[18:21], v[224:227], v[176:179], v[18:21]
	v_mfma_f32_16x16x32_bf16 v[30:33], v[204:207], v[196:199], v[30:33]
	v_mfma_f32_16x16x32_bf16 v[26:29], v[224:227], v[196:199], v[26:29]
	v_mfma_f32_16x16x32_bf16 v[2:5], v[208:211], v[162:165], v[2:5]
	v_mfma_f32_16x16x32_bf16 v[6:9], v[228:231], v[162:165], v[6:9]
	v_mfma_f32_16x16x32_bf16 v[10:13], v[208:211], v[172:175], v[10:13]
	v_mfma_f32_16x16x32_bf16 v[14:17], v[228:231], v[172:175], v[14:17]
	v_mfma_f32_16x16x32_bf16 v[22:25], v[208:211], v[192:195], v[22:25]
	v_mfma_f32_16x16x32_bf16 v[18:21], v[228:231], v[192:195], v[18:21]
	v_mfma_f32_16x16x32_bf16 v[30:33], v[208:211], v[200:203], v[30:33]
	v_mfma_f32_16x16x32_bf16 v[26:29], v[228:231], v[200:203], v[26:29]
	s_setprio 0
	s_mov_b32 m0, s28
	v_lshl_add_u64 v[232:233], s[22:23], 0, v[136:137]
	s_barrier
	ds_read_b128 v[158:161], v140 offset:16384
	ds_read_b128 v[168:171], v140 offset:18432
	ds_read_b128 v[176:179], v140 offset:20480
	ds_read_b128 v[196:199], v140 offset:22528
	ds_read_b128 v[162:165], v140 offset:17408
	ds_read_b128 v[172:175], v140 offset:19456
	ds_read_b128 v[192:195], v140 offset:21504
	ds_read_b128 v[200:203], v140 offset:23552
	global_load_lds_dwordx4 v[232:233], off
	v_lshl_add_u64 v[234:235], s[22:23], 0, v[132:133]
	s_mov_b32 m0, s29
	s_nop 0
	global_load_lds_dwordx4 v[234:235], off
	s_waitcnt vmcnt(10)
	s_barrier
	s_waitcnt lgkmcnt(4)
	s_setprio 1
	s_waitcnt lgkmcnt(4)
	v_mfma_f32_16x16x32_bf16 v[110:113], v[142:145], v[158:161], v[110:113]
	v_mfma_f32_16x16x32_bf16 v[106:109], v[150:153], v[158:161], v[106:109]
	v_mfma_f32_16x16x32_bf16 v[90:93], v[142:145], v[168:171], v[90:93]
	v_mfma_f32_16x16x32_bf16 v[82:85], v[150:153], v[168:171], v[82:85]
	v_mfma_f32_16x16x32_bf16 v[78:81], v[142:145], v[176:179], v[78:81]
	v_mfma_f32_16x16x32_bf16 v[74:77], v[150:153], v[176:179], v[74:77]
	v_mfma_f32_16x16x32_bf16 v[70:73], v[142:145], v[196:199], v[70:73]
	v_mfma_f32_16x16x32_bf16 v[66:69], v[150:153], v[196:199], v[66:69]
	s_waitcnt lgkmcnt(0)
	v_mfma_f32_16x16x32_bf16 v[110:113], v[146:149], v[162:165], v[110:113]
	v_mfma_f32_16x16x32_bf16 v[106:109], v[154:157], v[162:165], v[106:109]
	v_mfma_f32_16x16x32_bf16 v[90:93], v[146:149], v[172:175], v[90:93]
	v_mfma_f32_16x16x32_bf16 v[82:85], v[154:157], v[172:175], v[82:85]
	v_mfma_f32_16x16x32_bf16 v[78:81], v[146:149], v[192:195], v[78:81]
	v_mfma_f32_16x16x32_bf16 v[74:77], v[154:157], v[192:195], v[74:77]
	v_mfma_f32_16x16x32_bf16 v[70:73], v[146:149], v[200:203], v[70:73]
	v_mfma_f32_16x16x32_bf16 v[66:69], v[154:157], v[200:203], v[66:69]
	s_setprio 0
	s_barrier
	s_add_u32 s56, s90, 0x200000
	s_addc_u32 s57, s91, 0
	s_add_i32 s58, s58, s81
	v_lshl_add_u64 v[142:143], s[56:57], 0, v[134:135]
	s_mov_b32 m0, s58
	s_nop 0
	global_load_lds_dwordx4 v[142:143], off
	v_lshl_add_u64 v[142:143], s[56:57], 0, v[130:131]
	s_add_i32 m0, s58, 0x2000
	s_nop 0
	global_load_lds_dwordx4 v[142:143], off
	v_add_u32_e32 v141, 0x18000, v139
	ds_read_b128 v[142:145], v141
	ds_read_b128 v[146:149], v141 offset:1024
	ds_read_b128 v[150:153], v141 offset:2048
	ds_read_b128 v[154:157], v141 offset:3072
	s_waitcnt vmcnt(6)
	s_barrier
	s_setprio 1
	v_mfma_f32_16x16x32_bf16 v[38:41], v[204:207], v[158:161], v[38:41]
	v_mfma_f32_16x16x32_bf16 v[34:37], v[224:227], v[158:161], v[34:37]
	v_mfma_f32_16x16x32_bf16 v[46:49], v[204:207], v[168:171], v[46:49]
	v_mfma_f32_16x16x32_bf16 v[42:45], v[224:227], v[168:171], v[42:45]
	v_mfma_f32_16x16x32_bf16 v[54:57], v[204:207], v[176:179], v[54:57]
	v_mfma_f32_16x16x32_bf16 v[50:53], v[224:227], v[176:179], v[50:53]
	v_mfma_f32_16x16x32_bf16 v[62:65], v[204:207], v[196:199], v[62:65]
	v_mfma_f32_16x16x32_bf16 v[58:61], v[224:227], v[196:199], v[58:61]
	v_mfma_f32_16x16x32_bf16 v[38:41], v[208:211], v[162:165], v[38:41]
	v_mfma_f32_16x16x32_bf16 v[34:37], v[228:231], v[162:165], v[34:37]
	v_mfma_f32_16x16x32_bf16 v[46:49], v[208:211], v[172:175], v[46:49]
	v_mfma_f32_16x16x32_bf16 v[42:45], v[228:231], v[172:175], v[42:45]
	v_mfma_f32_16x16x32_bf16 v[54:57], v[208:211], v[192:195], v[54:57]
	v_mfma_f32_16x16x32_bf16 v[50:53], v[228:231], v[192:195], v[50:53]
	v_mfma_f32_16x16x32_bf16 v[62:65], v[208:211], v[200:203], v[62:65]
	v_mfma_f32_16x16x32_bf16 v[58:61], v[228:231], v[200:203], v[58:61]
	s_setprio 0
	s_add_i32 s56, 0, 0x18000
	s_barrier
	s_add_u32 s22, s22, 0x10000
	s_addc_u32 s23, s23, 0
	s_mov_b32 m0, s44
	v_lshl_add_u64 v[204:205], s[22:23], 0, v[136:137]
	ds_read_b128 v[158:161], v140 offset:32768
	ds_read_b128 v[168:171], v140 offset:34816
	ds_read_b128 v[176:179], v140 offset:36864
	ds_read_b128 v[196:199], v140 offset:38912
	ds_read_b128 v[162:165], v140 offset:33792
	ds_read_b128 v[172:175], v140 offset:35840
	ds_read_b128 v[192:195], v140 offset:37888
	ds_read_b128 v[200:203], v140 offset:39936
	global_load_lds_dwordx4 v[204:205], off
	v_lshl_add_u64 v[204:205], s[22:23], 0, v[132:133]
	s_mov_b32 m0, s45
	s_nop 0
	global_load_lds_dwordx4 v[204:205], off
	s_waitcnt lgkmcnt(8)
	s_barrier
	s_waitcnt lgkmcnt(4)
	s_setprio 1
	s_waitcnt lgkmcnt(4)
	v_mfma_f32_16x16x32_bf16 v[86:89], v[142:145], v[158:161], v[86:89]
	v_mfma_f32_16x16x32_bf16 v[94:97], v[150:153], v[158:161], v[94:97]
	v_mfma_f32_16x16x32_bf16 v[98:101], v[142:145], v[168:171], v[98:101]
	v_mfma_f32_16x16x32_bf16 v[102:105], v[150:153], v[168:171], v[102:105]
	v_mfma_f32_16x16x32_bf16 v[114:117], v[142:145], v[176:179], v[114:117]
	v_mfma_f32_16x16x32_bf16 v[122:125], v[150:153], v[176:179], v[122:125]
	v_mfma_f32_16x16x32_bf16 v[126:129], v[142:145], v[196:199], v[126:129]
	v_mfma_f32_16x16x32_bf16 v[118:121], v[150:153], v[196:199], v[118:121]
	s_waitcnt lgkmcnt(0)
	v_mfma_f32_16x16x32_bf16 v[86:89], v[146:149], v[162:165], v[86:89]
	v_mfma_f32_16x16x32_bf16 v[94:97], v[154:157], v[162:165], v[94:97]
	v_mfma_f32_16x16x32_bf16 v[98:101], v[146:149], v[172:175], v[98:101]
	v_mfma_f32_16x16x32_bf16 v[102:105], v[154:157], v[172:175], v[102:105]
	v_mfma_f32_16x16x32_bf16 v[114:117], v[146:149], v[192:195], v[114:117]
	v_mfma_f32_16x16x32_bf16 v[122:125], v[154:157], v[192:195], v[122:125]
	v_mfma_f32_16x16x32_bf16 v[126:129], v[146:149], v[200:203], v[126:129]
	v_mfma_f32_16x16x32_bf16 v[118:121], v[154:157], v[200:203], v[118:121]
	s_setprio 0
	s_barrier
	s_add_i32 s57, 0, 0x1c000
	s_add_i32 s22, s56, s81
	v_add_u32_e32 v141, s57, v139
	v_lshl_add_u64 v[212:213], v[212:213], 0, s[78:79]
	s_mov_b32 m0, s22
	ds_read_b128 v[204:207], v141
	ds_read_b128 v[208:211], v141 offset:1024
	ds_read_b128 v[224:227], v141 offset:2048
	ds_read_b128 v[228:231], v141 offset:3072
	global_load_lds_dwordx4 v[212:213], off
	v_lshl_add_u64 v[212:213], v[222:223], 0, s[78:79]
	s_add_i32 m0, s22, 0x2000
	s_nop 0
	global_load_lds_dwordx4 v[212:213], off
	s_barrier
	s_waitcnt lgkmcnt(0)
	s_setprio 1
	s_waitcnt lgkmcnt(0)
	v_mfma_f32_16x16x32_bf16 v[2:5], v[204:207], v[158:161], v[2:5]
	v_mfma_f32_16x16x32_bf16 v[6:9], v[224:227], v[158:161], v[6:9]
	v_mfma_f32_16x16x32_bf16 v[10:13], v[204:207], v[168:171], v[10:13]
	v_mfma_f32_16x16x32_bf16 v[14:17], v[224:227], v[168:171], v[14:17]
	v_mfma_f32_16x16x32_bf16 v[22:25], v[204:207], v[176:179], v[22:25]
	v_mfma_f32_16x16x32_bf16 v[18:21], v[224:227], v[176:179], v[18:21]
	v_mfma_f32_16x16x32_bf16 v[30:33], v[204:207], v[196:199], v[30:33]
	v_mfma_f32_16x16x32_bf16 v[26:29], v[224:227], v[196:199], v[26:29]
	v_mfma_f32_16x16x32_bf16 v[2:5], v[208:211], v[162:165], v[2:5]
	v_mfma_f32_16x16x32_bf16 v[6:9], v[228:231], v[162:165], v[6:9]
	v_mfma_f32_16x16x32_bf16 v[10:13], v[208:211], v[172:175], v[10:13]
	v_mfma_f32_16x16x32_bf16 v[14:17], v[228:231], v[172:175], v[14:17]
	v_mfma_f32_16x16x32_bf16 v[22:25], v[208:211], v[192:195], v[22:25]
	v_mfma_f32_16x16x32_bf16 v[18:21], v[228:231], v[192:195], v[18:21]
	v_mfma_f32_16x16x32_bf16 v[30:33], v[208:211], v[200:203], v[30:33]
	v_mfma_f32_16x16x32_bf16 v[26:29], v[228:231], v[200:203], v[26:29]
	s_setprio 0
	s_mov_b32 m0, s47
	v_lshl_add_u64 v[212:213], v[232:233], 0, s[78:79]
	s_barrier
	ds_read_b128 v[158:161], v140 offset:49152
	ds_read_b128 v[168:171], v140 offset:51200
	ds_read_b128 v[176:179], v140 offset:53248
	ds_read_b128 v[196:199], v140 offset:55296
	ds_read_b128 v[162:165], v140 offset:50176
	ds_read_b128 v[172:175], v140 offset:52224
	ds_read_b128 v[192:195], v140 offset:54272
	ds_read_b128 v[200:203], v140 offset:56320
	global_load_lds_dwordx4 v[212:213], off
	v_lshl_add_u64 v[212:213], v[234:235], 0, s[78:79]
	s_mov_b32 m0, s48
	s_nop 0
	global_load_lds_dwordx4 v[212:213], off
	s_waitcnt vmcnt(10)
	s_barrier
	s_waitcnt lgkmcnt(4)
	s_setprio 1
	s_waitcnt lgkmcnt(4)
	v_mfma_f32_16x16x32_bf16 v[110:113], v[142:145], v[158:161], v[110:113]
	v_mfma_f32_16x16x32_bf16 v[106:109], v[150:153], v[158:161], v[106:109]
	v_mfma_f32_16x16x32_bf16 v[90:93], v[142:145], v[168:171], v[90:93]
	v_mfma_f32_16x16x32_bf16 v[82:85], v[150:153], v[168:171], v[82:85]
	v_mfma_f32_16x16x32_bf16 v[78:81], v[142:145], v[176:179], v[78:81]
	v_mfma_f32_16x16x32_bf16 v[74:77], v[150:153], v[176:179], v[74:77]
	v_mfma_f32_16x16x32_bf16 v[70:73], v[142:145], v[196:199], v[70:73]
	v_mfma_f32_16x16x32_bf16 v[66:69], v[150:153], v[196:199], v[66:69]
	s_waitcnt lgkmcnt(0)
	v_mfma_f32_16x16x32_bf16 v[110:113], v[146:149], v[162:165], v[110:113]
	v_mfma_f32_16x16x32_bf16 v[106:109], v[154:157], v[162:165], v[106:109]
	v_mfma_f32_16x16x32_bf16 v[90:93], v[146:149], v[172:175], v[90:93]
	v_mfma_f32_16x16x32_bf16 v[82:85], v[154:157], v[172:175], v[82:85]
	v_mfma_f32_16x16x32_bf16 v[78:81], v[146:149], v[192:195], v[78:81]
	v_mfma_f32_16x16x32_bf16 v[74:77], v[154:157], v[192:195], v[74:77]
	v_mfma_f32_16x16x32_bf16 v[70:73], v[146:149], v[200:203], v[70:73]
	v_mfma_f32_16x16x32_bf16 v[66:69], v[154:157], v[200:203], v[66:69]
	s_setprio 0
	s_barrier
	s_add_u32 s22, s90, 0x200080
	s_addc_u32 s23, s91, 0
	s_add_i32 s56, s57, s81
	v_lshl_add_u64 v[142:143], s[22:23], 0, v[134:135]
	s_mov_b32 m0, s56
	s_nop 0
	global_load_lds_dwordx4 v[142:143], off
	v_lshl_add_u64 v[142:143], s[22:23], 0, v[130:131]
	s_add_i32 m0, s56, 0x2000
	s_nop 0
	global_load_lds_dwordx4 v[142:143], off
	v_add_u32_e32 v141, 0x10000, v139
	ds_read_b128 v[142:145], v141
	ds_read_b128 v[146:149], v141 offset:1024
	ds_read_b128 v[150:153], v141 offset:2048
	ds_read_b128 v[154:157], v141 offset:3072
	s_waitcnt vmcnt(6)
	s_barrier
	s_setprio 1
	v_mfma_f32_16x16x32_bf16 v[38:41], v[204:207], v[158:161], v[38:41]
	v_mfma_f32_16x16x32_bf16 v[34:37], v[224:227], v[158:161], v[34:37]
	v_mfma_f32_16x16x32_bf16 v[46:49], v[204:207], v[168:171], v[46:49]
	v_mfma_f32_16x16x32_bf16 v[42:45], v[224:227], v[168:171], v[42:45]
	v_mfma_f32_16x16x32_bf16 v[54:57], v[204:207], v[176:179], v[54:57]
	v_mfma_f32_16x16x32_bf16 v[50:53], v[224:227], v[176:179], v[50:53]
	v_mfma_f32_16x16x32_bf16 v[62:65], v[204:207], v[196:199], v[62:65]
	v_mfma_f32_16x16x32_bf16 v[58:61], v[224:227], v[196:199], v[58:61]
	v_mfma_f32_16x16x32_bf16 v[38:41], v[208:211], v[162:165], v[38:41]
	v_mfma_f32_16x16x32_bf16 v[34:37], v[228:231], v[162:165], v[34:37]
	v_mfma_f32_16x16x32_bf16 v[46:49], v[208:211], v[172:175], v[46:49]
	v_mfma_f32_16x16x32_bf16 v[42:45], v[228:231], v[172:175], v[42:45]
	v_mfma_f32_16x16x32_bf16 v[54:57], v[208:211], v[192:195], v[54:57]
	v_mfma_f32_16x16x32_bf16 v[50:53], v[228:231], v[192:195], v[50:53]
	v_mfma_f32_16x16x32_bf16 v[62:65], v[208:211], v[200:203], v[62:65]
	v_mfma_f32_16x16x32_bf16 v[58:61], v[228:231], v[200:203], v[58:61]
	s_setprio 0
	s_add_i32 s54, s54, 2
	s_add_i32 s55, s55, 0x10000
	s_cmpk_gt_u32 s54, 0x7d
	s_mov_b64 s[90:91], vcc
	s_barrier
	s_cbranch_scc0 .LBB0_814
	s_waitcnt lgkmcnt(0)
	s_andn2_b64 vcc, exec, s[38:39]
	s_cbranch_vccnz .LBB0_806
	v_mov_b32_e32 v58, 0
	s_mov_b32 s80, s42
	s_mov_b32 s25, s82
	s_mov_b64 s[30:31], s[20:21]
	s_mov_b64 s[84:85], s[18:19]
	s_mov_b32 s49, s50
	v_mov_b32_e32 v59, v58
	v_mov_b32_e32 v60, v58
	v_mov_b32_e32 v61, v58
	v_mov_b32_e32 v62, v58
	v_mov_b32_e32 v63, v58
	v_mov_b32_e32 v64, v58
	v_mov_b32_e32 v65, v58
	v_mov_b32_e32 v50, v58
	v_mov_b32_e32 v51, v58
	v_mov_b32_e32 v52, v58
	v_mov_b32_e32 v53, v58
	v_mov_b32_e32 v54, v58
	v_mov_b32_e32 v55, v58
	v_mov_b32_e32 v56, v58
	v_mov_b32_e32 v57, v58
	v_mov_b32_e32 v42, v58
	v_mov_b32_e32 v43, v58
	v_mov_b32_e32 v44, v58
	v_mov_b32_e32 v45, v58
	v_mov_b32_e32 v46, v58
	v_mov_b32_e32 v47, v58
	v_mov_b32_e32 v48, v58
	v_mov_b32_e32 v49, v58
	v_mov_b32_e32 v34, v58
	v_mov_b32_e32 v35, v58
	v_mov_b32_e32 v36, v58
	v_mov_b32_e32 v37, v58
	v_mov_b32_e32 v38, v58
	v_mov_b32_e32 v39, v58
	v_mov_b32_e32 v40, v58
	v_mov_b32_e32 v41, v58
	v_mov_b32_e32 v66, v58
	v_mov_b32_e32 v67, v58
	v_mov_b32_e32 v68, v58
	v_mov_b32_e32 v69, v58
	v_mov_b32_e32 v70, v58
	v_mov_b32_e32 v71, v58
	v_mov_b32_e32 v72, v58
	v_mov_b32_e32 v73, v58
	v_mov_b32_e32 v74, v58
	v_mov_b32_e32 v75, v58
	v_mov_b32_e32 v76, v58
	v_mov_b32_e32 v77, v58
	v_mov_b32_e32 v78, v58
	v_mov_b32_e32 v79, v58
	v_mov_b32_e32 v80, v58
	v_mov_b32_e32 v81, v58
	v_mov_b32_e32 v82, v58
	v_mov_b32_e32 v83, v58
	v_mov_b32_e32 v84, v58
	v_mov_b32_e32 v85, v58
	v_mov_b32_e32 v90, v58
	v_mov_b32_e32 v91, v58
	v_mov_b32_e32 v92, v58
	v_mov_b32_e32 v93, v58
	v_mov_b32_e32 v106, v58
	v_mov_b32_e32 v107, v58
	v_mov_b32_e32 v108, v58
	v_mov_b32_e32 v109, v58
	v_mov_b32_e32 v110, v58
	v_mov_b32_e32 v111, v58
	v_mov_b32_e32 v112, v58
	v_mov_b32_e32 v113, v58
	v_mov_b32_e32 v26, v58
	v_mov_b32_e32 v27, v58
	v_mov_b32_e32 v28, v58
	v_mov_b32_e32 v29, v58
	v_mov_b32_e32 v30, v58
	v_mov_b32_e32 v31, v58
	v_mov_b32_e32 v32, v58
	v_mov_b32_e32 v33, v58
	v_mov_b32_e32 v18, v58
	v_mov_b32_e32 v19, v58
	v_mov_b32_e32 v20, v58
	v_mov_b32_e32 v21, v58
	v_mov_b32_e32 v22, v58
	v_mov_b32_e32 v23, v58
	v_mov_b32_e32 v24, v58
	v_mov_b32_e32 v25, v58
	v_mov_b32_e32 v14, v58
	v_mov_b32_e32 v15, v58
	v_mov_b32_e32 v16, v58
	v_mov_b32_e32 v17, v58
	v_mov_b32_e32 v10, v58
	v_mov_b32_e32 v11, v58
	v_mov_b32_e32 v12, v58
	v_mov_b32_e32 v13, v58
	v_mov_b32_e32 v6, v58
	v_mov_b32_e32 v7, v58
	v_mov_b32_e32 v8, v58
	v_mov_b32_e32 v9, v58
	v_mov_b32_e32 v2, v58
	v_mov_b32_e32 v3, v58
	v_mov_b32_e32 v4, v58
	v_mov_b32_e32 v5, v58
	v_mov_b32_e32 v118, v58
	v_mov_b32_e32 v119, v58
	v_mov_b32_e32 v120, v58
	v_mov_b32_e32 v121, v58
	v_mov_b32_e32 v126, v58
	v_mov_b32_e32 v127, v58
	v_mov_b32_e32 v128, v58
	v_mov_b32_e32 v129, v58
	v_mov_b32_e32 v122, v58
	v_mov_b32_e32 v123, v58
	v_mov_b32_e32 v124, v58
	v_mov_b32_e32 v125, v58
	v_mov_b32_e32 v114, v58
	v_mov_b32_e32 v115, v58
	v_mov_b32_e32 v116, v58
	v_mov_b32_e32 v117, v58
	v_mov_b32_e32 v102, v58
	v_mov_b32_e32 v103, v58
	v_mov_b32_e32 v104, v58
	v_mov_b32_e32 v105, v58
	v_mov_b32_e32 v98, v58
	v_mov_b32_e32 v99, v58
	v_mov_b32_e32 v100, v58
	v_mov_b32_e32 v101, v58
	v_mov_b32_e32 v94, v58
	v_mov_b32_e32 v95, v58
	v_mov_b32_e32 v96, v58
	v_mov_b32_e32 v97, v58
	v_mov_b32_e32 v86, v58
	v_mov_b32_e32 v87, v58
	v_mov_b32_e32 v88, v58
	v_mov_b32_e32 v89, v58
	s_branch .LBB0_806
